# K-loops: LDS-DMA M0 values computed directly from the wave base (one scalar add per group instead of add+move), remaining M0 wait-state nops filled with neighbouring scalar/ds_read instructions
# speedup vs baseline: 1.0348x; 1.0022x over previous
.LBB0_122:
	v_mov_b64_e32 v[0:1], 0x180
	s_ashr_i32 s15, s14, 31
	v_cmp_lt_i64_e32 vcc, s[16:17], v[0:1]
	s_lshl_b64 s[16:17], s[14:15], 19
	s_add_u32 s16, s30, s16
	s_addc_u32 s17, s31, s17
	s_and_b64 s[18:19], vcc, exec
	s_cselect_b32 s7, s17, s21
	s_cselect_b32 s9, s16, s20
	s_ashr_i32 s13, s12, 31
	s_lshl_b64 s[18:19], s[12:13], 19
	s_add_u32 s18, s34, s18
	s_addc_u32 s19, s35, s19
	s_and_b64 s[22:23], vcc, exec
	s_cselect_b32 s13, s19, s3
	s_cselect_b32 s15, s18, s2
	s_add_u32 s20, s20, 0x40080
	s_addc_u32 s21, s21, 0
	s_add_u32 s50, s2, 0x100
	s_addc_u32 s51, s3, 0
	s_mov_b32 s52, -2
	s_add_u32 s2, s20, 0xfffc0080
	s_addc_u32 s3, s21, -1
	ds_read_b128 v[24:27], v164
	ds_read_b128 v[28:31], v164 offset:1024
	ds_read_b128 v[32:35], v164 offset:2048
	ds_read_b128 v[36:39], v164 offset:3072
	s_cmp_eq_u32 s52, 12
	s_cselect_b32 s23, s7, s3
	s_cselect_b32 s22, s9, s2
	s_cselect_b32 s3, s13, s51
	s_cselect_b32 s2, s15, s50
	s_add_i32 m0, s37, 0xc000
	ds_read_b128 v[154:157], v165
	ds_read_b128 v[158:161], v165 offset:1024
	ds_read_b128 v[180:183], v165 offset:2048
	ds_read_b128 v[184:187], v165 offset:3072
	ds_read_b128 v[188:191], v165 offset:4096
	ds_read_b128 v[192:195], v165 offset:5120
	ds_read_b128 v[196:199], v165 offset:6144
	global_load_lds_dwordx4 v150, s[20:21]
	s_add_i32 m0, s37, 0xe000
	ds_read_b128 v[200:203], v165 offset:7168
	global_load_lds_dwordx4 v152, s[20:21]
	s_waitcnt lgkmcnt(8)
	s_barrier
	s_waitcnt lgkmcnt(0)
	v_mfma_f32_16x16x32_bf16 v[140:143], v[24:27], v[154:157], 0
	v_mfma_f32_16x16x32_bf16 v[136:139], v[32:35], v[154:157], 0
	v_mfma_f32_16x16x32_bf16 v[124:127], v[24:27], v[180:183], 0
	v_mfma_f32_16x16x32_bf16 v[120:123], v[32:35], v[180:183], 0
	v_mfma_f32_16x16x32_bf16 v[108:111], v[24:27], v[188:191], 0
	v_mfma_f32_16x16x32_bf16 v[104:107], v[32:35], v[188:191], 0
	v_mfma_f32_16x16x32_bf16 v[92:95], v[24:27], v[196:199], 0
	v_mfma_f32_16x16x32_bf16 v[88:91], v[32:35], v[196:199], 0
	v_mfma_f32_16x16x32_bf16 v[140:143], v[28:31], v[158:161], v[140:143]
	v_mfma_f32_16x16x32_bf16 v[136:139], v[36:39], v[158:161], v[136:139]
	v_mfma_f32_16x16x32_bf16 v[124:127], v[28:31], v[184:187], v[124:127]
	v_mfma_f32_16x16x32_bf16 v[120:123], v[36:39], v[184:187], v[120:123]
	v_mfma_f32_16x16x32_bf16 v[108:111], v[28:31], v[192:195], v[108:111]
	v_mfma_f32_16x16x32_bf16 v[104:107], v[36:39], v[192:195], v[104:107]
	v_mfma_f32_16x16x32_bf16 v[92:95], v[28:31], v[200:203], v[92:95]
	v_mfma_f32_16x16x32_bf16 v[88:91], v[36:39], v[200:203], v[88:91]
	s_barrier
	ds_read_b128 v[204:207], v164 offset:16384
	ds_read_b128 v[208:211], v164 offset:17408
	ds_read_b128 v[212:215], v164 offset:18432
	s_add_i32 m0, s36, 0x10000
	ds_read_b128 v[216:219], v164 offset:19456
	global_load_lds_dwordx4 v168, s[2:3]
	s_add_i32 m0, s36, 0x12000
	s_add_u32 s98, s2, 0x80
	s_addc_u32 s99, s3, 0
	global_load_lds_dwordx4 v148, s[2:3]
	s_barrier
	s_waitcnt lgkmcnt(0)
	v_mfma_f32_16x16x32_bf16 v[132:135], v[204:207], v[154:157], 0
	v_mfma_f32_16x16x32_bf16 v[128:131], v[212:215], v[154:157], 0
	v_mfma_f32_16x16x32_bf16 v[116:119], v[204:207], v[180:183], 0
	v_mfma_f32_16x16x32_bf16 v[112:115], v[212:215], v[180:183], 0
	v_mfma_f32_16x16x32_bf16 v[100:103], v[204:207], v[188:191], 0
	v_mfma_f32_16x16x32_bf16 v[96:99], v[212:215], v[188:191], 0
	v_mfma_f32_16x16x32_bf16 v[84:87], v[204:207], v[196:199], 0
	v_mfma_f32_16x16x32_bf16 v[80:83], v[212:215], v[196:199], 0
	v_mfma_f32_16x16x32_bf16 v[132:135], v[208:211], v[158:161], v[132:135]
	v_mfma_f32_16x16x32_bf16 v[128:131], v[216:219], v[158:161], v[128:131]
	v_mfma_f32_16x16x32_bf16 v[116:119], v[208:211], v[184:187], v[116:119]
	v_mfma_f32_16x16x32_bf16 v[112:115], v[216:219], v[184:187], v[112:115]
	v_mfma_f32_16x16x32_bf16 v[100:103], v[208:211], v[192:195], v[100:103]
	v_mfma_f32_16x16x32_bf16 v[96:99], v[216:219], v[192:195], v[96:99]
	v_mfma_f32_16x16x32_bf16 v[84:87], v[208:211], v[200:203], v[84:87]
	v_mfma_f32_16x16x32_bf16 v[80:83], v[216:219], v[200:203], v[80:83]
	s_mov_b32 m0, s37
	s_add_u32 s100, s22, 0x80
	s_addc_u32 s101, s23, 0
	s_barrier
	ds_read_b128 v[154:157], v165 offset:16384
	ds_read_b128 v[158:161], v165 offset:17408
	ds_read_b128 v[180:183], v165 offset:18432
	ds_read_b128 v[184:187], v165 offset:19456
	ds_read_b128 v[188:191], v165 offset:20480
	ds_read_b128 v[192:195], v165 offset:21504
	ds_read_b128 v[196:199], v165 offset:22528
	global_load_lds_dwordx4 v144, s[22:23]
	s_mov_b32 m0, s38
	ds_read_b128 v[200:203], v165 offset:23552
	global_load_lds_dwordx4 v146, s[22:23]
	s_barrier
	s_waitcnt lgkmcnt(0)
	v_mfma_f32_16x16x32_bf16 v[76:79], v[24:27], v[154:157], 0
	v_mfma_f32_16x16x32_bf16 v[72:75], v[32:35], v[154:157], 0
	v_mfma_f32_16x16x32_bf16 v[60:63], v[24:27], v[180:183], 0
	v_mfma_f32_16x16x32_bf16 v[56:59], v[32:35], v[180:183], 0
	v_mfma_f32_16x16x32_bf16 v[44:47], v[24:27], v[188:191], 0
	v_mfma_f32_16x16x32_bf16 v[40:43], v[32:35], v[188:191], 0
	v_mfma_f32_16x16x32_bf16 v[12:15], v[24:27], v[196:199], 0
	v_mfma_f32_16x16x32_bf16 v[8:11], v[32:35], v[196:199], 0
	v_mfma_f32_16x16x32_bf16 v[76:79], v[28:31], v[158:161], v[76:79]
	v_mfma_f32_16x16x32_bf16 v[72:75], v[36:39], v[158:161], v[72:75]
	v_mfma_f32_16x16x32_bf16 v[60:63], v[28:31], v[184:187], v[60:63]
	v_mfma_f32_16x16x32_bf16 v[56:59], v[36:39], v[184:187], v[56:59]
	v_mfma_f32_16x16x32_bf16 v[44:47], v[28:31], v[192:195], v[44:47]
	v_mfma_f32_16x16x32_bf16 v[40:43], v[36:39], v[192:195], v[40:43]
	v_mfma_f32_16x16x32_bf16 v[12:15], v[28:31], v[200:203], v[12:15]
	v_mfma_f32_16x16x32_bf16 v[8:11], v[36:39], v[200:203], v[8:11]
	s_barrier
	s_add_i32 m0, s36, 0x14000
	s_add_u32 s54, s2, 0x40000
	s_addc_u32 s55, s3, 0
	global_load_lds_dwordx4 v168, s[54:55]
	s_add_i32 m0, s36, 0x16000
	s_add_u32 s22, s22, 0x40000
	s_addc_u32 s23, s23, 0
	global_load_lds_dwordx4 v148, s[54:55]
	s_waitcnt vmcnt(6)
	s_barrier
	v_mfma_f32_16x16x32_bf16 v[20:23], v[204:207], v[188:191], 0
	v_mfma_f32_16x16x32_bf16 v[16:19], v[212:215], v[188:191], 0
	v_mfma_f32_16x16x32_bf16 v[4:7], v[204:207], v[196:199], 0
	v_mfma_f32_16x16x32_bf16 v[0:3], v[212:215], v[196:199], 0
	v_mfma_f32_16x16x32_bf16 v[24:27], v[204:207], v[154:157], 0
	v_mfma_f32_16x16x32_bf16 v[28:31], v[212:215], v[154:157], 0
	v_mfma_f32_16x16x32_bf16 v[32:35], v[204:207], v[180:183], 0
	v_mfma_f32_16x16x32_bf16 v[36:39], v[212:215], v[180:183], 0
	v_mfma_f32_16x16x32_bf16 v[20:23], v[208:211], v[192:195], v[20:23]
	v_mfma_f32_16x16x32_bf16 v[16:19], v[216:219], v[192:195], v[16:19]
	v_mfma_f32_16x16x32_bf16 v[4:7], v[208:211], v[200:203], v[4:7]
	v_mfma_f32_16x16x32_bf16 v[0:3], v[216:219], v[200:203], v[0:3]
	v_mfma_f32_16x16x32_bf16 v[24:27], v[208:211], v[158:161], v[24:27]
	v_mfma_f32_16x16x32_bf16 v[28:31], v[216:219], v[158:161], v[28:31]
	v_mfma_f32_16x16x32_bf16 v[32:35], v[208:211], v[184:187], v[32:35]
	v_mfma_f32_16x16x32_bf16 v[36:39], v[216:219], v[184:187], v[36:39]
	s_barrier
	ds_read_b128 v[48:51], v164 offset:32768
	ds_read_b128 v[52:55], v164 offset:33792
	ds_read_b128 v[64:67], v164 offset:34816
	ds_read_b128 v[68:71], v164 offset:35840
	s_mov_b32 m0, s39
	ds_read_b128 v[154:157], v165 offset:32768
	ds_read_b128 v[158:161], v165 offset:33792
	ds_read_b128 v[180:183], v165 offset:34816
	ds_read_b128 v[184:187], v165 offset:35840
	ds_read_b128 v[188:191], v165 offset:36864
	ds_read_b128 v[192:195], v165 offset:37888
	ds_read_b128 v[196:199], v165 offset:38912
	global_load_lds_dwordx4 v144, s[22:23]
	s_mov_b32 m0, s40
	ds_read_b128 v[200:203], v165 offset:39936
	global_load_lds_dwordx4 v146, s[22:23]
	s_waitcnt lgkmcnt(8)
	s_barrier
	s_waitcnt lgkmcnt(0)
	v_mfma_f32_16x16x32_bf16 v[140:143], v[48:51], v[154:157], v[140:143]
	v_mfma_f32_16x16x32_bf16 v[136:139], v[64:67], v[154:157], v[136:139]
	v_mfma_f32_16x16x32_bf16 v[124:127], v[48:51], v[180:183], v[124:127]
	v_mfma_f32_16x16x32_bf16 v[120:123], v[64:67], v[180:183], v[120:123]
	v_mfma_f32_16x16x32_bf16 v[108:111], v[48:51], v[188:191], v[108:111]
	v_mfma_f32_16x16x32_bf16 v[104:107], v[64:67], v[188:191], v[104:107]
	v_mfma_f32_16x16x32_bf16 v[92:95], v[48:51], v[196:199], v[92:95]
	v_mfma_f32_16x16x32_bf16 v[88:91], v[64:67], v[196:199], v[88:91]
	v_mfma_f32_16x16x32_bf16 v[140:143], v[52:55], v[158:161], v[140:143]
	v_mfma_f32_16x16x32_bf16 v[136:139], v[68:71], v[158:161], v[136:139]
	v_mfma_f32_16x16x32_bf16 v[124:127], v[52:55], v[184:187], v[124:127]
	v_mfma_f32_16x16x32_bf16 v[120:123], v[68:71], v[184:187], v[120:123]
	v_mfma_f32_16x16x32_bf16 v[108:111], v[52:55], v[192:195], v[108:111]
	v_mfma_f32_16x16x32_bf16 v[104:107], v[68:71], v[192:195], v[104:107]
	v_mfma_f32_16x16x32_bf16 v[92:95], v[52:55], v[200:203], v[92:95]
	v_mfma_f32_16x16x32_bf16 v[88:91], v[68:71], v[200:203], v[88:91]
	s_barrier
	s_add_i32 m0, s36, 0x18000
	ds_read_b128 v[204:207], v164 offset:49152
	ds_read_b128 v[208:211], v164 offset:50176
	ds_read_b128 v[212:215], v164 offset:51200
	global_load_lds_dwordx4 v168, s[98:99]
	s_add_i32 m0, s36, 0x1a000
	ds_read_b128 v[216:219], v164 offset:52224
	global_load_lds_dwordx4 v148, s[98:99]
	s_barrier
	s_waitcnt lgkmcnt(0)
	v_mfma_f32_16x16x32_bf16 v[132:135], v[204:207], v[154:157], v[132:135]
	v_mfma_f32_16x16x32_bf16 v[128:131], v[212:215], v[154:157], v[128:131]
	v_mfma_f32_16x16x32_bf16 v[116:119], v[204:207], v[180:183], v[116:119]
	v_mfma_f32_16x16x32_bf16 v[112:115], v[212:215], v[180:183], v[112:115]
	v_mfma_f32_16x16x32_bf16 v[100:103], v[204:207], v[188:191], v[100:103]
	v_mfma_f32_16x16x32_bf16 v[96:99], v[212:215], v[188:191], v[96:99]
	v_mfma_f32_16x16x32_bf16 v[84:87], v[204:207], v[196:199], v[84:87]
	v_mfma_f32_16x16x32_bf16 v[80:83], v[212:215], v[196:199], v[80:83]
	v_mfma_f32_16x16x32_bf16 v[132:135], v[208:211], v[158:161], v[132:135]
	v_mfma_f32_16x16x32_bf16 v[128:131], v[216:219], v[158:161], v[128:131]
	v_mfma_f32_16x16x32_bf16 v[116:119], v[208:211], v[184:187], v[116:119]
	v_mfma_f32_16x16x32_bf16 v[112:115], v[216:219], v[184:187], v[112:115]
	v_mfma_f32_16x16x32_bf16 v[100:103], v[208:211], v[192:195], v[100:103]
	v_mfma_f32_16x16x32_bf16 v[96:99], v[216:219], v[192:195], v[96:99]
	v_mfma_f32_16x16x32_bf16 v[84:87], v[208:211], v[200:203], v[84:87]
	v_mfma_f32_16x16x32_bf16 v[80:83], v[216:219], v[200:203], v[80:83]
	s_mov_b32 m0, s45
	s_barrier
	ds_read_b128 v[154:157], v165 offset:49152
	ds_read_b128 v[158:161], v165 offset:50176
	ds_read_b128 v[180:183], v165 offset:51200
	ds_read_b128 v[184:187], v165 offset:52224
	ds_read_b128 v[188:191], v165 offset:53248
	ds_read_b128 v[192:195], v165 offset:54272
	ds_read_b128 v[196:199], v165 offset:55296
	global_load_lds_dwordx4 v144, s[100:101]
	s_mov_b32 m0, s46
	ds_read_b128 v[200:203], v165 offset:56320
	global_load_lds_dwordx4 v146, s[100:101]
	s_barrier
	s_waitcnt lgkmcnt(0)
	v_mfma_f32_16x16x32_bf16 v[76:79], v[48:51], v[154:157], v[76:79]
	v_mfma_f32_16x16x32_bf16 v[72:75], v[64:67], v[154:157], v[72:75]
	v_mfma_f32_16x16x32_bf16 v[60:63], v[48:51], v[180:183], v[60:63]
	v_mfma_f32_16x16x32_bf16 v[56:59], v[64:67], v[180:183], v[56:59]
	v_mfma_f32_16x16x32_bf16 v[44:47], v[48:51], v[188:191], v[44:47]
	v_mfma_f32_16x16x32_bf16 v[40:43], v[64:67], v[188:191], v[40:43]
	v_mfma_f32_16x16x32_bf16 v[12:15], v[48:51], v[196:199], v[12:15]
	v_mfma_f32_16x16x32_bf16 v[8:11], v[64:67], v[196:199], v[8:11]
	v_mfma_f32_16x16x32_bf16 v[76:79], v[52:55], v[158:161], v[76:79]
	v_mfma_f32_16x16x32_bf16 v[72:75], v[68:71], v[158:161], v[72:75]
	v_mfma_f32_16x16x32_bf16 v[60:63], v[52:55], v[184:187], v[60:63]
	v_mfma_f32_16x16x32_bf16 v[56:59], v[68:71], v[184:187], v[56:59]
	v_mfma_f32_16x16x32_bf16 v[44:47], v[52:55], v[192:195], v[44:47]
	v_mfma_f32_16x16x32_bf16 v[40:43], v[68:71], v[192:195], v[40:43]
	v_mfma_f32_16x16x32_bf16 v[12:15], v[52:55], v[200:203], v[12:15]
	v_mfma_f32_16x16x32_bf16 v[8:11], v[68:71], v[200:203], v[8:11]
	s_barrier
	s_add_i32 m0, s36, 0x1c000
	s_add_u32 s2, s2, 0x40080
	s_addc_u32 s3, s3, 0
	global_load_lds_dwordx4 v168, s[2:3]
	s_add_i32 m0, s36, 0x1e000
	s_add_i32 s52, s52, 2
	global_load_lds_dwordx4 v148, s[2:3]
	s_waitcnt vmcnt(6)
	s_barrier
	v_mfma_f32_16x16x32_bf16 v[24:27], v[204:207], v[154:157], v[24:27]
	v_mfma_f32_16x16x32_bf16 v[68:71], v[208:211], v[158:161], v[24:27]
	v_mfma_f32_16x16x32_bf16 v[24:27], v[212:215], v[154:157], v[28:31]
	v_mfma_f32_16x16x32_bf16 v[64:67], v[216:219], v[158:161], v[24:27]
	v_mfma_f32_16x16x32_bf16 v[24:27], v[204:207], v[180:183], v[32:35]
	v_mfma_f32_16x16x32_bf16 v[52:55], v[208:211], v[184:187], v[24:27]
	v_mfma_f32_16x16x32_bf16 v[24:27], v[212:215], v[180:183], v[36:39]
	v_mfma_f32_16x16x32_bf16 v[20:23], v[204:207], v[188:191], v[20:23]
	v_mfma_f32_16x16x32_bf16 v[16:19], v[212:215], v[188:191], v[16:19]
	v_mfma_f32_16x16x32_bf16 v[4:7], v[204:207], v[196:199], v[4:7]
	v_mfma_f32_16x16x32_bf16 v[0:3], v[212:215], v[196:199], v[0:3]
	v_mfma_f32_16x16x32_bf16 v[48:51], v[216:219], v[184:187], v[24:27]
	v_mfma_f32_16x16x32_bf16 v[20:23], v[208:211], v[192:195], v[20:23]
	v_mfma_f32_16x16x32_bf16 v[16:19], v[216:219], v[192:195], v[16:19]
	v_mfma_f32_16x16x32_bf16 v[4:7], v[208:211], v[200:203], v[4:7]
	v_mfma_f32_16x16x32_bf16 v[0:3], v[216:219], v[200:203], v[0:3]
	s_add_u32 s20, s20, 0x100
	s_addc_u32 s21, s21, 0
	s_add_u32 s50, s50, 0x100
	s_addc_u32 s51, s51, 0
	s_cmp_gt_u32 s52, 13
	s_barrier
.LBB0_123:
	s_add_u32 s2, s20, 0xfffc0080
	s_addc_u32 s3, s21, -1
	ds_read_b128 v[24:27], v164
	ds_read_b128 v[28:31], v164 offset:1024
	ds_read_b128 v[32:35], v164 offset:2048
	ds_read_b128 v[36:39], v164 offset:3072
	s_cmp_eq_u32 s52, 12
	s_cselect_b32 s23, s7, s3
	s_cselect_b32 s22, s9, s2
	s_cselect_b32 s3, s13, s51
	s_cselect_b32 s2, s15, s50
	s_add_i32 m0, s37, 0xc000
	ds_read_b128 v[154:157], v165
	ds_read_b128 v[158:161], v165 offset:1024
	ds_read_b128 v[180:183], v165 offset:2048
	ds_read_b128 v[184:187], v165 offset:3072
	ds_read_b128 v[188:191], v165 offset:4096
	ds_read_b128 v[192:195], v165 offset:5120
	ds_read_b128 v[196:199], v165 offset:6144
	global_load_lds_dwordx4 v150, s[20:21]
	s_add_i32 m0, s37, 0xe000
	ds_read_b128 v[200:203], v165 offset:7168
	global_load_lds_dwordx4 v152, s[20:21]
	s_waitcnt lgkmcnt(8)
	s_barrier
	s_waitcnt lgkmcnt(0)
	v_mfma_f32_16x16x32_bf16 v[140:143], v[24:27], v[154:157], v[140:143]
	v_mfma_f32_16x16x32_bf16 v[136:139], v[32:35], v[154:157], v[136:139]
	v_mfma_f32_16x16x32_bf16 v[124:127], v[24:27], v[180:183], v[124:127]
	v_mfma_f32_16x16x32_bf16 v[120:123], v[32:35], v[180:183], v[120:123]
	v_mfma_f32_16x16x32_bf16 v[108:111], v[24:27], v[188:191], v[108:111]
	v_mfma_f32_16x16x32_bf16 v[104:107], v[32:35], v[188:191], v[104:107]
	v_mfma_f32_16x16x32_bf16 v[92:95], v[24:27], v[196:199], v[92:95]
	v_mfma_f32_16x16x32_bf16 v[88:91], v[32:35], v[196:199], v[88:91]
	v_mfma_f32_16x16x32_bf16 v[140:143], v[28:31], v[158:161], v[140:143]
	v_mfma_f32_16x16x32_bf16 v[136:139], v[36:39], v[158:161], v[136:139]
	v_mfma_f32_16x16x32_bf16 v[124:127], v[28:31], v[184:187], v[124:127]
	v_mfma_f32_16x16x32_bf16 v[120:123], v[36:39], v[184:187], v[120:123]
	v_mfma_f32_16x16x32_bf16 v[108:111], v[28:31], v[192:195], v[108:111]
	v_mfma_f32_16x16x32_bf16 v[104:107], v[36:39], v[192:195], v[104:107]
	v_mfma_f32_16x16x32_bf16 v[92:95], v[28:31], v[200:203], v[92:95]
	v_mfma_f32_16x16x32_bf16 v[88:91], v[36:39], v[200:203], v[88:91]
	s_barrier
	ds_read_b128 v[204:207], v164 offset:16384
	ds_read_b128 v[208:211], v164 offset:17408
	ds_read_b128 v[212:215], v164 offset:18432
	s_add_i32 m0, s36, 0x10000
	ds_read_b128 v[216:219], v164 offset:19456
	global_load_lds_dwordx4 v168, s[2:3]
	s_add_i32 m0, s36, 0x12000
	s_add_u32 s98, s2, 0x80
	s_addc_u32 s99, s3, 0
	global_load_lds_dwordx4 v148, s[2:3]
	s_barrier
	s_waitcnt lgkmcnt(0)
	v_mfma_f32_16x16x32_bf16 v[132:135], v[204:207], v[154:157], v[132:135]
	v_mfma_f32_16x16x32_bf16 v[128:131], v[212:215], v[154:157], v[128:131]
	v_mfma_f32_16x16x32_bf16 v[116:119], v[204:207], v[180:183], v[116:119]
	v_mfma_f32_16x16x32_bf16 v[112:115], v[212:215], v[180:183], v[112:115]
	v_mfma_f32_16x16x32_bf16 v[100:103], v[204:207], v[188:191], v[100:103]
	v_mfma_f32_16x16x32_bf16 v[96:99], v[212:215], v[188:191], v[96:99]
	v_mfma_f32_16x16x32_bf16 v[84:87], v[204:207], v[196:199], v[84:87]
	v_mfma_f32_16x16x32_bf16 v[80:83], v[212:215], v[196:199], v[80:83]
	v_mfma_f32_16x16x32_bf16 v[132:135], v[208:211], v[158:161], v[132:135]
	v_mfma_f32_16x16x32_bf16 v[128:131], v[216:219], v[158:161], v[128:131]
	v_mfma_f32_16x16x32_bf16 v[116:119], v[208:211], v[184:187], v[116:119]
	v_mfma_f32_16x16x32_bf16 v[112:115], v[216:219], v[184:187], v[112:115]
	v_mfma_f32_16x16x32_bf16 v[100:103], v[208:211], v[192:195], v[100:103]
	v_mfma_f32_16x16x32_bf16 v[96:99], v[216:219], v[192:195], v[96:99]
	v_mfma_f32_16x16x32_bf16 v[84:87], v[208:211], v[200:203], v[84:87]
	v_mfma_f32_16x16x32_bf16 v[80:83], v[216:219], v[200:203], v[80:83]
	s_mov_b32 m0, s37
	s_add_u32 s100, s22, 0x80
	s_addc_u32 s101, s23, 0
	s_barrier
	ds_read_b128 v[154:157], v165 offset:16384
	ds_read_b128 v[158:161], v165 offset:17408
	ds_read_b128 v[180:183], v165 offset:18432
	ds_read_b128 v[184:187], v165 offset:19456
	ds_read_b128 v[188:191], v165 offset:20480
	ds_read_b128 v[192:195], v165 offset:21504
	ds_read_b128 v[196:199], v165 offset:22528
	global_load_lds_dwordx4 v144, s[22:23]
	s_mov_b32 m0, s38
	ds_read_b128 v[200:203], v165 offset:23552
	global_load_lds_dwordx4 v146, s[22:23]
	s_barrier
	s_waitcnt lgkmcnt(0)
	v_mfma_f32_16x16x32_bf16 v[76:79], v[24:27], v[154:157], v[76:79]
	v_mfma_f32_16x16x32_bf16 v[72:75], v[32:35], v[154:157], v[72:75]
	v_mfma_f32_16x16x32_bf16 v[60:63], v[24:27], v[180:183], v[60:63]
	v_mfma_f32_16x16x32_bf16 v[56:59], v[32:35], v[180:183], v[56:59]
	v_mfma_f32_16x16x32_bf16 v[44:47], v[24:27], v[188:191], v[44:47]
	v_mfma_f32_16x16x32_bf16 v[40:43], v[32:35], v[188:191], v[40:43]
	v_mfma_f32_16x16x32_bf16 v[12:15], v[24:27], v[196:199], v[12:15]
	v_mfma_f32_16x16x32_bf16 v[8:11], v[32:35], v[196:199], v[8:11]
	v_mfma_f32_16x16x32_bf16 v[76:79], v[28:31], v[158:161], v[76:79]
	v_mfma_f32_16x16x32_bf16 v[72:75], v[36:39], v[158:161], v[72:75]
	v_mfma_f32_16x16x32_bf16 v[60:63], v[28:31], v[184:187], v[60:63]
	v_mfma_f32_16x16x32_bf16 v[56:59], v[36:39], v[184:187], v[56:59]
	v_mfma_f32_16x16x32_bf16 v[44:47], v[28:31], v[192:195], v[44:47]
	v_mfma_f32_16x16x32_bf16 v[40:43], v[36:39], v[192:195], v[40:43]
	v_mfma_f32_16x16x32_bf16 v[12:15], v[28:31], v[200:203], v[12:15]
	v_mfma_f32_16x16x32_bf16 v[8:11], v[36:39], v[200:203], v[8:11]
	s_barrier
	s_add_i32 m0, s36, 0x14000
	s_add_u32 s54, s2, 0x40000
	s_addc_u32 s55, s3, 0
	global_load_lds_dwordx4 v168, s[54:55]
	s_add_i32 m0, s36, 0x16000
	s_add_u32 s22, s22, 0x40000
	s_addc_u32 s23, s23, 0
	global_load_lds_dwordx4 v148, s[54:55]
	s_waitcnt vmcnt(6)
	s_barrier
	v_mfma_f32_16x16x32_bf16 v[20:23], v[204:207], v[188:191], v[20:23]
	v_mfma_f32_16x16x32_bf16 v[16:19], v[212:215], v[188:191], v[16:19]
	v_mfma_f32_16x16x32_bf16 v[4:7], v[204:207], v[196:199], v[4:7]
	v_mfma_f32_16x16x32_bf16 v[0:3], v[212:215], v[196:199], v[0:3]
	v_mfma_f32_16x16x32_bf16 v[24:27], v[204:207], v[154:157], v[68:71]
	v_mfma_f32_16x16x32_bf16 v[28:31], v[212:215], v[154:157], v[64:67]
	v_mfma_f32_16x16x32_bf16 v[32:35], v[204:207], v[180:183], v[52:55]
	v_mfma_f32_16x16x32_bf16 v[36:39], v[212:215], v[180:183], v[48:51]
	v_mfma_f32_16x16x32_bf16 v[20:23], v[208:211], v[192:195], v[20:23]
	v_mfma_f32_16x16x32_bf16 v[16:19], v[216:219], v[192:195], v[16:19]
	v_mfma_f32_16x16x32_bf16 v[4:7], v[208:211], v[200:203], v[4:7]
	v_mfma_f32_16x16x32_bf16 v[0:3], v[216:219], v[200:203], v[0:3]
	v_mfma_f32_16x16x32_bf16 v[24:27], v[208:211], v[158:161], v[24:27]
	v_mfma_f32_16x16x32_bf16 v[28:31], v[216:219], v[158:161], v[28:31]
	v_mfma_f32_16x16x32_bf16 v[32:35], v[208:211], v[184:187], v[32:35]
	v_mfma_f32_16x16x32_bf16 v[36:39], v[216:219], v[184:187], v[36:39]
	s_barrier
	ds_read_b128 v[48:51], v164 offset:32768
	ds_read_b128 v[52:55], v164 offset:33792
	ds_read_b128 v[64:67], v164 offset:34816
	ds_read_b128 v[68:71], v164 offset:35840
	s_mov_b32 m0, s39
	ds_read_b128 v[154:157], v165 offset:32768
	ds_read_b128 v[158:161], v165 offset:33792
	ds_read_b128 v[180:183], v165 offset:34816
	ds_read_b128 v[184:187], v165 offset:35840
	ds_read_b128 v[188:191], v165 offset:36864
	ds_read_b128 v[192:195], v165 offset:37888
	ds_read_b128 v[196:199], v165 offset:38912
	global_load_lds_dwordx4 v144, s[22:23]
	s_mov_b32 m0, s40
	ds_read_b128 v[200:203], v165 offset:39936
	global_load_lds_dwordx4 v146, s[22:23]
	s_waitcnt lgkmcnt(8)
	s_barrier
	s_waitcnt lgkmcnt(0)
	v_mfma_f32_16x16x32_bf16 v[140:143], v[48:51], v[154:157], v[140:143]
	v_mfma_f32_16x16x32_bf16 v[136:139], v[64:67], v[154:157], v[136:139]
	v_mfma_f32_16x16x32_bf16 v[124:127], v[48:51], v[180:183], v[124:127]
	v_mfma_f32_16x16x32_bf16 v[120:123], v[64:67], v[180:183], v[120:123]
	v_mfma_f32_16x16x32_bf16 v[108:111], v[48:51], v[188:191], v[108:111]
	v_mfma_f32_16x16x32_bf16 v[104:107], v[64:67], v[188:191], v[104:107]
	v_mfma_f32_16x16x32_bf16 v[92:95], v[48:51], v[196:199], v[92:95]
	v_mfma_f32_16x16x32_bf16 v[88:91], v[64:67], v[196:199], v[88:91]
	v_mfma_f32_16x16x32_bf16 v[140:143], v[52:55], v[158:161], v[140:143]
	v_mfma_f32_16x16x32_bf16 v[136:139], v[68:71], v[158:161], v[136:139]
	v_mfma_f32_16x16x32_bf16 v[124:127], v[52:55], v[184:187], v[124:127]
	v_mfma_f32_16x16x32_bf16 v[120:123], v[68:71], v[184:187], v[120:123]
	v_mfma_f32_16x16x32_bf16 v[108:111], v[52:55], v[192:195], v[108:111]
	v_mfma_f32_16x16x32_bf16 v[104:107], v[68:71], v[192:195], v[104:107]
	v_mfma_f32_16x16x32_bf16 v[92:95], v[52:55], v[200:203], v[92:95]
	v_mfma_f32_16x16x32_bf16 v[88:91], v[68:71], v[200:203], v[88:91]
	s_barrier
	s_add_i32 m0, s36, 0x18000
	ds_read_b128 v[204:207], v164 offset:49152
	ds_read_b128 v[208:211], v164 offset:50176
	ds_read_b128 v[212:215], v164 offset:51200
	global_load_lds_dwordx4 v168, s[98:99]
	s_add_i32 m0, s36, 0x1a000
	ds_read_b128 v[216:219], v164 offset:52224
	global_load_lds_dwordx4 v148, s[98:99]
	s_barrier
	s_waitcnt lgkmcnt(0)
	v_mfma_f32_16x16x32_bf16 v[132:135], v[204:207], v[154:157], v[132:135]
	v_mfma_f32_16x16x32_bf16 v[128:131], v[212:215], v[154:157], v[128:131]
	v_mfma_f32_16x16x32_bf16 v[116:119], v[204:207], v[180:183], v[116:119]
	v_mfma_f32_16x16x32_bf16 v[112:115], v[212:215], v[180:183], v[112:115]
	v_mfma_f32_16x16x32_bf16 v[100:103], v[204:207], v[188:191], v[100:103]
	v_mfma_f32_16x16x32_bf16 v[96:99], v[212:215], v[188:191], v[96:99]
	v_mfma_f32_16x16x32_bf16 v[84:87], v[204:207], v[196:199], v[84:87]
	v_mfma_f32_16x16x32_bf16 v[80:83], v[212:215], v[196:199], v[80:83]
	v_mfma_f32_16x16x32_bf16 v[132:135], v[208:211], v[158:161], v[132:135]
	v_mfma_f32_16x16x32_bf16 v[128:131], v[216:219], v[158:161], v[128:131]
	v_mfma_f32_16x16x32_bf16 v[116:119], v[208:211], v[184:187], v[116:119]
	v_mfma_f32_16x16x32_bf16 v[112:115], v[216:219], v[184:187], v[112:115]
	v_mfma_f32_16x16x32_bf16 v[100:103], v[208:211], v[192:195], v[100:103]
	v_mfma_f32_16x16x32_bf16 v[96:99], v[216:219], v[192:195], v[96:99]
	v_mfma_f32_16x16x32_bf16 v[84:87], v[208:211], v[200:203], v[84:87]
	v_mfma_f32_16x16x32_bf16 v[80:83], v[216:219], v[200:203], v[80:83]
	s_mov_b32 m0, s45
	s_barrier
	ds_read_b128 v[154:157], v165 offset:49152
	ds_read_b128 v[158:161], v165 offset:50176
	ds_read_b128 v[180:183], v165 offset:51200
	ds_read_b128 v[184:187], v165 offset:52224
	ds_read_b128 v[188:191], v165 offset:53248
	ds_read_b128 v[192:195], v165 offset:54272
	ds_read_b128 v[196:199], v165 offset:55296
	global_load_lds_dwordx4 v144, s[100:101]
	s_mov_b32 m0, s46
	ds_read_b128 v[200:203], v165 offset:56320
	global_load_lds_dwordx4 v146, s[100:101]
	s_barrier
	s_waitcnt lgkmcnt(0)
	v_mfma_f32_16x16x32_bf16 v[76:79], v[48:51], v[154:157], v[76:79]
	v_mfma_f32_16x16x32_bf16 v[72:75], v[64:67], v[154:157], v[72:75]
	v_mfma_f32_16x16x32_bf16 v[60:63], v[48:51], v[180:183], v[60:63]
	v_mfma_f32_16x16x32_bf16 v[56:59], v[64:67], v[180:183], v[56:59]
	v_mfma_f32_16x16x32_bf16 v[44:47], v[48:51], v[188:191], v[44:47]
	v_mfma_f32_16x16x32_bf16 v[40:43], v[64:67], v[188:191], v[40:43]
	v_mfma_f32_16x16x32_bf16 v[12:15], v[48:51], v[196:199], v[12:15]
	v_mfma_f32_16x16x32_bf16 v[8:11], v[64:67], v[196:199], v[8:11]
	v_mfma_f32_16x16x32_bf16 v[76:79], v[52:55], v[158:161], v[76:79]
	v_mfma_f32_16x16x32_bf16 v[72:75], v[68:71], v[158:161], v[72:75]
	v_mfma_f32_16x16x32_bf16 v[60:63], v[52:55], v[184:187], v[60:63]
	v_mfma_f32_16x16x32_bf16 v[56:59], v[68:71], v[184:187], v[56:59]
	v_mfma_f32_16x16x32_bf16 v[44:47], v[52:55], v[192:195], v[44:47]
	v_mfma_f32_16x16x32_bf16 v[40:43], v[68:71], v[192:195], v[40:43]
	v_mfma_f32_16x16x32_bf16 v[12:15], v[52:55], v[200:203], v[12:15]
	v_mfma_f32_16x16x32_bf16 v[8:11], v[68:71], v[200:203], v[8:11]
	s_barrier
	s_add_i32 m0, s36, 0x1c000
	s_add_u32 s2, s2, 0x40080
	s_addc_u32 s3, s3, 0
	global_load_lds_dwordx4 v168, s[2:3]
	s_add_i32 m0, s36, 0x1e000
	s_add_i32 s52, s52, 2
	global_load_lds_dwordx4 v148, s[2:3]
	s_waitcnt vmcnt(6)
	s_barrier
	v_mfma_f32_16x16x32_bf16 v[24:27], v[204:207], v[154:157], v[24:27]
	v_mfma_f32_16x16x32_bf16 v[68:71], v[208:211], v[158:161], v[24:27]
	v_mfma_f32_16x16x32_bf16 v[24:27], v[212:215], v[154:157], v[28:31]
	v_mfma_f32_16x16x32_bf16 v[64:67], v[216:219], v[158:161], v[24:27]
	v_mfma_f32_16x16x32_bf16 v[24:27], v[204:207], v[180:183], v[32:35]
	v_mfma_f32_16x16x32_bf16 v[52:55], v[208:211], v[184:187], v[24:27]
	v_mfma_f32_16x16x32_bf16 v[24:27], v[212:215], v[180:183], v[36:39]
	v_mfma_f32_16x16x32_bf16 v[20:23], v[204:207], v[188:191], v[20:23]
	v_mfma_f32_16x16x32_bf16 v[16:19], v[212:215], v[188:191], v[16:19]
	v_mfma_f32_16x16x32_bf16 v[4:7], v[204:207], v[196:199], v[4:7]
	v_mfma_f32_16x16x32_bf16 v[0:3], v[212:215], v[196:199], v[0:3]
	v_mfma_f32_16x16x32_bf16 v[48:51], v[216:219], v[184:187], v[24:27]
	v_mfma_f32_16x16x32_bf16 v[20:23], v[208:211], v[192:195], v[20:23]
	v_mfma_f32_16x16x32_bf16 v[16:19], v[216:219], v[192:195], v[16:19]
	v_mfma_f32_16x16x32_bf16 v[4:7], v[208:211], v[200:203], v[4:7]
	v_mfma_f32_16x16x32_bf16 v[0:3], v[216:219], v[200:203], v[0:3]
	s_add_u32 s20, s20, 0x100
	s_addc_u32 s21, s21, 0
	s_add_u32 s50, s50, 0x100
	s_addc_u32 s51, s51, 0
	s_cmp_gt_u32 s52, 13
	s_barrier
	s_cbranch_scc0 .LBB0_123
	s_lshl_b32 s2, s6, 8
	s_add_i32 s3, s2, s43
	s_lshl_b32 s2, s8, 8
	s_cmp_gt_i32 s8, 3
	s_cselect_b64 s[20:21], -1, 0
	s_and_b64 s[22:23], s[20:21], exec
	s_mov_b32 s7, 0x8982000
	s_cselect_b32 s7, s7, 0x7182000
	s_add_u32 s22, s26, s7
	s_addc_u32 s23, s25, 0
	s_add_i32 s7, s6, -16
	v_mov_b32_e32 v160, v163
	v_mov_b32_e32 v24, v162
	s_lshr_b32 s7, s7, 3
	s_add_i32 s96, s7, 1
	v_add_u32_e32 v154, s3, v24
	s_lshl_b64 s[50:51], s[96:97], 11
	v_ashrrev_i32_e32 v155, 31, v154
	s_cmp_gt_i32 s6, 15
	v_lshl_add_u64 v[156:157], v[154:155], 2, s[10:11]
	s_cselect_b32 s7, s51, 0
	s_cselect_b32 s6, s50, 0
	global_load_dword v166, v[156:157], off
	global_load_dword v191, v[156:157], off offset:64
	global_load_dword v192, v[156:157], off offset:128
	global_load_dword v193, v[156:157], off offset:192
	global_load_dword v194, v[156:157], off offset:512
	global_load_dword v195, v[156:157], off offset:576
	global_load_dword v196, v[156:157], off offset:640
	global_load_dword v197, v[156:157], off offset:704
	s_lshl_b64 s[6:7], s[6:7], 2
	s_add_u32 s9, s41, s6
	s_addc_u32 s13, s42, s7
	s_ashr_i32 s3, s2, 31
	s_lshl_b64 s[6:7], s[2:3], 2
	s_add_u32 s3, s9, s6
	s_addc_u32 s7, s13, s7
	v_lshlrev_b32_e32 v158, 3, v160
	s_add_u32 s6, s3, s49
	s_addc_u32 s7, s7, 0
	v_ashrrev_i32_e32 v159, 31, v158
	v_lshl_add_u64 v[24:25], v[158:159], 2, s[6:7]
	global_load_dwordx4 v[36:39], v[24:25], off
	global_load_dwordx4 v[32:35], v[24:25], off offset:16
	global_load_dwordx4 v[28:31], v[24:25], off offset:512
	s_nop 0
	global_load_dwordx4 v[24:27], v[24:25], off offset:528
	s_and_b32 s2, s2, 0x300
	s_or_b32 s2, s2, s44
	v_add_u32_e32 v158, s2, v158
	v_cmp_eq_u32_e64 s[6:7], 0, v160
	v_lshlrev_b64 v[160:161], 11, v[154:155]
	s_cmp_lt_i32 s8, 4
	s_waitcnt vmcnt(0)
	v_ashrrev_i32_e32 v159, 31, v158
	v_lshl_add_u64 v[158:159], v[158:159], 1, s[22:23]
	v_lshl_add_u64 v[160:161], v[158:159], 0, v[160:161]
	v_lshl_add_u64 v[156:157], v[154:155], 2, s[0:1]
	s_and_b64 s[6:7], s[6:7], s[20:21]
	s_mov_b64 s[2:3], 0x8000
	s_mov_b64 s[50:51], 0x28000
	v_mov_b32_e32 v180, 0xc0135761
	v_mov_b32_e32 v181, 0xc0135761
	v_mov_b32_e32 v182, 0xbdd2d3e7
	v_mov_b32_e32 v183, 0xbdd2d3e7
	v_fmamk_f32 v166, v166, 0x3a800000, v225
	v_fmamk_f32 v190, v191, 0x3a800000, v225
	v_fmamk_f32 v192, v192, 0x3a800000, v225
	v_fmamk_f32 v188, v193, 0x3a800000, v225
	v_fmamk_f32 v194, v194, 0x3a800000, v225
	v_fmamk_f32 v186, v195, 0x3a800000, v225
	v_fmamk_f32 v196, v196, 0x3a800000, v225
	v_fmamk_f32 v184, v197, 0x3a800000, v225
	v_rsq_f32_e32 v166, v166
	v_rsq_f32_e32 v190, v190
	v_rsq_f32_e32 v192, v192
	v_rsq_f32_e32 v188, v188
	v_rsq_f32_e32 v194, v194
	v_rsq_f32_e32 v186, v186
	v_rsq_f32_e32 v196, v196
	v_rsq_f32_e32 v184, v184
	v_pk_fma_f32 v[140:141], v[140:141], v[166:167], v[36:37] op_sel_hi:[1,0,1]
	v_pk_fma_f32 v[142:143], v[142:143], v[166:167], v[38:39] op_sel_hi:[1,0,1]
	v_pk_fma_f32 v[136:137], v[136:137], v[166:167], v[32:33] op_sel_hi:[1,0,1]
	v_pk_fma_f32 v[138:139], v[138:139], v[166:167], v[34:35] op_sel_hi:[1,0,1]
	v_pk_fma_f32 v[132:133], v[132:133], v[166:167], v[28:29] op_sel_hi:[1,0,1]
	v_pk_fma_f32 v[134:135], v[134:135], v[166:167], v[30:31] op_sel_hi:[1,0,1]
	v_pk_fma_f32 v[128:129], v[128:129], v[166:167], v[24:25] op_sel_hi:[1,0,1]
	v_pk_fma_f32 v[130:131], v[130:131], v[166:167], v[26:27] op_sel_hi:[1,0,1]
	v_pk_fma_f32 v[124:125], v[124:125], v[190:191], v[36:37] op_sel_hi:[1,0,1]
	v_pk_fma_f32 v[126:127], v[126:127], v[190:191], v[38:39] op_sel_hi:[1,0,1]
	v_pk_fma_f32 v[120:121], v[120:121], v[190:191], v[32:33] op_sel_hi:[1,0,1]
	v_pk_fma_f32 v[122:123], v[122:123], v[190:191], v[34:35] op_sel_hi:[1,0,1]
	v_pk_fma_f32 v[116:117], v[116:117], v[190:191], v[28:29] op_sel_hi:[1,0,1]
	v_pk_fma_f32 v[118:119], v[118:119], v[190:191], v[30:31] op_sel_hi:[1,0,1]
	v_pk_fma_f32 v[112:113], v[112:113], v[190:191], v[24:25] op_sel_hi:[1,0,1]
	v_pk_fma_f32 v[114:115], v[114:115], v[190:191], v[26:27] op_sel_hi:[1,0,1]
	v_pk_fma_f32 v[108:109], v[108:109], v[192:193], v[36:37] op_sel_hi:[1,0,1]
	v_pk_fma_f32 v[110:111], v[110:111], v[192:193], v[38:39] op_sel_hi:[1,0,1]
	v_pk_fma_f32 v[104:105], v[104:105], v[192:193], v[32:33] op_sel_hi:[1,0,1]
	v_pk_fma_f32 v[106:107], v[106:107], v[192:193], v[34:35] op_sel_hi:[1,0,1]
	v_pk_fma_f32 v[100:101], v[100:101], v[192:193], v[28:29] op_sel_hi:[1,0,1]
	v_pk_fma_f32 v[102:103], v[102:103], v[192:193], v[30:31] op_sel_hi:[1,0,1]
	v_pk_fma_f32 v[96:97], v[96:97], v[192:193], v[24:25] op_sel_hi:[1,0,1]
	v_pk_fma_f32 v[98:99], v[98:99], v[192:193], v[26:27] op_sel_hi:[1,0,1]
	v_pk_fma_f32 v[92:93], v[92:93], v[188:189], v[36:37] op_sel_hi:[1,0,1]
	v_pk_fma_f32 v[94:95], v[94:95], v[188:189], v[38:39] op_sel_hi:[1,0,1]
	v_pk_fma_f32 v[88:89], v[88:89], v[188:189], v[32:33] op_sel_hi:[1,0,1]
	v_pk_fma_f32 v[90:91], v[90:91], v[188:189], v[34:35] op_sel_hi:[1,0,1]
	v_pk_fma_f32 v[84:85], v[84:85], v[188:189], v[28:29] op_sel_hi:[1,0,1]
	v_pk_fma_f32 v[86:87], v[86:87], v[188:189], v[30:31] op_sel_hi:[1,0,1]
	v_pk_fma_f32 v[80:81], v[80:81], v[188:189], v[24:25] op_sel_hi:[1,0,1]
	v_pk_fma_f32 v[82:83], v[82:83], v[188:189], v[26:27] op_sel_hi:[1,0,1]
	v_pk_fma_f32 v[76:77], v[76:77], v[194:195], v[36:37] op_sel_hi:[1,0,1]
	v_pk_fma_f32 v[78:79], v[78:79], v[194:195], v[38:39] op_sel_hi:[1,0,1]
	v_pk_fma_f32 v[72:73], v[72:73], v[194:195], v[32:33] op_sel_hi:[1,0,1]
	v_pk_fma_f32 v[74:75], v[74:75], v[194:195], v[34:35] op_sel_hi:[1,0,1]
	v_pk_fma_f32 v[68:69], v[68:69], v[194:195], v[28:29] op_sel_hi:[1,0,1]
	v_pk_fma_f32 v[70:71], v[70:71], v[194:195], v[30:31] op_sel_hi:[1,0,1]
	v_pk_fma_f32 v[64:65], v[64:65], v[194:195], v[24:25] op_sel_hi:[1,0,1]
	v_pk_fma_f32 v[66:67], v[66:67], v[194:195], v[26:27] op_sel_hi:[1,0,1]
	v_pk_fma_f32 v[60:61], v[60:61], v[186:187], v[36:37] op_sel_hi:[1,0,1]
	v_pk_fma_f32 v[62:63], v[62:63], v[186:187], v[38:39] op_sel_hi:[1,0,1]
	v_pk_fma_f32 v[56:57], v[56:57], v[186:187], v[32:33] op_sel_hi:[1,0,1]
	v_pk_fma_f32 v[58:59], v[58:59], v[186:187], v[34:35] op_sel_hi:[1,0,1]
	v_pk_fma_f32 v[52:53], v[52:53], v[186:187], v[28:29] op_sel_hi:[1,0,1]
	v_pk_fma_f32 v[54:55], v[54:55], v[186:187], v[30:31] op_sel_hi:[1,0,1]
	v_pk_fma_f32 v[48:49], v[48:49], v[186:187], v[24:25] op_sel_hi:[1,0,1]
	v_pk_fma_f32 v[50:51], v[50:51], v[186:187], v[26:27] op_sel_hi:[1,0,1]
	v_pk_fma_f32 v[44:45], v[44:45], v[196:197], v[36:37] op_sel_hi:[1,0,1]
	v_pk_fma_f32 v[46:47], v[46:47], v[196:197], v[38:39] op_sel_hi:[1,0,1]
	v_pk_fma_f32 v[40:41], v[40:41], v[196:197], v[32:33] op_sel_hi:[1,0,1]
	v_pk_fma_f32 v[42:43], v[42:43], v[196:197], v[34:35] op_sel_hi:[1,0,1]
	v_pk_fma_f32 v[20:21], v[20:21], v[196:197], v[28:29] op_sel_hi:[1,0,1]
	v_pk_fma_f32 v[22:23], v[22:23], v[196:197], v[30:31] op_sel_hi:[1,0,1]
	v_pk_fma_f32 v[16:17], v[16:17], v[196:197], v[24:25] op_sel_hi:[1,0,1]
	v_pk_fma_f32 v[18:19], v[18:19], v[196:197], v[26:27] op_sel_hi:[1,0,1]
	v_pk_fma_f32 v[12:13], v[12:13], v[184:185], v[36:37] op_sel_hi:[1,0,1]
	v_pk_fma_f32 v[14:15], v[14:15], v[184:185], v[38:39] op_sel_hi:[1,0,1]
	v_pk_fma_f32 v[8:9], v[8:9], v[184:185], v[32:33] op_sel_hi:[1,0,1]
	v_pk_fma_f32 v[10:11], v[10:11], v[184:185], v[34:35] op_sel_hi:[1,0,1]
	v_pk_fma_f32 v[4:5], v[4:5], v[184:185], v[28:29] op_sel_hi:[1,0,1]
	v_pk_fma_f32 v[6:7], v[6:7], v[184:185], v[30:31] op_sel_hi:[1,0,1]
	v_pk_fma_f32 v[0:1], v[0:1], v[184:185], v[24:25] op_sel_hi:[1,0,1]
	v_pk_fma_f32 v[2:3], v[2:3], v[184:185], v[26:27] op_sel_hi:[1,0,1]
	v_pk_mul_f32 v[24:25], v[140:141], v[140:141]
	v_pk_mul_f32 v[26:27], v[142:143], v[142:143]
	v_pk_mul_f32 v[28:29], v[136:137], v[136:137]
	v_pk_mul_f32 v[30:31], v[138:139], v[138:139]
	v_pk_mul_f32 v[32:33], v[132:133], v[132:133]
	v_pk_mul_f32 v[34:35], v[134:135], v[134:135]
	v_pk_mul_f32 v[36:37], v[128:129], v[128:129]
	v_pk_mul_f32 v[38:39], v[130:131], v[130:131]
	v_pk_fma_f32 v[24:25], v[24:25], v[182:183], v[180:181]
	v_pk_fma_f32 v[26:27], v[26:27], v[182:183], v[180:181]
	v_pk_fma_f32 v[28:29], v[28:29], v[182:183], v[180:181]
	v_pk_fma_f32 v[30:31], v[30:31], v[182:183], v[180:181]
	v_pk_fma_f32 v[32:33], v[32:33], v[182:183], v[180:181]
	v_pk_fma_f32 v[34:35], v[34:35], v[182:183], v[180:181]
	v_pk_fma_f32 v[36:37], v[36:37], v[182:183], v[180:181]
	v_pk_fma_f32 v[38:39], v[38:39], v[182:183], v[180:181]
	v_pk_mul_f32 v[24:25], v[24:25], v[140:141]
	v_pk_mul_f32 v[26:27], v[26:27], v[142:143]
	v_pk_mul_f32 v[28:29], v[28:29], v[136:137]
	v_pk_mul_f32 v[30:31], v[30:31], v[138:139]
	v_pk_mul_f32 v[32:33], v[32:33], v[132:133]
	v_pk_mul_f32 v[34:35], v[34:35], v[134:135]
	v_pk_mul_f32 v[36:37], v[36:37], v[128:129]
	v_pk_mul_f32 v[38:39], v[38:39], v[130:131]
	v_exp_f32_e32 v24, v24
	v_exp_f32_e32 v25, v25
	v_exp_f32_e32 v26, v26
	v_exp_f32_e32 v27, v27
	v_exp_f32_e32 v28, v28
	v_exp_f32_e32 v29, v29
	v_exp_f32_e32 v30, v30
	v_exp_f32_e32 v31, v31
	v_exp_f32_e32 v32, v32
	v_exp_f32_e32 v33, v33
	v_exp_f32_e32 v34, v34
	v_exp_f32_e32 v35, v35
	v_exp_f32_e32 v36, v36
	v_exp_f32_e32 v37, v37
	v_exp_f32_e32 v38, v38
	v_exp_f32_e32 v39, v39
	v_pk_add_f32 v[24:25], v[24:25], 1.0 op_sel_hi:[1,0]
	v_pk_add_f32 v[26:27], v[26:27], 1.0 op_sel_hi:[1,0]
	v_pk_add_f32 v[28:29], v[28:29], 1.0 op_sel_hi:[1,0]
	v_pk_add_f32 v[30:31], v[30:31], 1.0 op_sel_hi:[1,0]
	v_pk_add_f32 v[32:33], v[32:33], 1.0 op_sel_hi:[1,0]
	v_pk_add_f32 v[34:35], v[34:35], 1.0 op_sel_hi:[1,0]
	v_pk_add_f32 v[36:37], v[36:37], 1.0 op_sel_hi:[1,0]
	v_pk_add_f32 v[38:39], v[38:39], 1.0 op_sel_hi:[1,0]
	v_rcp_f32_e32 v24, v24
	v_rcp_f32_e32 v25, v25
	v_rcp_f32_e32 v26, v26
	v_rcp_f32_e32 v27, v27
	v_rcp_f32_e32 v28, v28
	v_rcp_f32_e32 v29, v29
	v_rcp_f32_e32 v30, v30
	v_rcp_f32_e32 v31, v31
	v_rcp_f32_e32 v32, v32
	v_rcp_f32_e32 v33, v33
	v_rcp_f32_e32 v34, v34
	v_rcp_f32_e32 v35, v35
	v_rcp_f32_e32 v36, v36
	v_rcp_f32_e32 v37, v37
	v_rcp_f32_e32 v38, v38
	v_rcp_f32_e32 v39, v39
	v_pk_mul_f32 v[140:141], v[140:141], v[24:25]
	v_pk_mul_f32 v[142:143], v[142:143], v[26:27]
	v_pk_mul_f32 v[136:137], v[136:137], v[28:29]
	v_pk_mul_f32 v[138:139], v[138:139], v[30:31]
	v_pk_mul_f32 v[132:133], v[132:133], v[32:33]
	v_pk_mul_f32 v[134:135], v[134:135], v[34:35]
	v_pk_mul_f32 v[128:129], v[128:129], v[36:37]
	v_pk_mul_f32 v[130:131], v[130:131], v[38:39]
	v_cvt_pk_bf16_f32 v24, v140, v141
	v_cvt_pk_bf16_f32 v25, v142, v143
	v_cvt_pk_bf16_f32 v26, v136, v137
	v_cvt_pk_bf16_f32 v27, v138, v139
	v_cvt_pk_bf16_f32 v28, v132, v133
	v_cvt_pk_bf16_f32 v29, v134, v135
	v_cvt_pk_bf16_f32 v30, v128, v129
	v_cvt_pk_bf16_f32 v31, v130, v131
	global_store_dwordx4 v[160:161], v[24:27], off
	global_store_dwordx4 v[160:161], v[28:31], off offset:256
	s_and_b64 vcc, exec, s[20:21]
	s_cbranch_vccz .Lio_skip_0
	v_pk_mul_f32 v[32:33], v[140:141], v[140:141]
	v_pk_fma_f32 v[32:33], v[142:143], v[142:143], v[32:33]
	v_pk_fma_f32 v[32:33], v[136:137], v[136:137], v[32:33]
	v_pk_fma_f32 v[32:33], v[138:139], v[138:139], v[32:33]
	v_pk_fma_f32 v[32:33], v[132:133], v[132:133], v[32:33]
	v_pk_fma_f32 v[32:33], v[134:135], v[134:135], v[32:33]
	v_pk_fma_f32 v[32:33], v[128:129], v[128:129], v[32:33]
	v_pk_fma_f32 v[32:33], v[130:131], v[130:131], v[32:33]
	s_nop 0
	v_add_f32_e32 v32, v32, v33
	v_mov_b32_e32 v33, v32
	s_nop 1
	v_permlane16_swap_b32_e32 v32, v33
	v_add_f32_e32 v32, v32, v33
	v_mov_b32_e32 v33, v32
	s_nop 1
	v_permlane32_swap_b32_e32 v32, v33
	s_and_saveexec_b64 vcc, s[6:7]
	v_add_f32_e32 v32, v32, v33
	global_atomic_add_f32 v[156:157], v32, off
	s_mov_b64 exec, vcc

.Lie_done_b:
.LBB0_354:
	s_ashr_i32 s31, s30, 31
	v_cmp_lt_i64_e32 vcc, s[8:9], v[170:171]
	s_lshl_b64 s[8:9], s[30:31], 19
	s_add_u32 s34, s52, s8
	s_addc_u32 s35, s53, s9
	s_and_b64 s[8:9], vcc, exec
	s_cselect_b32 s1, s35, s7
	s_cselect_b32 s31, s34, s6
	s_ashr_i32 s29, s28, 31
	s_lshl_b64 s[8:9], s[28:29], 19
	s_add_u32 s36, s43, s8
	s_addc_u32 s37, s42, s9
	s_and_b64 s[8:9], vcc, exec
	s_cselect_b32 s29, s37, s3
	s_cselect_b32 s38, s36, s2
	s_add_u32 s6, s6, 0x40080
	s_addc_u32 s7, s7, 0
	s_add_u32 s39, s2, 0x100
	s_addc_u32 s40, s3, 0
	s_mov_b32 s41, -2
	s_add_u32 s2, s6, 0xfffc0080
	s_addc_u32 s3, s7, -1
	ds_read_b128 v[128:131], v208
	ds_read_b128 v[132:135], v208 offset:1024
	ds_read_b128 v[136:139], v208 offset:2048
	ds_read_b128 v[140:143], v208 offset:3072
	s_cmp_eq_u32 s41, 12
	s_cselect_b32 s9, s1, s3
	s_cselect_b32 s8, s31, s2
	s_cselect_b32 s3, s29, s40
	s_cselect_b32 s2, s38, s39
	s_add_i32 m0, s21, 0xc000
	ds_read_b128 v[144:147], v209
	ds_read_b128 v[148:151], v209 offset:1024
	ds_read_b128 v[152:155], v209 offset:2048
	ds_read_b128 v[156:159], v209 offset:3072
	ds_read_b128 v[180:183], v209 offset:4096
	ds_read_b128 v[184:187], v209 offset:5120
	ds_read_b128 v[188:191], v209 offset:6144
	global_load_lds_dwordx4 v164, s[6:7]
	s_add_i32 m0, s21, 0xe000
	ds_read_b128 v[192:195], v209 offset:7168
	global_load_lds_dwordx4 v166, s[6:7]
	s_waitcnt lgkmcnt(8)
	s_barrier
	s_waitcnt lgkmcnt(0)
	v_mfma_f32_16x16x32_bf16 v[124:127], v[128:131], v[144:147], 0
	v_mfma_f32_16x16x32_bf16 v[120:123], v[136:139], v[144:147], 0
	v_mfma_f32_16x16x32_bf16 v[116:119], v[128:131], v[152:155], 0
	v_mfma_f32_16x16x32_bf16 v[112:115], v[136:139], v[152:155], 0
	v_mfma_f32_16x16x32_bf16 v[100:103], v[128:131], v[180:183], 0
	v_mfma_f32_16x16x32_bf16 v[96:99], v[136:139], v[180:183], 0
	v_mfma_f32_16x16x32_bf16 v[84:87], v[128:131], v[188:191], 0
	v_mfma_f32_16x16x32_bf16 v[80:83], v[136:139], v[188:191], 0
	v_mfma_f32_16x16x32_bf16 v[124:127], v[132:135], v[148:151], v[124:127]
	v_mfma_f32_16x16x32_bf16 v[120:123], v[140:143], v[148:151], v[120:123]
	v_mfma_f32_16x16x32_bf16 v[116:119], v[132:135], v[156:159], v[116:119]
	v_mfma_f32_16x16x32_bf16 v[112:115], v[140:143], v[156:159], v[112:115]
	v_mfma_f32_16x16x32_bf16 v[100:103], v[132:135], v[184:187], v[100:103]
	v_mfma_f32_16x16x32_bf16 v[96:99], v[140:143], v[184:187], v[96:99]
	v_mfma_f32_16x16x32_bf16 v[84:87], v[132:135], v[192:195], v[84:87]
	v_mfma_f32_16x16x32_bf16 v[80:83], v[140:143], v[192:195], v[80:83]
	s_barrier
	s_add_u32 s98, s2, 0x80
	s_addc_u32 s99, s3, 0
	s_add_i32 m0, s54, 0x10000
	ds_read_b128 v[196:199], v208 offset:16384
	ds_read_b128 v[200:203], v208 offset:17408
	ds_read_b128 v[210:213], v208 offset:18432
	global_load_lds_dwordx4 v160, s[2:3]
	s_add_i32 m0, s54, 0x12000
	ds_read_b128 v[214:217], v208 offset:19456
	global_load_lds_dwordx4 v162, s[2:3]
	s_barrier
	s_waitcnt lgkmcnt(0)
	v_mfma_f32_16x16x32_bf16 v[108:111], v[196:199], v[144:147], 0
	v_mfma_f32_16x16x32_bf16 v[104:107], v[210:213], v[144:147], 0
	v_mfma_f32_16x16x32_bf16 v[92:95], v[196:199], v[152:155], 0
	v_mfma_f32_16x16x32_bf16 v[88:91], v[210:213], v[152:155], 0
	v_mfma_f32_16x16x32_bf16 v[76:79], v[196:199], v[180:183], 0
	v_mfma_f32_16x16x32_bf16 v[72:75], v[210:213], v[180:183], 0
	v_mfma_f32_16x16x32_bf16 v[68:71], v[196:199], v[188:191], 0
	v_mfma_f32_16x16x32_bf16 v[64:67], v[210:213], v[188:191], 0
	v_mfma_f32_16x16x32_bf16 v[108:111], v[200:203], v[148:151], v[108:111]
	v_mfma_f32_16x16x32_bf16 v[104:107], v[214:217], v[148:151], v[104:107]
	v_mfma_f32_16x16x32_bf16 v[92:95], v[200:203], v[156:159], v[92:95]
	v_mfma_f32_16x16x32_bf16 v[88:91], v[214:217], v[156:159], v[88:91]
	v_mfma_f32_16x16x32_bf16 v[76:79], v[200:203], v[184:187], v[76:79]
	v_mfma_f32_16x16x32_bf16 v[72:75], v[214:217], v[184:187], v[72:75]
	v_mfma_f32_16x16x32_bf16 v[68:71], v[200:203], v[192:195], v[68:71]
	v_mfma_f32_16x16x32_bf16 v[64:67], v[214:217], v[192:195], v[64:67]
	s_mov_b32 m0, s21
	s_add_u32 s100, s8, 0x80
	s_addc_u32 s101, s9, 0
	s_barrier
	ds_read_b128 v[144:147], v209 offset:16384
	ds_read_b128 v[148:151], v209 offset:17408
	ds_read_b128 v[152:155], v209 offset:18432
	ds_read_b128 v[156:159], v209 offset:19456
	ds_read_b128 v[180:183], v209 offset:20480
	ds_read_b128 v[184:187], v209 offset:21504
	ds_read_b128 v[188:191], v209 offset:22528
	global_load_lds_dwordx4 v160, s[8:9]
	s_mov_b32 m0, s55
	ds_read_b128 v[192:195], v209 offset:23552
	global_load_lds_dwordx4 v162, s[8:9]
	s_barrier
	s_waitcnt lgkmcnt(0)
	v_mfma_f32_16x16x32_bf16 v[60:63], v[128:131], v[144:147], 0
	v_mfma_f32_16x16x32_bf16 v[56:59], v[136:139], v[144:147], 0
	v_mfma_f32_16x16x32_bf16 v[52:55], v[128:131], v[152:155], 0
	v_mfma_f32_16x16x32_bf16 v[48:51], v[136:139], v[152:155], 0
	v_mfma_f32_16x16x32_bf16 v[36:39], v[128:131], v[180:183], 0
	v_mfma_f32_16x16x32_bf16 v[32:35], v[136:139], v[180:183], 0
	v_mfma_f32_16x16x32_bf16 v[20:23], v[128:131], v[188:191], 0
	v_mfma_f32_16x16x32_bf16 v[16:19], v[136:139], v[188:191], 0
	v_mfma_f32_16x16x32_bf16 v[60:63], v[132:135], v[148:151], v[60:63]
	v_mfma_f32_16x16x32_bf16 v[56:59], v[140:143], v[148:151], v[56:59]
	v_mfma_f32_16x16x32_bf16 v[52:55], v[132:135], v[156:159], v[52:55]
	v_mfma_f32_16x16x32_bf16 v[48:51], v[140:143], v[156:159], v[48:51]
	v_mfma_f32_16x16x32_bf16 v[36:39], v[132:135], v[184:187], v[36:39]
	v_mfma_f32_16x16x32_bf16 v[32:35], v[140:143], v[184:187], v[32:35]
	v_mfma_f32_16x16x32_bf16 v[20:23], v[132:135], v[192:195], v[20:23]
	v_mfma_f32_16x16x32_bf16 v[16:19], v[140:143], v[192:195], v[16:19]
	s_barrier
	s_add_i32 m0, s54, 0x14000
	s_add_u32 s64, s2, 0x40000
	s_addc_u32 s65, s3, 0
	global_load_lds_dwordx4 v160, s[64:65]
	s_add_i32 m0, s54, 0x16000
	s_add_u32 s8, s8, 0x40000
	s_addc_u32 s9, s9, 0
	global_load_lds_dwordx4 v162, s[64:65]
	s_waitcnt vmcnt(6)
	s_barrier
	v_mfma_f32_16x16x32_bf16 v[44:47], v[196:199], v[144:147], 0
	v_mfma_f32_16x16x32_bf16 v[40:43], v[210:213], v[144:147], 0
	v_mfma_f32_16x16x32_bf16 v[28:31], v[196:199], v[152:155], 0
	v_mfma_f32_16x16x32_bf16 v[24:27], v[210:213], v[152:155], 0
	v_mfma_f32_16x16x32_bf16 v[12:15], v[196:199], v[180:183], 0
	v_mfma_f32_16x16x32_bf16 v[8:11], v[210:213], v[180:183], 0
	v_mfma_f32_16x16x32_bf16 v[4:7], v[196:199], v[188:191], 0
	v_mfma_f32_16x16x32_bf16 v[0:3], v[210:213], v[188:191], 0
	v_mfma_f32_16x16x32_bf16 v[44:47], v[200:203], v[148:151], v[44:47]
	v_mfma_f32_16x16x32_bf16 v[40:43], v[214:217], v[148:151], v[40:43]
	v_mfma_f32_16x16x32_bf16 v[28:31], v[200:203], v[156:159], v[28:31]
	v_mfma_f32_16x16x32_bf16 v[24:27], v[214:217], v[156:159], v[24:27]
	v_mfma_f32_16x16x32_bf16 v[12:15], v[200:203], v[184:187], v[12:15]
	v_mfma_f32_16x16x32_bf16 v[8:11], v[214:217], v[184:187], v[8:11]
	v_mfma_f32_16x16x32_bf16 v[4:7], v[200:203], v[192:195], v[4:7]
	v_mfma_f32_16x16x32_bf16 v[0:3], v[214:217], v[192:195], v[0:3]
	s_barrier
	ds_read_b128 v[128:131], v208 offset:32768
	ds_read_b128 v[132:135], v208 offset:33792
	ds_read_b128 v[136:139], v208 offset:34816
	ds_read_b128 v[140:143], v208 offset:35840
	s_mov_b32 m0, s56
	ds_read_b128 v[144:147], v209 offset:32768
	ds_read_b128 v[148:151], v209 offset:33792
	ds_read_b128 v[152:155], v209 offset:34816
	ds_read_b128 v[156:159], v209 offset:35840
	ds_read_b128 v[180:183], v209 offset:36864
	ds_read_b128 v[184:187], v209 offset:37888
	ds_read_b128 v[188:191], v209 offset:38912
	global_load_lds_dwordx4 v160, s[8:9]
	s_mov_b32 m0, s57
	ds_read_b128 v[192:195], v209 offset:39936
	global_load_lds_dwordx4 v162, s[8:9]
	s_waitcnt lgkmcnt(8)
	s_barrier
	s_waitcnt lgkmcnt(0)
	v_mfma_f32_16x16x32_bf16 v[124:127], v[128:131], v[144:147], v[124:127]
	v_mfma_f32_16x16x32_bf16 v[120:123], v[136:139], v[144:147], v[120:123]
	v_mfma_f32_16x16x32_bf16 v[116:119], v[128:131], v[152:155], v[116:119]
	v_mfma_f32_16x16x32_bf16 v[112:115], v[136:139], v[152:155], v[112:115]
	v_mfma_f32_16x16x32_bf16 v[100:103], v[128:131], v[180:183], v[100:103]
	v_mfma_f32_16x16x32_bf16 v[96:99], v[136:139], v[180:183], v[96:99]
	v_mfma_f32_16x16x32_bf16 v[84:87], v[128:131], v[188:191], v[84:87]
	v_mfma_f32_16x16x32_bf16 v[80:83], v[136:139], v[188:191], v[80:83]
	v_mfma_f32_16x16x32_bf16 v[124:127], v[132:135], v[148:151], v[124:127]
	v_mfma_f32_16x16x32_bf16 v[120:123], v[140:143], v[148:151], v[120:123]
	v_mfma_f32_16x16x32_bf16 v[116:119], v[132:135], v[156:159], v[116:119]
	v_mfma_f32_16x16x32_bf16 v[112:115], v[140:143], v[156:159], v[112:115]
	v_mfma_f32_16x16x32_bf16 v[100:103], v[132:135], v[184:187], v[100:103]
	v_mfma_f32_16x16x32_bf16 v[96:99], v[140:143], v[184:187], v[96:99]
	v_mfma_f32_16x16x32_bf16 v[84:87], v[132:135], v[192:195], v[84:87]
	v_mfma_f32_16x16x32_bf16 v[80:83], v[140:143], v[192:195], v[80:83]
	s_barrier
	s_add_i32 m0, s54, 0x18000
	ds_read_b128 v[196:199], v208 offset:49152
	ds_read_b128 v[200:203], v208 offset:50176
	ds_read_b128 v[210:213], v208 offset:51200
	global_load_lds_dwordx4 v160, s[98:99]
	s_add_i32 m0, s54, 0x1a000
	ds_read_b128 v[214:217], v208 offset:52224
	global_load_lds_dwordx4 v162, s[98:99]
	s_barrier
	s_waitcnt lgkmcnt(0)
	v_mfma_f32_16x16x32_bf16 v[108:111], v[196:199], v[144:147], v[108:111]
	v_mfma_f32_16x16x32_bf16 v[104:107], v[210:213], v[144:147], v[104:107]
	v_mfma_f32_16x16x32_bf16 v[92:95], v[196:199], v[152:155], v[92:95]
	v_mfma_f32_16x16x32_bf16 v[88:91], v[210:213], v[152:155], v[88:91]
	v_mfma_f32_16x16x32_bf16 v[76:79], v[196:199], v[180:183], v[76:79]
	v_mfma_f32_16x16x32_bf16 v[72:75], v[210:213], v[180:183], v[72:75]
	v_mfma_f32_16x16x32_bf16 v[68:71], v[196:199], v[188:191], v[68:71]
	v_mfma_f32_16x16x32_bf16 v[64:67], v[210:213], v[188:191], v[64:67]
	v_mfma_f32_16x16x32_bf16 v[108:111], v[200:203], v[148:151], v[108:111]
	v_mfma_f32_16x16x32_bf16 v[104:107], v[214:217], v[148:151], v[104:107]
	v_mfma_f32_16x16x32_bf16 v[92:95], v[200:203], v[156:159], v[92:95]
	v_mfma_f32_16x16x32_bf16 v[88:91], v[214:217], v[156:159], v[88:91]
	v_mfma_f32_16x16x32_bf16 v[76:79], v[200:203], v[184:187], v[76:79]
	v_mfma_f32_16x16x32_bf16 v[72:75], v[214:217], v[184:187], v[72:75]
	v_mfma_f32_16x16x32_bf16 v[68:71], v[200:203], v[192:195], v[68:71]
	v_mfma_f32_16x16x32_bf16 v[64:67], v[214:217], v[192:195], v[64:67]
	s_mov_b32 m0, s60
	s_barrier
	ds_read_b128 v[144:147], v209 offset:49152
	ds_read_b128 v[148:151], v209 offset:50176
	ds_read_b128 v[152:155], v209 offset:51200
	ds_read_b128 v[156:159], v209 offset:52224
	ds_read_b128 v[180:183], v209 offset:53248
	ds_read_b128 v[184:187], v209 offset:54272
	ds_read_b128 v[188:191], v209 offset:55296
	global_load_lds_dwordx4 v160, s[100:101]
	s_mov_b32 m0, s61
	ds_read_b128 v[192:195], v209 offset:56320
	global_load_lds_dwordx4 v162, s[100:101]
	s_barrier
	s_waitcnt lgkmcnt(0)
	v_mfma_f32_16x16x32_bf16 v[60:63], v[128:131], v[144:147], v[60:63]
	v_mfma_f32_16x16x32_bf16 v[56:59], v[136:139], v[144:147], v[56:59]
	v_mfma_f32_16x16x32_bf16 v[52:55], v[128:131], v[152:155], v[52:55]
	v_mfma_f32_16x16x32_bf16 v[48:51], v[136:139], v[152:155], v[48:51]
	v_mfma_f32_16x16x32_bf16 v[36:39], v[128:131], v[180:183], v[36:39]
	v_mfma_f32_16x16x32_bf16 v[32:35], v[136:139], v[180:183], v[32:35]
	v_mfma_f32_16x16x32_bf16 v[20:23], v[128:131], v[188:191], v[20:23]
	v_mfma_f32_16x16x32_bf16 v[16:19], v[136:139], v[188:191], v[16:19]
	v_mfma_f32_16x16x32_bf16 v[60:63], v[132:135], v[148:151], v[60:63]
	v_mfma_f32_16x16x32_bf16 v[56:59], v[140:143], v[148:151], v[56:59]
	v_mfma_f32_16x16x32_bf16 v[52:55], v[132:135], v[156:159], v[52:55]
	v_mfma_f32_16x16x32_bf16 v[48:51], v[140:143], v[156:159], v[48:51]
	v_mfma_f32_16x16x32_bf16 v[36:39], v[132:135], v[184:187], v[36:39]
	v_mfma_f32_16x16x32_bf16 v[32:35], v[140:143], v[184:187], v[32:35]
	v_mfma_f32_16x16x32_bf16 v[20:23], v[132:135], v[192:195], v[20:23]
	v_mfma_f32_16x16x32_bf16 v[16:19], v[140:143], v[192:195], v[16:19]
	s_barrier
	s_add_i32 m0, s54, 0x1c000
	s_add_u32 s2, s2, 0x40080
	s_addc_u32 s3, s3, 0
	global_load_lds_dwordx4 v160, s[2:3]
	s_add_i32 m0, s54, 0x1e000
	s_add_i32 s41, s41, 2
	global_load_lds_dwordx4 v162, s[2:3]
	s_waitcnt vmcnt(6)
	s_barrier
	v_mfma_f32_16x16x32_bf16 v[44:47], v[196:199], v[144:147], v[44:47]
	v_mfma_f32_16x16x32_bf16 v[40:43], v[210:213], v[144:147], v[40:43]
	v_mfma_f32_16x16x32_bf16 v[28:31], v[196:199], v[152:155], v[28:31]
	v_mfma_f32_16x16x32_bf16 v[24:27], v[210:213], v[152:155], v[24:27]
	v_mfma_f32_16x16x32_bf16 v[12:15], v[196:199], v[180:183], v[12:15]
	v_mfma_f32_16x16x32_bf16 v[8:11], v[210:213], v[180:183], v[8:11]
	v_mfma_f32_16x16x32_bf16 v[4:7], v[196:199], v[188:191], v[4:7]
	v_mfma_f32_16x16x32_bf16 v[0:3], v[210:213], v[188:191], v[0:3]
	v_mfma_f32_16x16x32_bf16 v[44:47], v[200:203], v[148:151], v[44:47]
	v_mfma_f32_16x16x32_bf16 v[40:43], v[214:217], v[148:151], v[40:43]
	v_mfma_f32_16x16x32_bf16 v[28:31], v[200:203], v[156:159], v[28:31]
	v_mfma_f32_16x16x32_bf16 v[24:27], v[214:217], v[156:159], v[24:27]
	v_mfma_f32_16x16x32_bf16 v[12:15], v[200:203], v[184:187], v[12:15]
	v_mfma_f32_16x16x32_bf16 v[8:11], v[214:217], v[184:187], v[8:11]
	v_mfma_f32_16x16x32_bf16 v[4:7], v[200:203], v[192:195], v[4:7]
	v_mfma_f32_16x16x32_bf16 v[0:3], v[214:217], v[192:195], v[0:3]
	s_add_u32 s6, s6, 0x100
	s_addc_u32 s7, s7, 0
	s_add_u32 s39, s39, 0x100
	s_addc_u32 s40, s40, 0
	s_cmp_gt_u32 s41, 13
	s_barrier
.LBB0_355:
	s_add_u32 s2, s6, 0xfffc0080
	s_addc_u32 s3, s7, -1
	ds_read_b128 v[128:131], v208
	ds_read_b128 v[132:135], v208 offset:1024
	ds_read_b128 v[136:139], v208 offset:2048
	ds_read_b128 v[140:143], v208 offset:3072
	s_cmp_eq_u32 s41, 12
	s_cselect_b32 s9, s1, s3
	s_cselect_b32 s8, s31, s2
	s_cselect_b32 s3, s29, s40
	s_cselect_b32 s2, s38, s39
	s_add_i32 m0, s21, 0xc000
	ds_read_b128 v[144:147], v209
	ds_read_b128 v[148:151], v209 offset:1024
	ds_read_b128 v[152:155], v209 offset:2048
	ds_read_b128 v[156:159], v209 offset:3072
	ds_read_b128 v[180:183], v209 offset:4096
	ds_read_b128 v[184:187], v209 offset:5120
	ds_read_b128 v[188:191], v209 offset:6144
	global_load_lds_dwordx4 v164, s[6:7]
	s_add_i32 m0, s21, 0xe000
	ds_read_b128 v[192:195], v209 offset:7168
	global_load_lds_dwordx4 v166, s[6:7]
	s_waitcnt lgkmcnt(8)
	s_barrier
	s_waitcnt lgkmcnt(0)
	v_mfma_f32_16x16x32_bf16 v[124:127], v[128:131], v[144:147], v[124:127]
	v_mfma_f32_16x16x32_bf16 v[120:123], v[136:139], v[144:147], v[120:123]
	v_mfma_f32_16x16x32_bf16 v[116:119], v[128:131], v[152:155], v[116:119]
	v_mfma_f32_16x16x32_bf16 v[112:115], v[136:139], v[152:155], v[112:115]
	v_mfma_f32_16x16x32_bf16 v[100:103], v[128:131], v[180:183], v[100:103]
	v_mfma_f32_16x16x32_bf16 v[96:99], v[136:139], v[180:183], v[96:99]
	v_mfma_f32_16x16x32_bf16 v[84:87], v[128:131], v[188:191], v[84:87]
	v_mfma_f32_16x16x32_bf16 v[80:83], v[136:139], v[188:191], v[80:83]
	v_mfma_f32_16x16x32_bf16 v[124:127], v[132:135], v[148:151], v[124:127]
	v_mfma_f32_16x16x32_bf16 v[120:123], v[140:143], v[148:151], v[120:123]
	v_mfma_f32_16x16x32_bf16 v[116:119], v[132:135], v[156:159], v[116:119]
	v_mfma_f32_16x16x32_bf16 v[112:115], v[140:143], v[156:159], v[112:115]
	v_mfma_f32_16x16x32_bf16 v[100:103], v[132:135], v[184:187], v[100:103]
	v_mfma_f32_16x16x32_bf16 v[96:99], v[140:143], v[184:187], v[96:99]
	v_mfma_f32_16x16x32_bf16 v[84:87], v[132:135], v[192:195], v[84:87]
	v_mfma_f32_16x16x32_bf16 v[80:83], v[140:143], v[192:195], v[80:83]
	s_barrier
	s_add_u32 s98, s2, 0x80
	s_addc_u32 s99, s3, 0
	s_add_i32 m0, s54, 0x10000
	ds_read_b128 v[196:199], v208 offset:16384
	ds_read_b128 v[200:203], v208 offset:17408
	ds_read_b128 v[210:213], v208 offset:18432
	global_load_lds_dwordx4 v160, s[2:3]
	s_add_i32 m0, s54, 0x12000
	ds_read_b128 v[214:217], v208 offset:19456
	global_load_lds_dwordx4 v162, s[2:3]
	s_barrier
	s_waitcnt lgkmcnt(0)
	v_mfma_f32_16x16x32_bf16 v[108:111], v[196:199], v[144:147], v[108:111]
	v_mfma_f32_16x16x32_bf16 v[104:107], v[210:213], v[144:147], v[104:107]
	v_mfma_f32_16x16x32_bf16 v[92:95], v[196:199], v[152:155], v[92:95]
	v_mfma_f32_16x16x32_bf16 v[88:91], v[210:213], v[152:155], v[88:91]
	v_mfma_f32_16x16x32_bf16 v[76:79], v[196:199], v[180:183], v[76:79]
	v_mfma_f32_16x16x32_bf16 v[72:75], v[210:213], v[180:183], v[72:75]
	v_mfma_f32_16x16x32_bf16 v[68:71], v[196:199], v[188:191], v[68:71]
	v_mfma_f32_16x16x32_bf16 v[64:67], v[210:213], v[188:191], v[64:67]
	v_mfma_f32_16x16x32_bf16 v[108:111], v[200:203], v[148:151], v[108:111]
	v_mfma_f32_16x16x32_bf16 v[104:107], v[214:217], v[148:151], v[104:107]
	v_mfma_f32_16x16x32_bf16 v[92:95], v[200:203], v[156:159], v[92:95]
	v_mfma_f32_16x16x32_bf16 v[88:91], v[214:217], v[156:159], v[88:91]
	v_mfma_f32_16x16x32_bf16 v[76:79], v[200:203], v[184:187], v[76:79]
	v_mfma_f32_16x16x32_bf16 v[72:75], v[214:217], v[184:187], v[72:75]
	v_mfma_f32_16x16x32_bf16 v[68:71], v[200:203], v[192:195], v[68:71]
	v_mfma_f32_16x16x32_bf16 v[64:67], v[214:217], v[192:195], v[64:67]
	s_mov_b32 m0, s21
	s_add_u32 s100, s8, 0x80
	s_addc_u32 s101, s9, 0
	s_barrier
	ds_read_b128 v[144:147], v209 offset:16384
	ds_read_b128 v[148:151], v209 offset:17408
	ds_read_b128 v[152:155], v209 offset:18432
	ds_read_b128 v[156:159], v209 offset:19456
	ds_read_b128 v[180:183], v209 offset:20480
	ds_read_b128 v[184:187], v209 offset:21504
	ds_read_b128 v[188:191], v209 offset:22528
	global_load_lds_dwordx4 v160, s[8:9]
	s_mov_b32 m0, s55
	ds_read_b128 v[192:195], v209 offset:23552
	global_load_lds_dwordx4 v162, s[8:9]
	s_barrier
	s_waitcnt lgkmcnt(0)
	v_mfma_f32_16x16x32_bf16 v[60:63], v[128:131], v[144:147], v[60:63]
	v_mfma_f32_16x16x32_bf16 v[56:59], v[136:139], v[144:147], v[56:59]
	v_mfma_f32_16x16x32_bf16 v[52:55], v[128:131], v[152:155], v[52:55]
	v_mfma_f32_16x16x32_bf16 v[48:51], v[136:139], v[152:155], v[48:51]
	v_mfma_f32_16x16x32_bf16 v[36:39], v[128:131], v[180:183], v[36:39]
	v_mfma_f32_16x16x32_bf16 v[32:35], v[136:139], v[180:183], v[32:35]
	v_mfma_f32_16x16x32_bf16 v[20:23], v[128:131], v[188:191], v[20:23]
	v_mfma_f32_16x16x32_bf16 v[16:19], v[136:139], v[188:191], v[16:19]
	v_mfma_f32_16x16x32_bf16 v[60:63], v[132:135], v[148:151], v[60:63]
	v_mfma_f32_16x16x32_bf16 v[56:59], v[140:143], v[148:151], v[56:59]
	v_mfma_f32_16x16x32_bf16 v[52:55], v[132:135], v[156:159], v[52:55]
	v_mfma_f32_16x16x32_bf16 v[48:51], v[140:143], v[156:159], v[48:51]
	v_mfma_f32_16x16x32_bf16 v[36:39], v[132:135], v[184:187], v[36:39]
	v_mfma_f32_16x16x32_bf16 v[32:35], v[140:143], v[184:187], v[32:35]
	v_mfma_f32_16x16x32_bf16 v[20:23], v[132:135], v[192:195], v[20:23]
	v_mfma_f32_16x16x32_bf16 v[16:19], v[140:143], v[192:195], v[16:19]
	s_barrier
	s_add_i32 m0, s54, 0x14000
	s_add_u32 s64, s2, 0x40000
	s_addc_u32 s65, s3, 0
	global_load_lds_dwordx4 v160, s[64:65]
	s_add_i32 m0, s54, 0x16000
	s_add_u32 s8, s8, 0x40000
	s_addc_u32 s9, s9, 0
	global_load_lds_dwordx4 v162, s[64:65]
	s_waitcnt vmcnt(6)
	s_barrier
	v_mfma_f32_16x16x32_bf16 v[44:47], v[196:199], v[144:147], v[44:47]
	v_mfma_f32_16x16x32_bf16 v[40:43], v[210:213], v[144:147], v[40:43]
	v_mfma_f32_16x16x32_bf16 v[28:31], v[196:199], v[152:155], v[28:31]
	v_mfma_f32_16x16x32_bf16 v[24:27], v[210:213], v[152:155], v[24:27]
	v_mfma_f32_16x16x32_bf16 v[12:15], v[196:199], v[180:183], v[12:15]
	v_mfma_f32_16x16x32_bf16 v[8:11], v[210:213], v[180:183], v[8:11]
	v_mfma_f32_16x16x32_bf16 v[4:7], v[196:199], v[188:191], v[4:7]
	v_mfma_f32_16x16x32_bf16 v[0:3], v[210:213], v[188:191], v[0:3]
	v_mfma_f32_16x16x32_bf16 v[44:47], v[200:203], v[148:151], v[44:47]
	v_mfma_f32_16x16x32_bf16 v[40:43], v[214:217], v[148:151], v[40:43]
	v_mfma_f32_16x16x32_bf16 v[28:31], v[200:203], v[156:159], v[28:31]
	v_mfma_f32_16x16x32_bf16 v[24:27], v[214:217], v[156:159], v[24:27]
	v_mfma_f32_16x16x32_bf16 v[12:15], v[200:203], v[184:187], v[12:15]
	v_mfma_f32_16x16x32_bf16 v[8:11], v[214:217], v[184:187], v[8:11]
	v_mfma_f32_16x16x32_bf16 v[4:7], v[200:203], v[192:195], v[4:7]
	v_mfma_f32_16x16x32_bf16 v[0:3], v[214:217], v[192:195], v[0:3]
	s_barrier
	ds_read_b128 v[128:131], v208 offset:32768
	ds_read_b128 v[132:135], v208 offset:33792
	ds_read_b128 v[136:139], v208 offset:34816
	ds_read_b128 v[140:143], v208 offset:35840
	s_mov_b32 m0, s56
	ds_read_b128 v[144:147], v209 offset:32768
	ds_read_b128 v[148:151], v209 offset:33792
	ds_read_b128 v[152:155], v209 offset:34816
	ds_read_b128 v[156:159], v209 offset:35840
	ds_read_b128 v[180:183], v209 offset:36864
	ds_read_b128 v[184:187], v209 offset:37888
	ds_read_b128 v[188:191], v209 offset:38912
	global_load_lds_dwordx4 v160, s[8:9]
	s_mov_b32 m0, s57
	ds_read_b128 v[192:195], v209 offset:39936
	global_load_lds_dwordx4 v162, s[8:9]
	s_waitcnt lgkmcnt(8)
	s_barrier
	s_waitcnt lgkmcnt(0)
	v_mfma_f32_16x16x32_bf16 v[124:127], v[128:131], v[144:147], v[124:127]
	v_mfma_f32_16x16x32_bf16 v[120:123], v[136:139], v[144:147], v[120:123]
	v_mfma_f32_16x16x32_bf16 v[116:119], v[128:131], v[152:155], v[116:119]
	v_mfma_f32_16x16x32_bf16 v[112:115], v[136:139], v[152:155], v[112:115]
	v_mfma_f32_16x16x32_bf16 v[100:103], v[128:131], v[180:183], v[100:103]
	v_mfma_f32_16x16x32_bf16 v[96:99], v[136:139], v[180:183], v[96:99]
	v_mfma_f32_16x16x32_bf16 v[84:87], v[128:131], v[188:191], v[84:87]
	v_mfma_f32_16x16x32_bf16 v[80:83], v[136:139], v[188:191], v[80:83]
	v_mfma_f32_16x16x32_bf16 v[124:127], v[132:135], v[148:151], v[124:127]
	v_mfma_f32_16x16x32_bf16 v[120:123], v[140:143], v[148:151], v[120:123]
	v_mfma_f32_16x16x32_bf16 v[116:119], v[132:135], v[156:159], v[116:119]
	v_mfma_f32_16x16x32_bf16 v[112:115], v[140:143], v[156:159], v[112:115]
	v_mfma_f32_16x16x32_bf16 v[100:103], v[132:135], v[184:187], v[100:103]
	v_mfma_f32_16x16x32_bf16 v[96:99], v[140:143], v[184:187], v[96:99]
	v_mfma_f32_16x16x32_bf16 v[84:87], v[132:135], v[192:195], v[84:87]
	v_mfma_f32_16x16x32_bf16 v[80:83], v[140:143], v[192:195], v[80:83]
	s_barrier
	s_add_i32 m0, s54, 0x18000
	ds_read_b128 v[196:199], v208 offset:49152
	ds_read_b128 v[200:203], v208 offset:50176
	ds_read_b128 v[210:213], v208 offset:51200
	global_load_lds_dwordx4 v160, s[98:99]
	s_add_i32 m0, s54, 0x1a000
	ds_read_b128 v[214:217], v208 offset:52224
	global_load_lds_dwordx4 v162, s[98:99]
	s_barrier
	s_waitcnt lgkmcnt(0)
	v_mfma_f32_16x16x32_bf16 v[108:111], v[196:199], v[144:147], v[108:111]
	v_mfma_f32_16x16x32_bf16 v[104:107], v[210:213], v[144:147], v[104:107]
	v_mfma_f32_16x16x32_bf16 v[92:95], v[196:199], v[152:155], v[92:95]
	v_mfma_f32_16x16x32_bf16 v[88:91], v[210:213], v[152:155], v[88:91]
	v_mfma_f32_16x16x32_bf16 v[76:79], v[196:199], v[180:183], v[76:79]
	v_mfma_f32_16x16x32_bf16 v[72:75], v[210:213], v[180:183], v[72:75]
	v_mfma_f32_16x16x32_bf16 v[68:71], v[196:199], v[188:191], v[68:71]
	v_mfma_f32_16x16x32_bf16 v[64:67], v[210:213], v[188:191], v[64:67]
	v_mfma_f32_16x16x32_bf16 v[108:111], v[200:203], v[148:151], v[108:111]
	v_mfma_f32_16x16x32_bf16 v[104:107], v[214:217], v[148:151], v[104:107]
	v_mfma_f32_16x16x32_bf16 v[92:95], v[200:203], v[156:159], v[92:95]
	v_mfma_f32_16x16x32_bf16 v[88:91], v[214:217], v[156:159], v[88:91]
	v_mfma_f32_16x16x32_bf16 v[76:79], v[200:203], v[184:187], v[76:79]
	v_mfma_f32_16x16x32_bf16 v[72:75], v[214:217], v[184:187], v[72:75]
	v_mfma_f32_16x16x32_bf16 v[68:71], v[200:203], v[192:195], v[68:71]
	v_mfma_f32_16x16x32_bf16 v[64:67], v[214:217], v[192:195], v[64:67]
	s_mov_b32 m0, s60
	s_barrier
	ds_read_b128 v[144:147], v209 offset:49152
	ds_read_b128 v[148:151], v209 offset:50176
	ds_read_b128 v[152:155], v209 offset:51200
	ds_read_b128 v[156:159], v209 offset:52224
	ds_read_b128 v[180:183], v209 offset:53248
	ds_read_b128 v[184:187], v209 offset:54272
	ds_read_b128 v[188:191], v209 offset:55296
	global_load_lds_dwordx4 v160, s[100:101]
	s_mov_b32 m0, s61
	ds_read_b128 v[192:195], v209 offset:56320
	global_load_lds_dwordx4 v162, s[100:101]
	s_barrier
	s_waitcnt lgkmcnt(0)
	v_mfma_f32_16x16x32_bf16 v[60:63], v[128:131], v[144:147], v[60:63]
	v_mfma_f32_16x16x32_bf16 v[56:59], v[136:139], v[144:147], v[56:59]
	v_mfma_f32_16x16x32_bf16 v[52:55], v[128:131], v[152:155], v[52:55]
	v_mfma_f32_16x16x32_bf16 v[48:51], v[136:139], v[152:155], v[48:51]
	v_mfma_f32_16x16x32_bf16 v[36:39], v[128:131], v[180:183], v[36:39]
	v_mfma_f32_16x16x32_bf16 v[32:35], v[136:139], v[180:183], v[32:35]
	v_mfma_f32_16x16x32_bf16 v[20:23], v[128:131], v[188:191], v[20:23]
	v_mfma_f32_16x16x32_bf16 v[16:19], v[136:139], v[188:191], v[16:19]
	v_mfma_f32_16x16x32_bf16 v[60:63], v[132:135], v[148:151], v[60:63]
	v_mfma_f32_16x16x32_bf16 v[56:59], v[140:143], v[148:151], v[56:59]
	v_mfma_f32_16x16x32_bf16 v[52:55], v[132:135], v[156:159], v[52:55]
	v_mfma_f32_16x16x32_bf16 v[48:51], v[140:143], v[156:159], v[48:51]
	v_mfma_f32_16x16x32_bf16 v[36:39], v[132:135], v[184:187], v[36:39]
	v_mfma_f32_16x16x32_bf16 v[32:35], v[140:143], v[184:187], v[32:35]
	v_mfma_f32_16x16x32_bf16 v[20:23], v[132:135], v[192:195], v[20:23]
	v_mfma_f32_16x16x32_bf16 v[16:19], v[140:143], v[192:195], v[16:19]
	s_barrier
	s_add_i32 m0, s54, 0x1c000
	s_add_u32 s2, s2, 0x40080
	s_addc_u32 s3, s3, 0
	global_load_lds_dwordx4 v160, s[2:3]
	s_add_i32 m0, s54, 0x1e000
	s_add_i32 s41, s41, 2
	global_load_lds_dwordx4 v162, s[2:3]
	s_waitcnt vmcnt(6)
	s_barrier
	v_mfma_f32_16x16x32_bf16 v[44:47], v[196:199], v[144:147], v[44:47]
	v_mfma_f32_16x16x32_bf16 v[40:43], v[210:213], v[144:147], v[40:43]
	v_mfma_f32_16x16x32_bf16 v[28:31], v[196:199], v[152:155], v[28:31]
	v_mfma_f32_16x16x32_bf16 v[24:27], v[210:213], v[152:155], v[24:27]
	v_mfma_f32_16x16x32_bf16 v[12:15], v[196:199], v[180:183], v[12:15]
	v_mfma_f32_16x16x32_bf16 v[8:11], v[210:213], v[180:183], v[8:11]
	v_mfma_f32_16x16x32_bf16 v[4:7], v[196:199], v[188:191], v[4:7]
	v_mfma_f32_16x16x32_bf16 v[0:3], v[210:213], v[188:191], v[0:3]
	v_mfma_f32_16x16x32_bf16 v[44:47], v[200:203], v[148:151], v[44:47]
	v_mfma_f32_16x16x32_bf16 v[40:43], v[214:217], v[148:151], v[40:43]
	v_mfma_f32_16x16x32_bf16 v[28:31], v[200:203], v[156:159], v[28:31]
	v_mfma_f32_16x16x32_bf16 v[24:27], v[214:217], v[156:159], v[24:27]
	v_mfma_f32_16x16x32_bf16 v[12:15], v[200:203], v[184:187], v[12:15]
	v_mfma_f32_16x16x32_bf16 v[8:11], v[214:217], v[184:187], v[8:11]
	v_mfma_f32_16x16x32_bf16 v[4:7], v[200:203], v[192:195], v[4:7]
	v_mfma_f32_16x16x32_bf16 v[0:3], v[214:217], v[192:195], v[0:3]
	s_add_u32 s6, s6, 0x100
	s_addc_u32 s7, s7, 0
	s_add_u32 s39, s39, 0x100
	s_addc_u32 s40, s40, 0
	s_cmp_gt_u32 s41, 13
	s_barrier
	s_cbranch_scc0 .LBB0_355
	s_lshl_b32 s1, s0, 8
	v_mov_b32_e32 v211, v206
	v_mov_b32_e32 v210, v207
	s_add_i32 s1, s1, s59
	s_cmp_lt_i32 s20, 3
	v_add_u32_e32 v180, s1, v211
	s_mov_b64 s[2:3], -1
	s_cbranch_scc0 .LBB0_490
	s_cmp_gt_i32 s0, 15
	s_cselect_b64 s[2:3], -1, 0
	s_cmp_lt_i32 s0, 16
	s_cselect_b64 s[38:39], -1, 0
	s_cmp_eq_u32 s20, 2
	s_cselect_b64 s[8:9], -1, 0
	s_cmp_lg_u32 s20, 2
	s_cselect_b64 s[0:1], -1, 0
	s_and_b64 s[40:41], s[8:9], s[22:23]
	v_lshlrev_b32_e32 v182, 2, v210
	s_mov_b64 s[6:7], -1
	s_and_b64 vcc, exec, s[40:41]
	v_ashrrev_i32_e32 v183, 31, v182
	s_cbranch_vccnz .LBB0_447
	s_and_b64 s[6:7], s[8:9], exec
	s_cselect_b32 s6, s46, s44
	s_cselect_b32 s7, s47, s45
	v_mov_b32_e32 v128, s7
	v_mov_b32_e32 v129, s6
	v_lshl_add_u64 v[128:129], v[182:183], 2, v[128:129]
	global_load_dwordx4 v[140:143], v[128:129], off
	global_load_dwordx4 v[136:139], v[128:129], off offset:64
	global_load_dwordx4 v[132:135], v[128:129], off offset:128
	s_nop 0
	global_load_dwordx4 v[128:131], v[128:129], off offset:192
	v_mul_f32_e32 v144, v125, v125
	v_mul_f32_e32 v145, v127, v127
	v_fmac_f32_e32 v144, v124, v124
	v_fmac_f32_e32 v145, v126, v126
	v_add_f32_e32 v144, v144, v145
	v_mul_f32_e32 v145, v121, v121
	v_mul_f32_e32 v146, v123, v123
	v_fmac_f32_e32 v145, v120, v120
	v_fmac_f32_e32 v146, v122, v122
	v_add_f32_e32 v145, v145, v146
	v_add_f32_e32 v144, v144, v145
	v_mul_f32_e32 v145, v109, v109
	v_mul_f32_e32 v146, v111, v111
	v_fmac_f32_e32 v145, v108, v108
	v_fmac_f32_e32 v146, v110, v110
	v_add_f32_e32 v145, v145, v146
	v_add_f32_e32 v144, v144, v145
	v_mul_f32_e32 v145, v105, v105
	v_mul_f32_e32 v146, v107, v107
	v_fmac_f32_e32 v145, v104, v104
	v_fmac_f32_e32 v146, v106, v106
	v_add_f32_e32 v145, v145, v146
	v_add_f32_e32 v144, v144, v145
	v_mov_b32_e32 v145, v144
	s_nop 1
	v_permlane16_swap_b32_e32 v144, v145
	v_add_f32_e32 v144, v144, v145
	v_mov_b32_e32 v145, v144
	s_nop 1
	v_permlane32_swap_b32_e32 v144, v145
	v_add_f32_e32 v144, v144, v145
	v_fmamk_f32 v144, v144, 0x3c800000, v225
	v_cmp_gt_f32_e32 vcc, s93, v144
	v_mul_f32_e32 v145, 0x4b800000, v144
	v_and_b32_e32 v202, 63, v211
	v_cndmask_b32_e32 v144, v144, v145, vcc
	v_rsq_f32_e32 v144, v144
	v_cndmask_b32_e64 v168, 0, 1, s[2:3]
	v_cmp_ne_u32_e64 s[6:7], 1, v168
	v_lshlrev_b32_e32 v186, 7, v202
	v_mul_f32_e32 v145, 0x45800000, v144
	v_cndmask_b32_e32 v152, v144, v145, vcc
	v_pk_mul_f32 v[144:145], v[124:125], v[152:153] op_sel_hi:[1,0]
	v_pk_mul_f32 v[146:147], v[126:127], v[152:153] op_sel_hi:[1,0]
	v_pk_mul_f32 v[148:149], v[108:109], v[152:153] op_sel_hi:[1,0]
	v_pk_mul_f32 v[150:151], v[110:111], v[152:153] op_sel_hi:[1,0]
	v_pk_mul_f32 v[184:185], v[104:105], v[152:153] op_sel_hi:[1,0]
	s_andn2_b64 vcc, exec, s[2:3]
	s_waitcnt vmcnt(0)
	v_pk_mul_f32 v[158:159], v[142:143], v[146:147]
	v_pk_mul_f32 v[156:157], v[140:141], v[144:145]
	v_pk_mul_f32 v[144:145], v[120:121], v[152:153] op_sel_hi:[1,0]
	v_pk_mul_f32 v[146:147], v[122:123], v[152:153] op_sel_hi:[1,0]
	v_pk_mul_f32 v[152:153], v[106:107], v[152:153] op_sel_hi:[1,0]
	v_pk_mul_f32 v[146:147], v[138:139], v[146:147]
	v_pk_mul_f32 v[144:145], v[136:137], v[144:145]
	v_pk_mul_f32 v[150:151], v[134:135], v[150:151]
	v_pk_mul_f32 v[148:149], v[132:133], v[148:149]
	v_pk_mul_f32 v[154:155], v[130:131], v[152:153]
	v_pk_mul_f32 v[152:153], v[128:129], v[184:185]
	v_lshl_add_u64 v[184:185], v[182:183], 3, s[18:19]
	s_cbranch_vccnz .LBB0_360
	v_lshlrev_b32_e32 v168, 1, v180
	v_and_b32_e32 v168, 0xf80, v168
	v_lshl_add_u64 v[188:189], v[184:185], 0, v[168:169]
	global_load_dwordx4 v[190:193], v[188:189], off offset:16
	global_load_dwordx4 v[194:197], v[188:189], off
	v_mov_b32_e32 v187, v169
	s_waitcnt vmcnt(0)
	v_mul_f32_e32 v198, v158, v190
	v_mov_b32_e32 v188, v194
	v_mov_b32_e32 v189, v196
	v_mov_b32_e32 v196, v195
	v_mul_f32_e32 v200, v146, v191
	v_mul_f32_e32 v204, v146, v190
	v_mul_f32_e32 v212, v158, v191
	v_mov_b32_e32 v146, v159
	v_mov_b32_e32 v158, v147
	v_pk_mul_f32 v[194:195], v[144:145], v[196:197]
	v_pk_mul_f32 v[144:145], v[144:145], v[188:189]
	v_pk_mul_f32 v[190:191], v[146:147], v[192:193]
	v_pk_mul_f32 v[146:147], v[158:159], v[192:193]
	v_lshl_add_u64 v[192:193], v[184:185], 0, v[186:187]
	v_mov_b32_e32 v199, v190
	v_mov_b32_e32 v201, v191
	v_pk_fma_f32 v[190:191], v[156:157], v[188:189], v[194:195] neg_lo:[0,0,1] neg_hi:[0,0,1]
	v_pk_fma_f32 v[144:145], v[156:157], v[196:197], v[144:145]
	global_load_dwordx4 v[156:159], v[192:193], off offset:16
	s_nop 0
	global_load_dwordx4 v[192:195], v[192:193], off
	v_pk_add_f32 v[188:189], v[198:199], v[200:201] neg_lo:[0,1] neg_hi:[0,1]
	v_mov_b32_e32 v213, v147
	v_mov_b32_e32 v205, v146
	v_pk_add_f32 v[146:147], v[212:213], v[204:205]
	s_waitcnt vmcnt(0)
	v_mul_f32_e32 v198, v150, v156
	v_mul_f32_e32 v200, v154, v157
	v_mul_f32_e32 v156, v154, v156
	v_mov_b32_e32 v154, v151
	v_mov_b32_e32 v197, v194
	v_mov_b32_e32 v194, v193
	v_mul_f32_e32 v204, v150, v157
	v_pk_mul_f32 v[212:213], v[154:155], v[158:159]
	v_mov_b32_e32 v150, v155
	v_mov_b32_e32 v196, v192
	v_pk_mul_f32 v[192:193], v[152:153], v[194:195]
	v_mov_b32_e32 v199, v212
	v_mov_b32_e32 v201, v213
	v_pk_mul_f32 v[150:151], v[150:151], v[158:159]
	v_pk_mul_f32 v[152:153], v[152:153], v[196:197]
	v_pk_fma_f32 v[192:193], v[148:149], v[196:197], v[192:193] neg_lo:[0,0,1] neg_hi:[0,0,1]
	v_pk_add_f32 v[196:197], v[198:199], v[200:201] neg_lo:[0,1] neg_hi:[0,1]
	v_mov_b32_e32 v205, v151
	v_mov_b32_e32 v157, v150
	v_pk_fma_f32 v[152:153], v[148:149], v[194:195], v[152:153]
	v_pk_add_f32 v[154:155], v[204:205], v[156:157]
	v_mov_b32_e32 v148, v192
	v_mov_b32_e32 v149, v193
	v_mov_b32_e32 v150, v196
	v_mov_b32_e32 v151, v197
	v_mov_b32_e32 v156, v190
	v_mov_b32_e32 v157, v191
	v_mov_b32_e32 v158, v188
	v_mov_b32_e32 v159, v189

.LBB0_677:
	s_ashr_i32 s23, s22, 31
	v_cmp_lt_i64_e32 vcc, s[24:25], v[174:175]
	s_lshl_b64 s[24:25], s[22:23], 19
	s_add_u32 s24, s36, s24
	s_addc_u32 s25, s37, s25
	s_and_b64 s[26:27], vcc, exec
	s_cselect_b32 s1, s25, s9
	s_cselect_b32 s7, s24, s8
	s_ashr_i32 s21, s20, 31
	s_lshl_b64 s[26:27], s[20:21], 19
	s_add_u32 s26, s38, s26
	s_addc_u32 s27, s39, s27
	s_and_b64 s[28:29], vcc, exec
	s_cselect_b32 s21, s27, s3
	s_cselect_b32 s23, s26, s2
	s_add_u32 s8, s8, 0x40080
	s_addc_u32 s9, s9, 0
	s_add_u32 s56, s2, 0x100
	s_addc_u32 s57, s3, 0
	s_mov_b32 s58, -2
	s_add_u32 s2, s8, 0xfffc0080
	s_addc_u32 s3, s9, -1
	ds_read_b128 v[48:51], v206
	ds_read_b128 v[52:55], v206 offset:1024
	ds_read_b128 v[60:63], v206 offset:2048
	ds_read_b128 v[68:71], v206 offset:3072
	s_cmp_eq_u32 s58, 12
	s_cselect_b32 s29, s1, s3
	s_cselect_b32 s28, s7, s2
	s_cselect_b32 s3, s21, s57
	s_cselect_b32 s2, s23, s56
	s_add_i32 m0, s41, 0xc000
	ds_read_b128 v[72:75], v207
	ds_read_b128 v[76:79], v207 offset:1024
	ds_read_b128 v[80:83], v207 offset:2048
	ds_read_b128 v[84:87], v207 offset:3072
	ds_read_b128 v[160:163], v207 offset:4096
	ds_read_b128 v[164:167], v207 offset:5120
	ds_read_b128 v[192:195], v207 offset:6144
	global_load_lds_dwordx4 v188, s[8:9]
	s_add_i32 m0, s41, 0xe000
	ds_read_b128 v[196:199], v207 offset:7168
	global_load_lds_dwordx4 v190, s[8:9]
	s_waitcnt lgkmcnt(8)
	s_barrier
	s_waitcnt lgkmcnt(0)
	v_mfma_f32_16x16x32_bf16 v[156:159], v[48:51], v[72:75], 0
	v_mfma_f32_16x16x32_bf16 v[152:155], v[60:63], v[72:75], 0
	v_mfma_f32_16x16x32_bf16 v[140:143], v[48:51], v[80:83], 0
	v_mfma_f32_16x16x32_bf16 v[136:139], v[60:63], v[80:83], 0
	v_mfma_f32_16x16x32_bf16 v[124:127], v[48:51], v[160:163], 0
	v_mfma_f32_16x16x32_bf16 v[120:123], v[60:63], v[160:163], 0
	v_mfma_f32_16x16x32_bf16 v[108:111], v[48:51], v[192:195], 0
	v_mfma_f32_16x16x32_bf16 v[104:107], v[60:63], v[192:195], 0
	v_mfma_f32_16x16x32_bf16 v[156:159], v[52:55], v[76:79], v[156:159]
	v_mfma_f32_16x16x32_bf16 v[152:155], v[68:71], v[76:79], v[152:155]
	v_mfma_f32_16x16x32_bf16 v[140:143], v[52:55], v[84:87], v[140:143]
	v_mfma_f32_16x16x32_bf16 v[136:139], v[68:71], v[84:87], v[136:139]
	v_mfma_f32_16x16x32_bf16 v[124:127], v[52:55], v[164:167], v[124:127]
	v_mfma_f32_16x16x32_bf16 v[120:123], v[68:71], v[164:167], v[120:123]
	v_mfma_f32_16x16x32_bf16 v[108:111], v[52:55], v[196:199], v[108:111]
	v_mfma_f32_16x16x32_bf16 v[104:107], v[68:71], v[196:199], v[104:107]
	s_barrier
	s_add_u32 s98, s2, 0x80
	s_addc_u32 s99, s3, 0
	s_add_i32 m0, s40, 0x10000
	ds_read_b128 v[200:203], v206 offset:16384
	ds_read_b128 v[208:211], v206 offset:17408
	ds_read_b128 v[212:215], v206 offset:18432
	global_load_lds_dwordx4 v182, s[2:3]
	s_add_i32 m0, s40, 0x12000
	ds_read_b128 v[216:219], v206 offset:19456
	global_load_lds_dwordx4 v186, s[2:3]
	s_barrier
	s_waitcnt lgkmcnt(0)
	v_mfma_f32_16x16x32_bf16 v[148:151], v[200:203], v[72:75], 0
	v_mfma_f32_16x16x32_bf16 v[72:75], v[212:215], v[72:75], 0
	v_mfma_f32_16x16x32_bf16 v[148:151], v[208:211], v[76:79], v[148:151]
	v_mfma_f32_16x16x32_bf16 v[72:75], v[216:219], v[76:79], v[72:75]
	v_mfma_f32_16x16x32_bf16 v[76:79], v[200:203], v[80:83], 0
	v_mfma_f32_16x16x32_bf16 v[80:83], v[212:215], v[80:83], 0
	v_mfma_f32_16x16x32_bf16 v[112:115], v[212:215], v[160:163], 0
	v_mfma_f32_16x16x32_bf16 v[100:103], v[200:203], v[192:195], 0
	v_mfma_f32_16x16x32_bf16 v[96:99], v[212:215], v[192:195], 0
	v_mfma_f32_16x16x32_bf16 v[76:79], v[208:211], v[84:87], v[76:79]
	v_mfma_f32_16x16x32_bf16 v[80:83], v[216:219], v[84:87], v[80:83]
	v_mfma_f32_16x16x32_bf16 v[84:87], v[200:203], v[160:163], 0
	v_mfma_f32_16x16x32_bf16 v[112:115], v[216:219], v[164:167], v[112:115]
	v_mfma_f32_16x16x32_bf16 v[100:103], v[208:211], v[196:199], v[100:103]
	v_mfma_f32_16x16x32_bf16 v[96:99], v[216:219], v[196:199], v[96:99]
	v_mfma_f32_16x16x32_bf16 v[84:87], v[208:211], v[164:167], v[84:87]
	s_mov_b32 m0, s41
	s_add_u32 s100, s28, 0x80
	s_addc_u32 s101, s29, 0
	s_barrier
	ds_read_b128 v[116:119], v207 offset:16384
	ds_read_b128 v[128:131], v207 offset:17408
	ds_read_b128 v[132:135], v207 offset:18432
	ds_read_b128 v[144:147], v207 offset:19456
	ds_read_b128 v[160:163], v207 offset:20480
	ds_read_b128 v[164:167], v207 offset:21504
	ds_read_b128 v[192:195], v207 offset:22528
	global_load_lds_dwordx4 v180, s[28:29]
	s_mov_b32 m0, s42
	ds_read_b128 v[196:199], v207 offset:23552
	global_load_lds_dwordx4 v184, s[28:29]
	s_barrier
	s_waitcnt lgkmcnt(0)
	v_mfma_f32_16x16x32_bf16 v[92:95], v[48:51], v[116:119], 0
	v_mfma_f32_16x16x32_bf16 v[88:91], v[60:63], v[116:119], 0
	v_mfma_f32_16x16x32_bf16 v[44:47], v[48:51], v[132:135], 0
	v_mfma_f32_16x16x32_bf16 v[40:43], v[60:63], v[132:135], 0
	v_mfma_f32_16x16x32_bf16 v[28:31], v[48:51], v[160:163], 0
	v_mfma_f32_16x16x32_bf16 v[24:27], v[60:63], v[160:163], 0
	v_mfma_f32_16x16x32_bf16 v[12:15], v[48:51], v[192:195], 0
	v_mfma_f32_16x16x32_bf16 v[8:11], v[60:63], v[192:195], 0
	v_mfma_f32_16x16x32_bf16 v[92:95], v[52:55], v[128:131], v[92:95]
	v_mfma_f32_16x16x32_bf16 v[88:91], v[68:71], v[128:131], v[88:91]
	v_mfma_f32_16x16x32_bf16 v[44:47], v[52:55], v[144:147], v[44:47]
	v_mfma_f32_16x16x32_bf16 v[40:43], v[68:71], v[144:147], v[40:43]
	v_mfma_f32_16x16x32_bf16 v[28:31], v[52:55], v[164:167], v[28:31]
	v_mfma_f32_16x16x32_bf16 v[24:27], v[68:71], v[164:167], v[24:27]
	v_mfma_f32_16x16x32_bf16 v[12:15], v[52:55], v[196:199], v[12:15]
	v_mfma_f32_16x16x32_bf16 v[8:11], v[68:71], v[196:199], v[8:11]
	s_barrier
	s_add_i32 m0, s40, 0x14000
	s_add_u32 s60, s2, 0x40000
	s_addc_u32 s61, s3, 0
	global_load_lds_dwordx4 v182, s[60:61]
	s_add_i32 m0, s40, 0x16000
	s_add_u32 s28, s28, 0x40000
	s_addc_u32 s29, s29, 0
	global_load_lds_dwordx4 v186, s[60:61]
	s_waitcnt vmcnt(6)
	s_barrier
	v_mfma_f32_16x16x32_bf16 v[36:39], v[200:203], v[132:135], 0
	v_mfma_f32_16x16x32_bf16 v[32:35], v[212:215], v[132:135], 0
	v_mfma_f32_16x16x32_bf16 v[20:23], v[200:203], v[160:163], 0
	v_mfma_f32_16x16x32_bf16 v[16:19], v[212:215], v[160:163], 0
	v_mfma_f32_16x16x32_bf16 v[4:7], v[200:203], v[192:195], 0
	v_mfma_f32_16x16x32_bf16 v[0:3], v[212:215], v[192:195], 0
	v_mfma_f32_16x16x32_bf16 v[48:51], v[200:203], v[116:119], 0
	v_mfma_f32_16x16x32_bf16 v[52:55], v[212:215], v[116:119], 0
	v_mfma_f32_16x16x32_bf16 v[36:39], v[208:211], v[144:147], v[36:39]
	v_mfma_f32_16x16x32_bf16 v[32:35], v[216:219], v[144:147], v[32:35]
	v_mfma_f32_16x16x32_bf16 v[20:23], v[208:211], v[164:167], v[20:23]
	v_mfma_f32_16x16x32_bf16 v[16:19], v[216:219], v[164:167], v[16:19]
	v_mfma_f32_16x16x32_bf16 v[4:7], v[208:211], v[196:199], v[4:7]
	v_mfma_f32_16x16x32_bf16 v[0:3], v[216:219], v[196:199], v[0:3]
	v_mfma_f32_16x16x32_bf16 v[48:51], v[208:211], v[128:131], v[48:51]
	v_mfma_f32_16x16x32_bf16 v[52:55], v[216:219], v[128:131], v[52:55]
	s_barrier
	ds_read_b128 v[56:59], v206 offset:32768
	ds_read_b128 v[60:63], v206 offset:33792
	ds_read_b128 v[64:67], v206 offset:34816
	ds_read_b128 v[68:71], v206 offset:35840
	s_mov_b32 m0, s43
	ds_read_b128 v[116:119], v207 offset:32768
	ds_read_b128 v[128:131], v207 offset:33792
	ds_read_b128 v[160:163], v207 offset:34816
	ds_read_b128 v[164:167], v207 offset:35840
	ds_read_b128 v[192:195], v207 offset:36864
	ds_read_b128 v[196:199], v207 offset:37888
	ds_read_b128 v[200:203], v207 offset:38912
	global_load_lds_dwordx4 v180, s[28:29]
	s_mov_b32 m0, s44
	ds_read_b128 v[208:211], v207 offset:39936
	global_load_lds_dwordx4 v184, s[28:29]
	s_waitcnt lgkmcnt(8)
	s_barrier
	s_waitcnt lgkmcnt(0)
	v_mfma_f32_16x16x32_bf16 v[132:135], v[56:59], v[116:119], v[156:159]
	v_mfma_f32_16x16x32_bf16 v[156:159], v[60:63], v[128:131], v[132:135]
	v_mfma_f32_16x16x32_bf16 v[132:135], v[64:67], v[116:119], v[152:155]
	v_mfma_f32_16x16x32_bf16 v[152:155], v[68:71], v[128:131], v[132:135]
	v_mfma_f32_16x16x32_bf16 v[132:135], v[56:59], v[160:163], v[140:143]
	v_mfma_f32_16x16x32_bf16 v[140:143], v[60:63], v[164:167], v[132:135]
	v_mfma_f32_16x16x32_bf16 v[132:135], v[64:67], v[160:163], v[136:139]
	v_mfma_f32_16x16x32_bf16 v[124:127], v[56:59], v[192:195], v[124:127]
	v_mfma_f32_16x16x32_bf16 v[120:123], v[64:67], v[192:195], v[120:123]
	v_mfma_f32_16x16x32_bf16 v[108:111], v[56:59], v[200:203], v[108:111]
	v_mfma_f32_16x16x32_bf16 v[104:107], v[64:67], v[200:203], v[104:107]
	v_mfma_f32_16x16x32_bf16 v[136:139], v[68:71], v[164:167], v[132:135]
	v_mfma_f32_16x16x32_bf16 v[124:127], v[60:63], v[196:199], v[124:127]
	v_mfma_f32_16x16x32_bf16 v[120:123], v[68:71], v[196:199], v[120:123]
	v_mfma_f32_16x16x32_bf16 v[108:111], v[60:63], v[208:211], v[108:111]
	v_mfma_f32_16x16x32_bf16 v[104:107], v[68:71], v[208:211], v[104:107]
	s_barrier
	ds_read_b128 v[212:215], v206 offset:49152
	ds_read_b128 v[216:219], v206 offset:50176
	s_add_i32 m0, s40, 0x18000
	ds_read_b128 v[220:223], v206 offset:51200
	global_load_lds_dwordx4 v182, s[98:99]
	s_add_i32 m0, s40, 0x1a000
	ds_read_b128 v[236:239], v206 offset:52224
	global_load_lds_dwordx4 v186, s[98:99]
	s_barrier
	s_waitcnt lgkmcnt(0)
	v_mfma_f32_16x16x32_bf16 v[72:75], v[220:223], v[116:119], v[72:75]
	v_mfma_f32_16x16x32_bf16 v[132:135], v[212:215], v[116:119], v[148:151]
	v_mfma_f32_16x16x32_bf16 v[144:147], v[236:239], v[128:131], v[72:75]
	v_mfma_f32_16x16x32_bf16 v[72:75], v[212:215], v[160:163], v[76:79]
	v_mfma_f32_16x16x32_bf16 v[148:151], v[216:219], v[128:131], v[132:135]
	v_mfma_f32_16x16x32_bf16 v[132:135], v[216:219], v[164:167], v[72:75]
	v_mfma_f32_16x16x32_bf16 v[72:75], v[220:223], v[160:163], v[80:83]
	v_mfma_f32_16x16x32_bf16 v[128:131], v[236:239], v[164:167], v[72:75]
	v_mfma_f32_16x16x32_bf16 v[72:75], v[212:215], v[192:195], v[84:87]
	v_mfma_f32_16x16x32_bf16 v[116:119], v[216:219], v[196:199], v[72:75]
	v_mfma_f32_16x16x32_bf16 v[72:75], v[220:223], v[192:195], v[112:115]
	v_mfma_f32_16x16x32_bf16 v[112:115], v[236:239], v[196:199], v[72:75]
	v_mfma_f32_16x16x32_bf16 v[72:75], v[212:215], v[200:203], v[100:103]
	v_mfma_f32_16x16x32_bf16 v[100:103], v[216:219], v[208:211], v[72:75]
	v_mfma_f32_16x16x32_bf16 v[72:75], v[220:223], v[200:203], v[96:99]
	v_mfma_f32_16x16x32_bf16 v[96:99], v[236:239], v[208:211], v[72:75]
	s_mov_b32 m0, s53
	s_barrier
	s_nop 2
	ds_read_b128 v[72:75], v207 offset:49152
	ds_read_b128 v[76:79], v207 offset:50176
	ds_read_b128 v[80:83], v207 offset:51200
	ds_read_b128 v[84:87], v207 offset:52224
	ds_read_b128 v[160:163], v207 offset:53248
	ds_read_b128 v[164:167], v207 offset:54272
	ds_read_b128 v[192:195], v207 offset:55296
	global_load_lds_dwordx4 v180, s[100:101]
	s_mov_b32 m0, s54
	ds_read_b128 v[196:199], v207 offset:56320
	global_load_lds_dwordx4 v184, s[100:101]
	s_barrier
	s_waitcnt lgkmcnt(0)
	v_mfma_f32_16x16x32_bf16 v[92:95], v[56:59], v[72:75], v[92:95]
	v_mfma_f32_16x16x32_bf16 v[88:91], v[64:67], v[72:75], v[88:91]
	v_mfma_f32_16x16x32_bf16 v[44:47], v[56:59], v[80:83], v[44:47]
	v_mfma_f32_16x16x32_bf16 v[40:43], v[64:67], v[80:83], v[40:43]
	v_mfma_f32_16x16x32_bf16 v[28:31], v[56:59], v[160:163], v[28:31]
	v_mfma_f32_16x16x32_bf16 v[24:27], v[64:67], v[160:163], v[24:27]
	v_mfma_f32_16x16x32_bf16 v[12:15], v[56:59], v[192:195], v[12:15]
	v_mfma_f32_16x16x32_bf16 v[8:11], v[64:67], v[192:195], v[8:11]
	v_mfma_f32_16x16x32_bf16 v[92:95], v[60:63], v[76:79], v[92:95]
	v_mfma_f32_16x16x32_bf16 v[88:91], v[68:71], v[76:79], v[88:91]
	v_mfma_f32_16x16x32_bf16 v[44:47], v[60:63], v[84:87], v[44:47]
	v_mfma_f32_16x16x32_bf16 v[40:43], v[68:71], v[84:87], v[40:43]
	v_mfma_f32_16x16x32_bf16 v[28:31], v[60:63], v[164:167], v[28:31]
	v_mfma_f32_16x16x32_bf16 v[24:27], v[68:71], v[164:167], v[24:27]
	v_mfma_f32_16x16x32_bf16 v[12:15], v[60:63], v[196:199], v[12:15]
	v_mfma_f32_16x16x32_bf16 v[8:11], v[68:71], v[196:199], v[8:11]
	s_barrier
	s_add_i32 m0, s40, 0x1c000
	s_add_u32 s2, s2, 0x40080
	s_addc_u32 s3, s3, 0
	global_load_lds_dwordx4 v182, s[2:3]
	s_add_i32 m0, s40, 0x1e000
	s_add_i32 s58, s58, 2
	global_load_lds_dwordx4 v186, s[2:3]
	s_waitcnt vmcnt(6)
	s_barrier
	v_mfma_f32_16x16x32_bf16 v[48:51], v[212:215], v[72:75], v[48:51]
	v_mfma_f32_16x16x32_bf16 v[64:67], v[216:219], v[76:79], v[48:51]
	v_mfma_f32_16x16x32_bf16 v[48:51], v[220:223], v[72:75], v[52:55]
	v_mfma_f32_16x16x32_bf16 v[36:39], v[212:215], v[80:83], v[36:39]
	v_mfma_f32_16x16x32_bf16 v[32:35], v[220:223], v[80:83], v[32:35]
	v_mfma_f32_16x16x32_bf16 v[20:23], v[212:215], v[160:163], v[20:23]
	v_mfma_f32_16x16x32_bf16 v[16:19], v[220:223], v[160:163], v[16:19]
	v_mfma_f32_16x16x32_bf16 v[4:7], v[212:215], v[192:195], v[4:7]
	v_mfma_f32_16x16x32_bf16 v[0:3], v[220:223], v[192:195], v[0:3]
	v_mfma_f32_16x16x32_bf16 v[56:59], v[236:239], v[76:79], v[48:51]
	v_mfma_f32_16x16x32_bf16 v[36:39], v[216:219], v[84:87], v[36:39]
	v_mfma_f32_16x16x32_bf16 v[32:35], v[236:239], v[84:87], v[32:35]
	v_mfma_f32_16x16x32_bf16 v[20:23], v[216:219], v[164:167], v[20:23]
	v_mfma_f32_16x16x32_bf16 v[16:19], v[236:239], v[164:167], v[16:19]
	v_mfma_f32_16x16x32_bf16 v[4:7], v[216:219], v[196:199], v[4:7]
	v_mfma_f32_16x16x32_bf16 v[0:3], v[236:239], v[196:199], v[0:3]
	s_add_u32 s8, s8, 0x100
	s_addc_u32 s9, s9, 0
	s_add_u32 s56, s56, 0x100
	s_addc_u32 s57, s57, 0
	s_cmp_gt_u32 s58, 13
	s_barrier
.LBB0_678:
	s_add_u32 s2, s8, 0xfffc0080
	s_addc_u32 s3, s9, -1
	ds_read_b128 v[48:51], v206
	ds_read_b128 v[52:55], v206 offset:1024
	ds_read_b128 v[60:63], v206 offset:2048
	ds_read_b128 v[68:71], v206 offset:3072
	s_cmp_eq_u32 s58, 12
	s_cselect_b32 s29, s1, s3
	s_cselect_b32 s28, s7, s2
	s_cselect_b32 s3, s21, s57
	s_cselect_b32 s2, s23, s56
	s_add_i32 m0, s41, 0xc000
	ds_read_b128 v[72:75], v207
	ds_read_b128 v[76:79], v207 offset:1024
	ds_read_b128 v[80:83], v207 offset:2048
	ds_read_b128 v[84:87], v207 offset:3072
	ds_read_b128 v[160:163], v207 offset:4096
	ds_read_b128 v[164:167], v207 offset:5120
	ds_read_b128 v[192:195], v207 offset:6144
	global_load_lds_dwordx4 v188, s[8:9]
	s_add_i32 m0, s41, 0xe000
	ds_read_b128 v[196:199], v207 offset:7168
	global_load_lds_dwordx4 v190, s[8:9]
	s_waitcnt lgkmcnt(8)
	s_barrier
	s_waitcnt lgkmcnt(0)
	v_mfma_f32_16x16x32_bf16 v[156:159], v[48:51], v[72:75], v[156:159]
	v_mfma_f32_16x16x32_bf16 v[152:155], v[60:63], v[72:75], v[152:155]
	v_mfma_f32_16x16x32_bf16 v[140:143], v[48:51], v[80:83], v[140:143]
	v_mfma_f32_16x16x32_bf16 v[136:139], v[60:63], v[80:83], v[136:139]
	v_mfma_f32_16x16x32_bf16 v[124:127], v[48:51], v[160:163], v[124:127]
	v_mfma_f32_16x16x32_bf16 v[120:123], v[60:63], v[160:163], v[120:123]
	v_mfma_f32_16x16x32_bf16 v[108:111], v[48:51], v[192:195], v[108:111]
	v_mfma_f32_16x16x32_bf16 v[104:107], v[60:63], v[192:195], v[104:107]
	v_mfma_f32_16x16x32_bf16 v[156:159], v[52:55], v[76:79], v[156:159]
	v_mfma_f32_16x16x32_bf16 v[152:155], v[68:71], v[76:79], v[152:155]
	v_mfma_f32_16x16x32_bf16 v[140:143], v[52:55], v[84:87], v[140:143]
	v_mfma_f32_16x16x32_bf16 v[136:139], v[68:71], v[84:87], v[136:139]
	v_mfma_f32_16x16x32_bf16 v[124:127], v[52:55], v[164:167], v[124:127]
	v_mfma_f32_16x16x32_bf16 v[120:123], v[68:71], v[164:167], v[120:123]
	v_mfma_f32_16x16x32_bf16 v[108:111], v[52:55], v[196:199], v[108:111]
	v_mfma_f32_16x16x32_bf16 v[104:107], v[68:71], v[196:199], v[104:107]
	s_barrier
	s_add_u32 s98, s2, 0x80
	s_addc_u32 s99, s3, 0
	s_add_i32 m0, s40, 0x10000
	ds_read_b128 v[200:203], v206 offset:16384
	ds_read_b128 v[208:211], v206 offset:17408
	ds_read_b128 v[212:215], v206 offset:18432
	global_load_lds_dwordx4 v182, s[2:3]
	s_add_i32 m0, s40, 0x12000
	ds_read_b128 v[216:219], v206 offset:19456
	global_load_lds_dwordx4 v186, s[2:3]
	s_barrier
	s_waitcnt lgkmcnt(0)
	v_mfma_f32_16x16x32_bf16 v[148:151], v[200:203], v[72:75], v[148:151]
	v_mfma_f32_16x16x32_bf16 v[72:75], v[212:215], v[72:75], v[144:147]
	v_mfma_f32_16x16x32_bf16 v[148:151], v[208:211], v[76:79], v[148:151]
	v_mfma_f32_16x16x32_bf16 v[72:75], v[216:219], v[76:79], v[72:75]
	v_mfma_f32_16x16x32_bf16 v[76:79], v[200:203], v[80:83], v[132:135]
	v_mfma_f32_16x16x32_bf16 v[80:83], v[212:215], v[80:83], v[128:131]
	v_mfma_f32_16x16x32_bf16 v[112:115], v[212:215], v[160:163], v[112:115]
	v_mfma_f32_16x16x32_bf16 v[100:103], v[200:203], v[192:195], v[100:103]
	v_mfma_f32_16x16x32_bf16 v[96:99], v[212:215], v[192:195], v[96:99]
	v_mfma_f32_16x16x32_bf16 v[76:79], v[208:211], v[84:87], v[76:79]
	v_mfma_f32_16x16x32_bf16 v[80:83], v[216:219], v[84:87], v[80:83]
	v_mfma_f32_16x16x32_bf16 v[84:87], v[200:203], v[160:163], v[116:119]
	v_mfma_f32_16x16x32_bf16 v[112:115], v[216:219], v[164:167], v[112:115]
	v_mfma_f32_16x16x32_bf16 v[100:103], v[208:211], v[196:199], v[100:103]
	v_mfma_f32_16x16x32_bf16 v[96:99], v[216:219], v[196:199], v[96:99]
	v_mfma_f32_16x16x32_bf16 v[84:87], v[208:211], v[164:167], v[84:87]
	s_mov_b32 m0, s41
	s_add_u32 s100, s28, 0x80
	s_addc_u32 s101, s29, 0
	s_barrier
	ds_read_b128 v[116:119], v207 offset:16384
	ds_read_b128 v[128:131], v207 offset:17408
	ds_read_b128 v[132:135], v207 offset:18432
	ds_read_b128 v[144:147], v207 offset:19456
	ds_read_b128 v[160:163], v207 offset:20480
	ds_read_b128 v[164:167], v207 offset:21504
	ds_read_b128 v[192:195], v207 offset:22528
	global_load_lds_dwordx4 v180, s[28:29]
	s_mov_b32 m0, s42
	ds_read_b128 v[196:199], v207 offset:23552
	global_load_lds_dwordx4 v184, s[28:29]
	s_barrier
	s_waitcnt lgkmcnt(0)
	v_mfma_f32_16x16x32_bf16 v[92:95], v[48:51], v[116:119], v[92:95]
	v_mfma_f32_16x16x32_bf16 v[88:91], v[60:63], v[116:119], v[88:91]
	v_mfma_f32_16x16x32_bf16 v[44:47], v[48:51], v[132:135], v[44:47]
	v_mfma_f32_16x16x32_bf16 v[40:43], v[60:63], v[132:135], v[40:43]
	v_mfma_f32_16x16x32_bf16 v[28:31], v[48:51], v[160:163], v[28:31]
	v_mfma_f32_16x16x32_bf16 v[24:27], v[60:63], v[160:163], v[24:27]
	v_mfma_f32_16x16x32_bf16 v[12:15], v[48:51], v[192:195], v[12:15]
	v_mfma_f32_16x16x32_bf16 v[8:11], v[60:63], v[192:195], v[8:11]
	v_mfma_f32_16x16x32_bf16 v[92:95], v[52:55], v[128:131], v[92:95]
	v_mfma_f32_16x16x32_bf16 v[88:91], v[68:71], v[128:131], v[88:91]
	v_mfma_f32_16x16x32_bf16 v[44:47], v[52:55], v[144:147], v[44:47]
	v_mfma_f32_16x16x32_bf16 v[40:43], v[68:71], v[144:147], v[40:43]
	v_mfma_f32_16x16x32_bf16 v[28:31], v[52:55], v[164:167], v[28:31]
	v_mfma_f32_16x16x32_bf16 v[24:27], v[68:71], v[164:167], v[24:27]
	v_mfma_f32_16x16x32_bf16 v[12:15], v[52:55], v[196:199], v[12:15]
	v_mfma_f32_16x16x32_bf16 v[8:11], v[68:71], v[196:199], v[8:11]
	s_barrier
	s_add_i32 m0, s40, 0x14000
	s_add_u32 s60, s2, 0x40000
	s_addc_u32 s61, s3, 0
	global_load_lds_dwordx4 v182, s[60:61]
	s_add_i32 m0, s40, 0x16000
	s_add_u32 s28, s28, 0x40000
	s_addc_u32 s29, s29, 0
	global_load_lds_dwordx4 v186, s[60:61]
	s_waitcnt vmcnt(6)
	s_barrier
	v_mfma_f32_16x16x32_bf16 v[36:39], v[200:203], v[132:135], v[36:39]
	v_mfma_f32_16x16x32_bf16 v[32:35], v[212:215], v[132:135], v[32:35]
	v_mfma_f32_16x16x32_bf16 v[20:23], v[200:203], v[160:163], v[20:23]
	v_mfma_f32_16x16x32_bf16 v[16:19], v[212:215], v[160:163], v[16:19]
	v_mfma_f32_16x16x32_bf16 v[4:7], v[200:203], v[192:195], v[4:7]
	v_mfma_f32_16x16x32_bf16 v[0:3], v[212:215], v[192:195], v[0:3]
	v_mfma_f32_16x16x32_bf16 v[48:51], v[200:203], v[116:119], v[64:67]
	v_mfma_f32_16x16x32_bf16 v[52:55], v[212:215], v[116:119], v[56:59]
	v_mfma_f32_16x16x32_bf16 v[36:39], v[208:211], v[144:147], v[36:39]
	v_mfma_f32_16x16x32_bf16 v[32:35], v[216:219], v[144:147], v[32:35]
	v_mfma_f32_16x16x32_bf16 v[20:23], v[208:211], v[164:167], v[20:23]
	v_mfma_f32_16x16x32_bf16 v[16:19], v[216:219], v[164:167], v[16:19]
	v_mfma_f32_16x16x32_bf16 v[4:7], v[208:211], v[196:199], v[4:7]
	v_mfma_f32_16x16x32_bf16 v[0:3], v[216:219], v[196:199], v[0:3]
	v_mfma_f32_16x16x32_bf16 v[48:51], v[208:211], v[128:131], v[48:51]
	v_mfma_f32_16x16x32_bf16 v[52:55], v[216:219], v[128:131], v[52:55]
	s_barrier
	ds_read_b128 v[56:59], v206 offset:32768
	ds_read_b128 v[60:63], v206 offset:33792
	ds_read_b128 v[64:67], v206 offset:34816
	ds_read_b128 v[68:71], v206 offset:35840
	s_mov_b32 m0, s43
	ds_read_b128 v[116:119], v207 offset:32768
	ds_read_b128 v[128:131], v207 offset:33792
	ds_read_b128 v[160:163], v207 offset:34816
	ds_read_b128 v[164:167], v207 offset:35840
	ds_read_b128 v[192:195], v207 offset:36864
	ds_read_b128 v[196:199], v207 offset:37888
	ds_read_b128 v[200:203], v207 offset:38912
	global_load_lds_dwordx4 v180, s[28:29]
	s_mov_b32 m0, s44
	ds_read_b128 v[208:211], v207 offset:39936
	global_load_lds_dwordx4 v184, s[28:29]
	s_waitcnt lgkmcnt(8)
	s_barrier
	s_waitcnt lgkmcnt(0)
	v_mfma_f32_16x16x32_bf16 v[132:135], v[56:59], v[116:119], v[156:159]
	v_mfma_f32_16x16x32_bf16 v[156:159], v[60:63], v[128:131], v[132:135]
	v_mfma_f32_16x16x32_bf16 v[132:135], v[64:67], v[116:119], v[152:155]
	v_mfma_f32_16x16x32_bf16 v[152:155], v[68:71], v[128:131], v[132:135]
	v_mfma_f32_16x16x32_bf16 v[132:135], v[56:59], v[160:163], v[140:143]
	v_mfma_f32_16x16x32_bf16 v[140:143], v[60:63], v[164:167], v[132:135]
	v_mfma_f32_16x16x32_bf16 v[132:135], v[64:67], v[160:163], v[136:139]
	v_mfma_f32_16x16x32_bf16 v[124:127], v[56:59], v[192:195], v[124:127]
	v_mfma_f32_16x16x32_bf16 v[120:123], v[64:67], v[192:195], v[120:123]
	v_mfma_f32_16x16x32_bf16 v[108:111], v[56:59], v[200:203], v[108:111]
	v_mfma_f32_16x16x32_bf16 v[104:107], v[64:67], v[200:203], v[104:107]
	v_mfma_f32_16x16x32_bf16 v[136:139], v[68:71], v[164:167], v[132:135]
	v_mfma_f32_16x16x32_bf16 v[124:127], v[60:63], v[196:199], v[124:127]
	v_mfma_f32_16x16x32_bf16 v[120:123], v[68:71], v[196:199], v[120:123]
	v_mfma_f32_16x16x32_bf16 v[108:111], v[60:63], v[208:211], v[108:111]
	v_mfma_f32_16x16x32_bf16 v[104:107], v[68:71], v[208:211], v[104:107]
	s_barrier
	ds_read_b128 v[212:215], v206 offset:49152
	ds_read_b128 v[216:219], v206 offset:50176
	s_add_i32 m0, s40, 0x18000
	ds_read_b128 v[220:223], v206 offset:51200
	global_load_lds_dwordx4 v182, s[98:99]
	s_add_i32 m0, s40, 0x1a000
	ds_read_b128 v[236:239], v206 offset:52224
	global_load_lds_dwordx4 v186, s[98:99]
	s_barrier
	s_waitcnt lgkmcnt(0)
	v_mfma_f32_16x16x32_bf16 v[72:75], v[220:223], v[116:119], v[72:75]
	v_mfma_f32_16x16x32_bf16 v[132:135], v[212:215], v[116:119], v[148:151]
	v_mfma_f32_16x16x32_bf16 v[144:147], v[236:239], v[128:131], v[72:75]
	v_mfma_f32_16x16x32_bf16 v[72:75], v[212:215], v[160:163], v[76:79]
	v_mfma_f32_16x16x32_bf16 v[148:151], v[216:219], v[128:131], v[132:135]
	v_mfma_f32_16x16x32_bf16 v[132:135], v[216:219], v[164:167], v[72:75]
	v_mfma_f32_16x16x32_bf16 v[72:75], v[220:223], v[160:163], v[80:83]
	v_mfma_f32_16x16x32_bf16 v[128:131], v[236:239], v[164:167], v[72:75]
	v_mfma_f32_16x16x32_bf16 v[72:75], v[212:215], v[192:195], v[84:87]
	v_mfma_f32_16x16x32_bf16 v[116:119], v[216:219], v[196:199], v[72:75]
	v_mfma_f32_16x16x32_bf16 v[72:75], v[220:223], v[192:195], v[112:115]
	v_mfma_f32_16x16x32_bf16 v[112:115], v[236:239], v[196:199], v[72:75]
	v_mfma_f32_16x16x32_bf16 v[72:75], v[212:215], v[200:203], v[100:103]
	v_mfma_f32_16x16x32_bf16 v[100:103], v[216:219], v[208:211], v[72:75]
	v_mfma_f32_16x16x32_bf16 v[72:75], v[220:223], v[200:203], v[96:99]
	v_mfma_f32_16x16x32_bf16 v[96:99], v[236:239], v[208:211], v[72:75]
	s_mov_b32 m0, s53
	s_barrier
	s_nop 2
	ds_read_b128 v[72:75], v207 offset:49152
	ds_read_b128 v[76:79], v207 offset:50176
	ds_read_b128 v[80:83], v207 offset:51200
	ds_read_b128 v[84:87], v207 offset:52224
	ds_read_b128 v[160:163], v207 offset:53248
	ds_read_b128 v[164:167], v207 offset:54272
	ds_read_b128 v[192:195], v207 offset:55296
	global_load_lds_dwordx4 v180, s[100:101]
	s_mov_b32 m0, s54
	ds_read_b128 v[196:199], v207 offset:56320
	global_load_lds_dwordx4 v184, s[100:101]
	s_barrier
	s_waitcnt lgkmcnt(0)
	v_mfma_f32_16x16x32_bf16 v[92:95], v[56:59], v[72:75], v[92:95]
	v_mfma_f32_16x16x32_bf16 v[88:91], v[64:67], v[72:75], v[88:91]
	v_mfma_f32_16x16x32_bf16 v[44:47], v[56:59], v[80:83], v[44:47]
	v_mfma_f32_16x16x32_bf16 v[40:43], v[64:67], v[80:83], v[40:43]
	v_mfma_f32_16x16x32_bf16 v[28:31], v[56:59], v[160:163], v[28:31]
	v_mfma_f32_16x16x32_bf16 v[24:27], v[64:67], v[160:163], v[24:27]
	v_mfma_f32_16x16x32_bf16 v[12:15], v[56:59], v[192:195], v[12:15]
	v_mfma_f32_16x16x32_bf16 v[8:11], v[64:67], v[192:195], v[8:11]
	v_mfma_f32_16x16x32_bf16 v[92:95], v[60:63], v[76:79], v[92:95]
	v_mfma_f32_16x16x32_bf16 v[88:91], v[68:71], v[76:79], v[88:91]
	v_mfma_f32_16x16x32_bf16 v[44:47], v[60:63], v[84:87], v[44:47]
	v_mfma_f32_16x16x32_bf16 v[40:43], v[68:71], v[84:87], v[40:43]
	v_mfma_f32_16x16x32_bf16 v[28:31], v[60:63], v[164:167], v[28:31]
	v_mfma_f32_16x16x32_bf16 v[24:27], v[68:71], v[164:167], v[24:27]
	v_mfma_f32_16x16x32_bf16 v[12:15], v[60:63], v[196:199], v[12:15]
	v_mfma_f32_16x16x32_bf16 v[8:11], v[68:71], v[196:199], v[8:11]
	s_barrier
	s_add_i32 m0, s40, 0x1c000
	s_add_u32 s2, s2, 0x40080
	s_addc_u32 s3, s3, 0
	global_load_lds_dwordx4 v182, s[2:3]
	s_add_i32 m0, s40, 0x1e000
	s_add_i32 s58, s58, 2
	global_load_lds_dwordx4 v186, s[2:3]
	s_waitcnt vmcnt(6)
	s_barrier
	v_mfma_f32_16x16x32_bf16 v[48:51], v[212:215], v[72:75], v[48:51]
	v_mfma_f32_16x16x32_bf16 v[64:67], v[216:219], v[76:79], v[48:51]
	v_mfma_f32_16x16x32_bf16 v[48:51], v[220:223], v[72:75], v[52:55]
	v_mfma_f32_16x16x32_bf16 v[36:39], v[212:215], v[80:83], v[36:39]
	v_mfma_f32_16x16x32_bf16 v[32:35], v[220:223], v[80:83], v[32:35]
	v_mfma_f32_16x16x32_bf16 v[20:23], v[212:215], v[160:163], v[20:23]
	v_mfma_f32_16x16x32_bf16 v[16:19], v[220:223], v[160:163], v[16:19]
	v_mfma_f32_16x16x32_bf16 v[4:7], v[212:215], v[192:195], v[4:7]
	v_mfma_f32_16x16x32_bf16 v[0:3], v[220:223], v[192:195], v[0:3]
	v_mfma_f32_16x16x32_bf16 v[56:59], v[236:239], v[76:79], v[48:51]
	v_mfma_f32_16x16x32_bf16 v[36:39], v[216:219], v[84:87], v[36:39]
	v_mfma_f32_16x16x32_bf16 v[32:35], v[236:239], v[84:87], v[32:35]
	v_mfma_f32_16x16x32_bf16 v[20:23], v[216:219], v[164:167], v[20:23]
	v_mfma_f32_16x16x32_bf16 v[16:19], v[236:239], v[164:167], v[16:19]
	v_mfma_f32_16x16x32_bf16 v[4:7], v[216:219], v[196:199], v[4:7]
	v_mfma_f32_16x16x32_bf16 v[0:3], v[236:239], v[196:199], v[0:3]
	s_add_u32 s8, s8, 0x100
	s_addc_u32 s9, s9, 0
	s_add_u32 s56, s56, 0x100
	s_addc_u32 s57, s57, 0
	s_cmp_gt_u32 s58, 13
	s_barrier
	s_cbranch_scc0 .LBB0_678
	s_lshl_b32 s1, s0, 8
	s_add_i32 s2, s1, s51
	s_lshl_b32 s1, s6, 8
	v_mov_b32_e32 v160, v205
	v_mov_b32_e32 v208, v204
	s_or_b32 s1, s1, s52
	s_nop 0
	v_lshl_add_u32 v192, v208, 3, s1
	s_add_i32 s1, s0, -16
	s_lshr_b32 s1, s1, 3
	s_add_i32 s1, s1, 1
	s_cmp_gt_i32 s0, 15
	s_cselect_b32 s3, s1, 0
	s_mul_i32 s96, s3, 0x1800
	s_lshl_b64 s[0:1], s[96:97], 2
	s_add_u32 s0, s45, s0
	v_ashrrev_i32_e32 v193, 31, v192
	s_addc_u32 s1, s46, s1
	v_lshlrev_b64 v[196:197], 2, v[192:193]
	s_lshl_b32 s96, s3, 10
	v_lshl_add_u64 v[48:49], s[0:1], 0, v[196:197]
	s_lshl_b64 s[0:1], s[96:97], 2
	s_add_u32 s0, s49, s0
	s_addc_u32 s1, s50, s1
	v_lshl_add_u64 v[52:53], s[0:1], 0, v[196:197]
	global_load_dwordx4 v[80:83], v[48:49], off offset:16
	global_load_dwordx4 v[84:87], v[48:49], off
	global_load_dwordx4 v[72:75], v[52:53], off offset:16
	global_load_dwordx4 v[76:79], v[52:53], off
	global_load_dwordx4 v[60:63], v[48:49], off offset:528
	global_load_dwordx4 v[68:71], v[48:49], off offset:512
	s_nop 0
	global_load_dwordx4 v[48:51], v[52:53], off offset:528
	s_nop 0
	global_load_dwordx4 v[52:55], v[52:53], off offset:512
	v_add_u32_e32 v194, s2, v160
	v_ashrrev_i32_e32 v195, 31, v194
	v_lshlrev_b64 v[160:161], 10, v[194:195]
	v_lshl_add_u64 v[198:199], v[160:161], 0, v[192:193]
	v_cndmask_b32_e64 v160, 0, 1, s[74:75]
	v_cmp_gt_i32_e64 s[0:1], s71, v194
	v_cmp_ne_u32_e64 s[6:7], 1, v160
	s_andn2_b64 vcc, exec, s[74:75]
	s_mov_b64 s[2:3], -1
	s_cbranch_vccnz .LBB0_681
	v_lshl_add_u64 v[160:161], v[198:199], 1, s[14:15]
	v_mov_b32_e32 v222, v160
	v_mov_b32_e32 v223, v161
	global_load_dwordx4 v[210:213], v[222:223], off
	global_load_dwordx4 v[214:217], v[222:223], off offset:256
	s_mov_b64 s[80:81], 0x8000
	v_lshl_add_u64 v[222:223], v[222:223], 0, s[80:81]
	global_load_dwordx4 v[218:221], v[222:223], off
	global_load_dwordx4 v[236:239], v[222:223], off offset:256
	s_mov_b64 s[2:3], 0
	s_waitcnt vmcnt(3)
	v_lshlrev_b32_e32 v164, 16, v210
	v_and_b32_e32 v165, 0xffff0000, v210
	v_lshlrev_b32_e32 v166, 16, v211
	v_and_b32_e32 v167, 0xffff0000, v211
	v_lshlrev_b32_e32 v160, 16, v212
	v_and_b32_e32 v161, 0xffff0000, v212
	v_lshlrev_b32_e32 v162, 16, v213
	v_and_b32_e32 v163, 0xffff0000, v213
	s_mov_b64 s[80:81], 0x8000
	v_lshl_add_u64 v[222:223], v[222:223], 0, s[80:81]
	global_load_dwordx4 v[210:213], v[222:223], off

.LBB0_879:
	s_ashr_i32 s39, s38, 31
	v_cmp_lt_i64_e32 vcc, s[12:13], v[178:179]
	s_lshl_b64 s[12:13], s[38:39], 19
	s_add_u32 s40, s49, s12
	s_addc_u32 s41, s50, s13
	s_lshl_b32 s84, s82, 18
	s_add_u32 s40, s40, s84
	s_addc_u32 s41, s41, 0
	s_and_b64 s[12:13], vcc, exec
	s_cselect_b32 s1, s41, s11
	s_cselect_b32 s9, s40, s10
	s_ashr_i32 s37, s36, 31
	s_lshl_b64 s[12:13], s[36:37], 19
	s_add_u32 s42, s51, s12
	s_addc_u32 s43, s52, s13
	s_and_b64 s[12:13], vcc, exec
	s_cselect_b32 s14, s43, s3
	s_cselect_b32 s15, s42, s2
	s_add_u32 s10, s10, 0x40080
	s_addc_u32 s11, s11, 0
	s_add_u32 s37, s2, 0x100
	s_addc_u32 s39, s3, 0
	s_mov_b32 s67, -2
	s_cmp_lg_u32 s83, 0
	s_cbranch_scc1 .Lup_half_peel
	s_add_u32 s2, s10, 0xfffc0080
	s_addc_u32 s3, s11, -1
	ds_read_b128 v[48:51], v237
	ds_read_b128 v[52:55], v237 offset:1024
	ds_read_b128 v[104:107], v237 offset:2048
	ds_read_b128 v[108:111], v237 offset:3072
	s_cmp_eq_u32 s67, 12
	s_cselect_b32 s13, s1, s3
	s_cselect_b32 s12, s9, s2
	s_cselect_b32 s3, s14, s39
	s_cselect_b32 s2, s15, s37
	s_add_i32 m0, s54, 0xc000
	ds_read_b128 v[112:115], v238
	ds_read_b128 v[116:119], v238 offset:1024
	ds_read_b128 v[120:123], v238 offset:2048
	ds_read_b128 v[156:159], v238 offset:3072
	ds_read_b128 v[160:163], v238 offset:4096
	ds_read_b128 v[164:167], v238 offset:5120
	ds_read_b128 v[190:193], v238 offset:6144
	global_load_lds_dwordx4 v186, s[10:11]
	s_add_i32 m0, s54, 0xe000
	ds_read_b128 v[194:197], v238 offset:7168
	global_load_lds_dwordx4 v188, s[10:11]
	s_waitcnt lgkmcnt(8)
	s_barrier
	s_waitcnt lgkmcnt(0)
	v_mfma_f32_16x16x32_bf16 v[152:155], v[48:51], v[112:115], 0
	v_mfma_f32_16x16x32_bf16 v[68:71], v[104:107], v[112:115], 0
	v_mfma_f32_16x16x32_bf16 v[148:151], v[48:51], v[120:123], 0
	v_mfma_f32_16x16x32_bf16 v[64:67], v[104:107], v[120:123], 0
	v_mfma_f32_16x16x32_bf16 v[136:139], v[48:51], v[160:163], 0
	v_mfma_f32_16x16x32_bf16 v[44:47], v[104:107], v[160:163], 0
	v_mfma_f32_16x16x32_bf16 v[128:131], v[48:51], v[190:193], 0
	v_mfma_f32_16x16x32_bf16 v[40:43], v[104:107], v[190:193], 0
	v_mfma_f32_16x16x32_bf16 v[152:155], v[52:55], v[116:119], v[152:155]
	v_mfma_f32_16x16x32_bf16 v[68:71], v[108:111], v[116:119], v[68:71]
	v_mfma_f32_16x16x32_bf16 v[148:151], v[52:55], v[156:159], v[148:151]
	v_mfma_f32_16x16x32_bf16 v[64:67], v[108:111], v[156:159], v[64:67]
	v_mfma_f32_16x16x32_bf16 v[136:139], v[52:55], v[164:167], v[136:139]
	v_mfma_f32_16x16x32_bf16 v[44:47], v[108:111], v[164:167], v[44:47]
	v_mfma_f32_16x16x32_bf16 v[128:131], v[52:55], v[194:197], v[128:131]
	v_mfma_f32_16x16x32_bf16 v[40:43], v[108:111], v[194:197], v[40:43]
	s_barrier
	s_add_u32 s98, s2, 0x80
	s_addc_u32 s99, s3, 0
	s_add_i32 m0, s53, 0x10000
	ds_read_b128 v[198:201], v237 offset:16384
	ds_read_b128 v[202:205], v237 offset:17408
	ds_read_b128 v[206:209], v237 offset:18432
	global_load_lds_dwordx4 v168, s[2:3]
	s_add_i32 m0, s53, 0x12000
	ds_read_b128 v[210:213], v237 offset:19456
	global_load_lds_dwordx4 v184, s[2:3]
	s_barrier
	s_waitcnt lgkmcnt(0)
	v_mfma_f32_16x16x32_bf16 v[144:147], v[198:201], v[112:115], 0
	v_mfma_f32_16x16x32_bf16 v[60:63], v[206:209], v[112:115], 0
	v_mfma_f32_16x16x32_bf16 v[56:59], v[206:209], v[120:123], 0
	v_mfma_f32_16x16x32_bf16 v[36:39], v[206:209], v[160:163], 0
	v_mfma_f32_16x16x32_bf16 v[32:35], v[206:209], v[190:193], 0
	v_mfma_f32_16x16x32_bf16 v[144:147], v[202:205], v[116:119], v[144:147]
	v_mfma_f32_16x16x32_bf16 v[60:63], v[210:213], v[116:119], v[60:63]
	v_mfma_f32_16x16x32_bf16 v[112:115], v[198:201], v[120:123], 0
	v_mfma_f32_16x16x32_bf16 v[56:59], v[210:213], v[156:159], v[56:59]
	v_mfma_f32_16x16x32_bf16 v[116:119], v[198:201], v[160:163], 0
	v_mfma_f32_16x16x32_bf16 v[36:39], v[210:213], v[164:167], v[36:39]
	v_mfma_f32_16x16x32_bf16 v[120:123], v[198:201], v[190:193], 0
	v_mfma_f32_16x16x32_bf16 v[32:35], v[210:213], v[194:197], v[32:35]
	v_mfma_f32_16x16x32_bf16 v[112:115], v[202:205], v[156:159], v[112:115]
	v_mfma_f32_16x16x32_bf16 v[116:119], v[202:205], v[164:167], v[116:119]
	v_mfma_f32_16x16x32_bf16 v[120:123], v[202:205], v[194:197], v[120:123]
	s_mov_b32 m0, s54
	s_add_u32 s100, s12, 0x80
	s_addc_u32 s101, s13, 0
	s_barrier
	ds_read_b128 v[124:127], v238 offset:16384
	ds_read_b128 v[132:135], v238 offset:17408
	ds_read_b128 v[140:143], v238 offset:18432
	ds_read_b128 v[156:159], v238 offset:19456
	ds_read_b128 v[160:163], v238 offset:20480
	ds_read_b128 v[164:167], v238 offset:21504
	ds_read_b128 v[190:193], v238 offset:22528
	global_load_lds_dwordx4 v180, s[12:13]
	s_mov_b32 m0, s55
	ds_read_b128 v[194:197], v238 offset:23552
	global_load_lds_dwordx4 v182, s[12:13]
	s_barrier
	s_waitcnt lgkmcnt(0)
	v_mfma_f32_16x16x32_bf16 v[100:103], v[48:51], v[124:127], 0
	v_mfma_f32_16x16x32_bf16 v[28:31], v[104:107], v[124:127], 0
	v_mfma_f32_16x16x32_bf16 v[96:99], v[48:51], v[140:143], 0
	v_mfma_f32_16x16x32_bf16 v[24:27], v[104:107], v[140:143], 0
	v_mfma_f32_16x16x32_bf16 v[84:87], v[48:51], v[160:163], 0
	v_mfma_f32_16x16x32_bf16 v[12:15], v[104:107], v[160:163], 0
	v_mfma_f32_16x16x32_bf16 v[8:11], v[104:107], v[190:193], 0
	v_mfma_f32_16x16x32_bf16 v[100:103], v[52:55], v[132:135], v[100:103]
	v_mfma_f32_16x16x32_bf16 v[28:31], v[108:111], v[132:135], v[28:31]
	v_mfma_f32_16x16x32_bf16 v[96:99], v[52:55], v[156:159], v[96:99]
	v_mfma_f32_16x16x32_bf16 v[24:27], v[108:111], v[156:159], v[24:27]
	v_mfma_f32_16x16x32_bf16 v[84:87], v[52:55], v[164:167], v[84:87]
	v_mfma_f32_16x16x32_bf16 v[12:15], v[108:111], v[164:167], v[12:15]
	v_mfma_f32_16x16x32_bf16 v[48:51], v[48:51], v[190:193], 0
	v_mfma_f32_16x16x32_bf16 v[8:11], v[108:111], v[194:197], v[8:11]
	v_mfma_f32_16x16x32_bf16 v[48:51], v[52:55], v[194:197], v[48:51]
	s_barrier
	s_add_i32 m0, s53, 0x14000
	s_add_u32 s68, s2, 0x40000
	s_addc_u32 s69, s3, 0
	global_load_lds_dwordx4 v168, s[68:69]
	s_add_i32 m0, s53, 0x16000
	s_add_u32 s12, s12, 0x40000
	s_addc_u32 s13, s13, 0
	global_load_lds_dwordx4 v184, s[68:69]
	s_waitcnt vmcnt(6)
	s_barrier
	v_mfma_f32_16x16x32_bf16 v[76:79], v[198:201], v[140:143], 0
	v_mfma_f32_16x16x32_bf16 v[20:23], v[206:209], v[124:127], 0
	v_mfma_f32_16x16x32_bf16 v[88:91], v[202:205], v[156:159], v[76:79]
	v_mfma_f32_16x16x32_bf16 v[16:19], v[206:209], v[140:143], 0
	v_mfma_f32_16x16x32_bf16 v[76:79], v[198:201], v[160:163], 0
	v_mfma_f32_16x16x32_bf16 v[4:7], v[206:209], v[160:163], 0
	v_mfma_f32_16x16x32_bf16 v[72:75], v[198:201], v[190:193], 0
	v_mfma_f32_16x16x32_bf16 v[0:3], v[206:209], v[190:193], 0
	v_mfma_f32_16x16x32_bf16 v[52:55], v[198:201], v[124:127], 0
	v_mfma_f32_16x16x32_bf16 v[20:23], v[210:213], v[132:135], v[20:23]
	v_mfma_f32_16x16x32_bf16 v[16:19], v[210:213], v[156:159], v[16:19]
	v_mfma_f32_16x16x32_bf16 v[80:83], v[202:205], v[164:167], v[76:79]
	v_mfma_f32_16x16x32_bf16 v[4:7], v[210:213], v[164:167], v[4:7]
	v_mfma_f32_16x16x32_bf16 v[72:75], v[202:205], v[194:197], v[72:75]
	v_mfma_f32_16x16x32_bf16 v[0:3], v[210:213], v[194:197], v[0:3]
	v_mfma_f32_16x16x32_bf16 v[52:55], v[202:205], v[132:135], v[52:55]
	s_barrier
	ds_read_b128 v[76:79], v237 offset:32768
	ds_read_b128 v[92:95], v237 offset:33792
	ds_read_b128 v[104:107], v237 offset:34816
	ds_read_b128 v[108:111], v237 offset:35840
	s_mov_b32 m0, s56
	ds_read_b128 v[124:127], v238 offset:32768
	ds_read_b128 v[132:135], v238 offset:33792
	ds_read_b128 v[156:159], v238 offset:34816
	ds_read_b128 v[160:163], v238 offset:35840
	ds_read_b128 v[164:167], v238 offset:36864
	ds_read_b128 v[190:193], v238 offset:37888
	ds_read_b128 v[194:197], v238 offset:38912
	global_load_lds_dwordx4 v180, s[12:13]
	s_mov_b32 m0, s57
	ds_read_b128 v[198:201], v238 offset:39936
	global_load_lds_dwordx4 v182, s[12:13]
	s_waitcnt lgkmcnt(8)
	s_barrier
	s_waitcnt lgkmcnt(0)
	v_mfma_f32_16x16x32_bf16 v[140:143], v[76:79], v[124:127], v[152:155]
	v_mfma_f32_16x16x32_bf16 v[152:155], v[92:95], v[132:135], v[140:143]
	v_mfma_f32_16x16x32_bf16 v[68:71], v[104:107], v[124:127], v[68:71]
	v_mfma_f32_16x16x32_bf16 v[140:143], v[76:79], v[156:159], v[148:151]
	v_mfma_f32_16x16x32_bf16 v[64:67], v[104:107], v[156:159], v[64:67]
	v_mfma_f32_16x16x32_bf16 v[136:139], v[76:79], v[164:167], v[136:139]
	v_mfma_f32_16x16x32_bf16 v[44:47], v[104:107], v[164:167], v[44:47]
	v_mfma_f32_16x16x32_bf16 v[128:131], v[76:79], v[194:197], v[128:131]
	v_mfma_f32_16x16x32_bf16 v[40:43], v[104:107], v[194:197], v[40:43]
	v_mfma_f32_16x16x32_bf16 v[68:71], v[108:111], v[132:135], v[68:71]
	v_mfma_f32_16x16x32_bf16 v[148:151], v[92:95], v[160:163], v[140:143]
	v_mfma_f32_16x16x32_bf16 v[64:67], v[108:111], v[160:163], v[64:67]
	v_mfma_f32_16x16x32_bf16 v[136:139], v[92:95], v[190:193], v[136:139]
	v_mfma_f32_16x16x32_bf16 v[44:47], v[108:111], v[190:193], v[44:47]
	v_mfma_f32_16x16x32_bf16 v[128:131], v[92:95], v[198:201], v[128:131]
	v_mfma_f32_16x16x32_bf16 v[40:43], v[108:111], v[198:201], v[40:43]
	s_barrier
	ds_read_b128 v[202:205], v237 offset:49152
	ds_read_b128 v[206:209], v237 offset:50176
	s_add_i32 m0, s53, 0x18000
	ds_read_b128 v[210:213], v237 offset:51200
	global_load_lds_dwordx4 v168, s[98:99]
	s_add_i32 m0, s53, 0x1a000
	ds_read_b128 v[214:217], v237 offset:52224
	global_load_lds_dwordx4 v184, s[98:99]
	s_barrier
	s_waitcnt lgkmcnt(0)
	v_mfma_f32_16x16x32_bf16 v[140:143], v[202:205], v[124:127], v[144:147]
	v_mfma_f32_16x16x32_bf16 v[112:115], v[202:205], v[156:159], v[112:115]
	v_mfma_f32_16x16x32_bf16 v[144:147], v[206:209], v[132:135], v[140:143]
	v_mfma_f32_16x16x32_bf16 v[60:63], v[210:213], v[124:127], v[60:63]
	v_mfma_f32_16x16x32_bf16 v[140:143], v[206:209], v[160:163], v[112:115]
	v_mfma_f32_16x16x32_bf16 v[112:115], v[202:205], v[164:167], v[116:119]
	v_mfma_f32_16x16x32_bf16 v[60:63], v[214:217], v[132:135], v[60:63]
	v_mfma_f32_16x16x32_bf16 v[56:59], v[210:213], v[156:159], v[56:59]
	v_mfma_f32_16x16x32_bf16 v[132:135], v[206:209], v[190:193], v[112:115]
	v_mfma_f32_16x16x32_bf16 v[36:39], v[210:213], v[164:167], v[36:39]
	v_mfma_f32_16x16x32_bf16 v[112:115], v[202:205], v[194:197], v[120:123]
	v_mfma_f32_16x16x32_bf16 v[32:35], v[210:213], v[194:197], v[32:35]
	v_mfma_f32_16x16x32_bf16 v[56:59], v[214:217], v[160:163], v[56:59]
	v_mfma_f32_16x16x32_bf16 v[36:39], v[214:217], v[190:193], v[36:39]
	v_mfma_f32_16x16x32_bf16 v[124:127], v[206:209], v[198:201], v[112:115]
	v_mfma_f32_16x16x32_bf16 v[32:35], v[214:217], v[198:201], v[32:35]
	s_mov_b32 m0, s62
	s_barrier
	ds_read_b128 v[112:115], v238 offset:49152
	ds_read_b128 v[116:119], v238 offset:50176
	ds_read_b128 v[120:123], v238 offset:51200
	ds_read_b128 v[156:159], v238 offset:52224
	ds_read_b128 v[160:163], v238 offset:53248
	ds_read_b128 v[164:167], v238 offset:54272
	ds_read_b128 v[190:193], v238 offset:55296
	global_load_lds_dwordx4 v180, s[100:101]
	s_mov_b32 m0, s63
	ds_read_b128 v[194:197], v238 offset:56320
	global_load_lds_dwordx4 v182, s[100:101]
	s_barrier
	s_waitcnt lgkmcnt(0)
	v_mfma_f32_16x16x32_bf16 v[100:103], v[76:79], v[112:115], v[100:103]
	v_mfma_f32_16x16x32_bf16 v[28:31], v[104:107], v[112:115], v[28:31]
	v_mfma_f32_16x16x32_bf16 v[96:99], v[76:79], v[120:123], v[96:99]
	v_mfma_f32_16x16x32_bf16 v[24:27], v[104:107], v[120:123], v[24:27]
	v_mfma_f32_16x16x32_bf16 v[84:87], v[76:79], v[160:163], v[84:87]
	v_mfma_f32_16x16x32_bf16 v[12:15], v[104:107], v[160:163], v[12:15]
	v_mfma_f32_16x16x32_bf16 v[48:51], v[76:79], v[190:193], v[48:51]
	v_mfma_f32_16x16x32_bf16 v[8:11], v[104:107], v[190:193], v[8:11]
	v_mfma_f32_16x16x32_bf16 v[100:103], v[92:95], v[116:119], v[100:103]
	v_mfma_f32_16x16x32_bf16 v[28:31], v[108:111], v[116:119], v[28:31]
	v_mfma_f32_16x16x32_bf16 v[96:99], v[92:95], v[156:159], v[96:99]
	v_mfma_f32_16x16x32_bf16 v[24:27], v[108:111], v[156:159], v[24:27]
	v_mfma_f32_16x16x32_bf16 v[84:87], v[92:95], v[164:167], v[84:87]
	v_mfma_f32_16x16x32_bf16 v[12:15], v[108:111], v[164:167], v[12:15]
	v_mfma_f32_16x16x32_bf16 v[76:79], v[92:95], v[194:197], v[48:51]
	v_mfma_f32_16x16x32_bf16 v[8:11], v[108:111], v[194:197], v[8:11]
	s_barrier
	s_add_i32 m0, s53, 0x1c000
	s_add_u32 s2, s2, 0x40080
	s_addc_u32 s3, s3, 0
	global_load_lds_dwordx4 v168, s[2:3]
	s_add_i32 m0, s53, 0x1e000
	s_add_i32 s67, s67, 2
	global_load_lds_dwordx4 v184, s[2:3]
	s_waitcnt vmcnt(6)
	s_barrier
	v_mfma_f32_16x16x32_bf16 v[48:51], v[202:205], v[112:115], v[52:55]
	v_mfma_f32_16x16x32_bf16 v[92:95], v[206:209], v[116:119], v[48:51]
	v_mfma_f32_16x16x32_bf16 v[48:51], v[202:205], v[120:123], v[88:91]
	v_mfma_f32_16x16x32_bf16 v[88:91], v[206:209], v[156:159], v[48:51]
	v_mfma_f32_16x16x32_bf16 v[48:51], v[202:205], v[160:163], v[80:83]
	v_mfma_f32_16x16x32_bf16 v[20:23], v[210:213], v[112:115], v[20:23]
	v_mfma_f32_16x16x32_bf16 v[16:19], v[210:213], v[120:123], v[16:19]
	v_mfma_f32_16x16x32_bf16 v[80:83], v[206:209], v[164:167], v[48:51]
	v_mfma_f32_16x16x32_bf16 v[4:7], v[210:213], v[160:163], v[4:7]
	v_mfma_f32_16x16x32_bf16 v[48:51], v[202:205], v[190:193], v[72:75]
	v_mfma_f32_16x16x32_bf16 v[0:3], v[210:213], v[190:193], v[0:3]
	v_mfma_f32_16x16x32_bf16 v[20:23], v[214:217], v[116:119], v[20:23]
	v_mfma_f32_16x16x32_bf16 v[16:19], v[214:217], v[156:159], v[16:19]
	v_mfma_f32_16x16x32_bf16 v[4:7], v[214:217], v[164:167], v[4:7]
	v_mfma_f32_16x16x32_bf16 v[72:75], v[206:209], v[194:197], v[48:51]
	v_mfma_f32_16x16x32_bf16 v[0:3], v[214:217], v[194:197], v[0:3]
	s_add_u32 s10, s10, 0x100
	s_addc_u32 s11, s11, 0
	s_add_u32 s37, s37, 0x100
	s_addc_u32 s39, s39, 0
	s_cmp_gt_u32 s67, 13
	s_barrier
.LBB0_880:
	s_add_u32 s2, s10, 0xfffc0080
	s_addc_u32 s3, s11, -1
	ds_read_b128 v[48:51], v237
	ds_read_b128 v[52:55], v237 offset:1024
	ds_read_b128 v[104:107], v237 offset:2048
	ds_read_b128 v[108:111], v237 offset:3072
	s_cmp_eq_u32 s67, 12
	s_cselect_b32 s13, s1, s3
	s_cselect_b32 s12, s9, s2
	s_cselect_b32 s3, s14, s39
	s_cselect_b32 s2, s15, s37
	s_add_i32 m0, s54, 0xc000
	ds_read_b128 v[112:115], v238
	ds_read_b128 v[116:119], v238 offset:1024
	ds_read_b128 v[120:123], v238 offset:2048
	ds_read_b128 v[156:159], v238 offset:3072
	ds_read_b128 v[160:163], v238 offset:4096
	ds_read_b128 v[164:167], v238 offset:5120
	ds_read_b128 v[190:193], v238 offset:6144
	global_load_lds_dwordx4 v186, s[10:11]
	s_add_i32 m0, s54, 0xe000
	ds_read_b128 v[194:197], v238 offset:7168
	global_load_lds_dwordx4 v188, s[10:11]
	s_waitcnt lgkmcnt(8)
	s_barrier
	s_waitcnt lgkmcnt(0)
	v_mfma_f32_16x16x32_bf16 v[152:155], v[48:51], v[112:115], v[152:155]
	v_mfma_f32_16x16x32_bf16 v[68:71], v[104:107], v[112:115], v[68:71]
	v_mfma_f32_16x16x32_bf16 v[148:151], v[48:51], v[120:123], v[148:151]
	v_mfma_f32_16x16x32_bf16 v[64:67], v[104:107], v[120:123], v[64:67]
	v_mfma_f32_16x16x32_bf16 v[136:139], v[48:51], v[160:163], v[136:139]
	v_mfma_f32_16x16x32_bf16 v[44:47], v[104:107], v[160:163], v[44:47]
	v_mfma_f32_16x16x32_bf16 v[128:131], v[48:51], v[190:193], v[128:131]
	v_mfma_f32_16x16x32_bf16 v[40:43], v[104:107], v[190:193], v[40:43]
	v_mfma_f32_16x16x32_bf16 v[152:155], v[52:55], v[116:119], v[152:155]
	v_mfma_f32_16x16x32_bf16 v[68:71], v[108:111], v[116:119], v[68:71]
	v_mfma_f32_16x16x32_bf16 v[148:151], v[52:55], v[156:159], v[148:151]
	v_mfma_f32_16x16x32_bf16 v[64:67], v[108:111], v[156:159], v[64:67]
	v_mfma_f32_16x16x32_bf16 v[136:139], v[52:55], v[164:167], v[136:139]
	v_mfma_f32_16x16x32_bf16 v[44:47], v[108:111], v[164:167], v[44:47]
	v_mfma_f32_16x16x32_bf16 v[128:131], v[52:55], v[194:197], v[128:131]
	v_mfma_f32_16x16x32_bf16 v[40:43], v[108:111], v[194:197], v[40:43]
	s_barrier
	s_add_u32 s98, s2, 0x80
	s_addc_u32 s99, s3, 0
	s_add_i32 m0, s53, 0x10000
	ds_read_b128 v[198:201], v237 offset:16384
	ds_read_b128 v[202:205], v237 offset:17408
	ds_read_b128 v[206:209], v237 offset:18432
	global_load_lds_dwordx4 v168, s[2:3]
	s_add_i32 m0, s53, 0x12000
	ds_read_b128 v[210:213], v237 offset:19456
	global_load_lds_dwordx4 v184, s[2:3]
	s_barrier
	s_waitcnt lgkmcnt(0)
	v_mfma_f32_16x16x32_bf16 v[144:147], v[198:201], v[112:115], v[144:147]
	v_mfma_f32_16x16x32_bf16 v[60:63], v[206:209], v[112:115], v[60:63]
	v_mfma_f32_16x16x32_bf16 v[56:59], v[206:209], v[120:123], v[56:59]
	v_mfma_f32_16x16x32_bf16 v[36:39], v[206:209], v[160:163], v[36:39]
	v_mfma_f32_16x16x32_bf16 v[32:35], v[206:209], v[190:193], v[32:35]
	v_mfma_f32_16x16x32_bf16 v[144:147], v[202:205], v[116:119], v[144:147]
	v_mfma_f32_16x16x32_bf16 v[60:63], v[210:213], v[116:119], v[60:63]
	v_mfma_f32_16x16x32_bf16 v[112:115], v[198:201], v[120:123], v[140:143]
	v_mfma_f32_16x16x32_bf16 v[56:59], v[210:213], v[156:159], v[56:59]
	v_mfma_f32_16x16x32_bf16 v[116:119], v[198:201], v[160:163], v[132:135]
	v_mfma_f32_16x16x32_bf16 v[36:39], v[210:213], v[164:167], v[36:39]
	v_mfma_f32_16x16x32_bf16 v[120:123], v[198:201], v[190:193], v[124:127]
	v_mfma_f32_16x16x32_bf16 v[32:35], v[210:213], v[194:197], v[32:35]
	v_mfma_f32_16x16x32_bf16 v[112:115], v[202:205], v[156:159], v[112:115]
	v_mfma_f32_16x16x32_bf16 v[116:119], v[202:205], v[164:167], v[116:119]
	v_mfma_f32_16x16x32_bf16 v[120:123], v[202:205], v[194:197], v[120:123]
	s_mov_b32 m0, s54
	s_add_u32 s100, s12, 0x80
	s_addc_u32 s101, s13, 0
	s_barrier
	ds_read_b128 v[124:127], v238 offset:16384
	ds_read_b128 v[132:135], v238 offset:17408
	ds_read_b128 v[140:143], v238 offset:18432
	ds_read_b128 v[156:159], v238 offset:19456
	ds_read_b128 v[160:163], v238 offset:20480
	ds_read_b128 v[164:167], v238 offset:21504
	ds_read_b128 v[190:193], v238 offset:22528
	global_load_lds_dwordx4 v180, s[12:13]
	s_mov_b32 m0, s55
	ds_read_b128 v[194:197], v238 offset:23552
	global_load_lds_dwordx4 v182, s[12:13]
	s_barrier
	s_waitcnt lgkmcnt(0)
	v_mfma_f32_16x16x32_bf16 v[100:103], v[48:51], v[124:127], v[100:103]
	v_mfma_f32_16x16x32_bf16 v[28:31], v[104:107], v[124:127], v[28:31]
	v_mfma_f32_16x16x32_bf16 v[96:99], v[48:51], v[140:143], v[96:99]
	v_mfma_f32_16x16x32_bf16 v[24:27], v[104:107], v[140:143], v[24:27]
	v_mfma_f32_16x16x32_bf16 v[84:87], v[48:51], v[160:163], v[84:87]
	v_mfma_f32_16x16x32_bf16 v[12:15], v[104:107], v[160:163], v[12:15]
	v_mfma_f32_16x16x32_bf16 v[8:11], v[104:107], v[190:193], v[8:11]
	v_mfma_f32_16x16x32_bf16 v[100:103], v[52:55], v[132:135], v[100:103]
	v_mfma_f32_16x16x32_bf16 v[28:31], v[108:111], v[132:135], v[28:31]
	v_mfma_f32_16x16x32_bf16 v[96:99], v[52:55], v[156:159], v[96:99]
	v_mfma_f32_16x16x32_bf16 v[24:27], v[108:111], v[156:159], v[24:27]
	v_mfma_f32_16x16x32_bf16 v[84:87], v[52:55], v[164:167], v[84:87]
	v_mfma_f32_16x16x32_bf16 v[12:15], v[108:111], v[164:167], v[12:15]
	v_mfma_f32_16x16x32_bf16 v[48:51], v[48:51], v[190:193], v[76:79]
	v_mfma_f32_16x16x32_bf16 v[8:11], v[108:111], v[194:197], v[8:11]
	v_mfma_f32_16x16x32_bf16 v[48:51], v[52:55], v[194:197], v[48:51]
	s_barrier
	s_add_i32 m0, s53, 0x14000
	s_add_u32 s68, s2, 0x40000
	s_addc_u32 s69, s3, 0
	global_load_lds_dwordx4 v168, s[68:69]
	s_add_i32 m0, s53, 0x16000
	s_add_u32 s12, s12, 0x40000
	s_addc_u32 s13, s13, 0
	global_load_lds_dwordx4 v184, s[68:69]
	s_waitcnt vmcnt(6)
	s_barrier
	v_mfma_f32_16x16x32_bf16 v[76:79], v[198:201], v[140:143], v[88:91]
	v_mfma_f32_16x16x32_bf16 v[20:23], v[206:209], v[124:127], v[20:23]
	v_mfma_f32_16x16x32_bf16 v[88:91], v[202:205], v[156:159], v[76:79]
	v_mfma_f32_16x16x32_bf16 v[16:19], v[206:209], v[140:143], v[16:19]
	v_mfma_f32_16x16x32_bf16 v[76:79], v[198:201], v[160:163], v[80:83]
	v_mfma_f32_16x16x32_bf16 v[4:7], v[206:209], v[160:163], v[4:7]
	v_mfma_f32_16x16x32_bf16 v[72:75], v[198:201], v[190:193], v[72:75]
	v_mfma_f32_16x16x32_bf16 v[0:3], v[206:209], v[190:193], v[0:3]
	v_mfma_f32_16x16x32_bf16 v[52:55], v[198:201], v[124:127], v[92:95]
	v_mfma_f32_16x16x32_bf16 v[20:23], v[210:213], v[132:135], v[20:23]
	v_mfma_f32_16x16x32_bf16 v[16:19], v[210:213], v[156:159], v[16:19]
	v_mfma_f32_16x16x32_bf16 v[80:83], v[202:205], v[164:167], v[76:79]
	v_mfma_f32_16x16x32_bf16 v[4:7], v[210:213], v[164:167], v[4:7]
	v_mfma_f32_16x16x32_bf16 v[72:75], v[202:205], v[194:197], v[72:75]
	v_mfma_f32_16x16x32_bf16 v[0:3], v[210:213], v[194:197], v[0:3]
	v_mfma_f32_16x16x32_bf16 v[52:55], v[202:205], v[132:135], v[52:55]
	s_barrier
	ds_read_b128 v[76:79], v237 offset:32768
	ds_read_b128 v[92:95], v237 offset:33792
	ds_read_b128 v[104:107], v237 offset:34816
	ds_read_b128 v[108:111], v237 offset:35840
	s_mov_b32 m0, s56
	ds_read_b128 v[124:127], v238 offset:32768
	ds_read_b128 v[132:135], v238 offset:33792
	ds_read_b128 v[156:159], v238 offset:34816
	ds_read_b128 v[160:163], v238 offset:35840
	ds_read_b128 v[164:167], v238 offset:36864
	ds_read_b128 v[190:193], v238 offset:37888
	ds_read_b128 v[194:197], v238 offset:38912
	global_load_lds_dwordx4 v180, s[12:13]
	s_mov_b32 m0, s57
	ds_read_b128 v[198:201], v238 offset:39936
	global_load_lds_dwordx4 v182, s[12:13]
	s_waitcnt lgkmcnt(8)
	s_barrier
	s_waitcnt lgkmcnt(0)
	v_mfma_f32_16x16x32_bf16 v[140:143], v[76:79], v[124:127], v[152:155]
	v_mfma_f32_16x16x32_bf16 v[152:155], v[92:95], v[132:135], v[140:143]
	v_mfma_f32_16x16x32_bf16 v[68:71], v[104:107], v[124:127], v[68:71]
	v_mfma_f32_16x16x32_bf16 v[140:143], v[76:79], v[156:159], v[148:151]
	v_mfma_f32_16x16x32_bf16 v[64:67], v[104:107], v[156:159], v[64:67]
	v_mfma_f32_16x16x32_bf16 v[136:139], v[76:79], v[164:167], v[136:139]
	v_mfma_f32_16x16x32_bf16 v[44:47], v[104:107], v[164:167], v[44:47]
	v_mfma_f32_16x16x32_bf16 v[128:131], v[76:79], v[194:197], v[128:131]
	v_mfma_f32_16x16x32_bf16 v[40:43], v[104:107], v[194:197], v[40:43]
	v_mfma_f32_16x16x32_bf16 v[68:71], v[108:111], v[132:135], v[68:71]
	v_mfma_f32_16x16x32_bf16 v[148:151], v[92:95], v[160:163], v[140:143]
	v_mfma_f32_16x16x32_bf16 v[64:67], v[108:111], v[160:163], v[64:67]
	v_mfma_f32_16x16x32_bf16 v[136:139], v[92:95], v[190:193], v[136:139]
	v_mfma_f32_16x16x32_bf16 v[44:47], v[108:111], v[190:193], v[44:47]
	v_mfma_f32_16x16x32_bf16 v[128:131], v[92:95], v[198:201], v[128:131]
	v_mfma_f32_16x16x32_bf16 v[40:43], v[108:111], v[198:201], v[40:43]
	s_barrier
	ds_read_b128 v[202:205], v237 offset:49152
	ds_read_b128 v[206:209], v237 offset:50176
	s_add_i32 m0, s53, 0x18000
	ds_read_b128 v[210:213], v237 offset:51200
	global_load_lds_dwordx4 v168, s[98:99]
	s_add_i32 m0, s53, 0x1a000
	ds_read_b128 v[214:217], v237 offset:52224
	global_load_lds_dwordx4 v184, s[98:99]
	s_barrier
	s_waitcnt lgkmcnt(0)
	v_mfma_f32_16x16x32_bf16 v[140:143], v[202:205], v[124:127], v[144:147]
	v_mfma_f32_16x16x32_bf16 v[112:115], v[202:205], v[156:159], v[112:115]
	v_mfma_f32_16x16x32_bf16 v[144:147], v[206:209], v[132:135], v[140:143]
	v_mfma_f32_16x16x32_bf16 v[60:63], v[210:213], v[124:127], v[60:63]
	v_mfma_f32_16x16x32_bf16 v[140:143], v[206:209], v[160:163], v[112:115]
	v_mfma_f32_16x16x32_bf16 v[112:115], v[202:205], v[164:167], v[116:119]
	v_mfma_f32_16x16x32_bf16 v[60:63], v[214:217], v[132:135], v[60:63]
	v_mfma_f32_16x16x32_bf16 v[56:59], v[210:213], v[156:159], v[56:59]
	v_mfma_f32_16x16x32_bf16 v[132:135], v[206:209], v[190:193], v[112:115]
	v_mfma_f32_16x16x32_bf16 v[36:39], v[210:213], v[164:167], v[36:39]
	v_mfma_f32_16x16x32_bf16 v[112:115], v[202:205], v[194:197], v[120:123]
	v_mfma_f32_16x16x32_bf16 v[32:35], v[210:213], v[194:197], v[32:35]
	v_mfma_f32_16x16x32_bf16 v[56:59], v[214:217], v[160:163], v[56:59]
	v_mfma_f32_16x16x32_bf16 v[36:39], v[214:217], v[190:193], v[36:39]
	v_mfma_f32_16x16x32_bf16 v[124:127], v[206:209], v[198:201], v[112:115]
	v_mfma_f32_16x16x32_bf16 v[32:35], v[214:217], v[198:201], v[32:35]
	s_mov_b32 m0, s62
	s_barrier
	ds_read_b128 v[112:115], v238 offset:49152
	ds_read_b128 v[116:119], v238 offset:50176
	ds_read_b128 v[120:123], v238 offset:51200
	ds_read_b128 v[156:159], v238 offset:52224
	ds_read_b128 v[160:163], v238 offset:53248
	ds_read_b128 v[164:167], v238 offset:54272
	ds_read_b128 v[190:193], v238 offset:55296
	global_load_lds_dwordx4 v180, s[100:101]
	s_mov_b32 m0, s63
	ds_read_b128 v[194:197], v238 offset:56320
	global_load_lds_dwordx4 v182, s[100:101]
	s_barrier
	s_waitcnt lgkmcnt(0)
	v_mfma_f32_16x16x32_bf16 v[100:103], v[76:79], v[112:115], v[100:103]
	v_mfma_f32_16x16x32_bf16 v[28:31], v[104:107], v[112:115], v[28:31]
	v_mfma_f32_16x16x32_bf16 v[96:99], v[76:79], v[120:123], v[96:99]
	v_mfma_f32_16x16x32_bf16 v[24:27], v[104:107], v[120:123], v[24:27]
	v_mfma_f32_16x16x32_bf16 v[84:87], v[76:79], v[160:163], v[84:87]
	v_mfma_f32_16x16x32_bf16 v[12:15], v[104:107], v[160:163], v[12:15]
	v_mfma_f32_16x16x32_bf16 v[48:51], v[76:79], v[190:193], v[48:51]
	v_mfma_f32_16x16x32_bf16 v[8:11], v[104:107], v[190:193], v[8:11]
	v_mfma_f32_16x16x32_bf16 v[100:103], v[92:95], v[116:119], v[100:103]
	v_mfma_f32_16x16x32_bf16 v[28:31], v[108:111], v[116:119], v[28:31]
	v_mfma_f32_16x16x32_bf16 v[96:99], v[92:95], v[156:159], v[96:99]
	v_mfma_f32_16x16x32_bf16 v[24:27], v[108:111], v[156:159], v[24:27]
	v_mfma_f32_16x16x32_bf16 v[84:87], v[92:95], v[164:167], v[84:87]
	v_mfma_f32_16x16x32_bf16 v[12:15], v[108:111], v[164:167], v[12:15]
	v_mfma_f32_16x16x32_bf16 v[76:79], v[92:95], v[194:197], v[48:51]
	v_mfma_f32_16x16x32_bf16 v[8:11], v[108:111], v[194:197], v[8:11]
	s_barrier
	s_add_i32 m0, s53, 0x1c000
	s_add_u32 s2, s2, 0x40080
	s_addc_u32 s3, s3, 0
	global_load_lds_dwordx4 v168, s[2:3]
	s_add_i32 m0, s53, 0x1e000
	s_add_i32 s67, s67, 2
	global_load_lds_dwordx4 v184, s[2:3]
	s_waitcnt vmcnt(6)
	s_barrier
	v_mfma_f32_16x16x32_bf16 v[48:51], v[202:205], v[112:115], v[52:55]
	v_mfma_f32_16x16x32_bf16 v[92:95], v[206:209], v[116:119], v[48:51]
	v_mfma_f32_16x16x32_bf16 v[48:51], v[202:205], v[120:123], v[88:91]
	v_mfma_f32_16x16x32_bf16 v[88:91], v[206:209], v[156:159], v[48:51]
	v_mfma_f32_16x16x32_bf16 v[48:51], v[202:205], v[160:163], v[80:83]
	v_mfma_f32_16x16x32_bf16 v[20:23], v[210:213], v[112:115], v[20:23]
	v_mfma_f32_16x16x32_bf16 v[16:19], v[210:213], v[120:123], v[16:19]
	v_mfma_f32_16x16x32_bf16 v[80:83], v[206:209], v[164:167], v[48:51]
	v_mfma_f32_16x16x32_bf16 v[4:7], v[210:213], v[160:163], v[4:7]
	v_mfma_f32_16x16x32_bf16 v[48:51], v[202:205], v[190:193], v[72:75]
	v_mfma_f32_16x16x32_bf16 v[0:3], v[210:213], v[190:193], v[0:3]
	v_mfma_f32_16x16x32_bf16 v[20:23], v[214:217], v[116:119], v[20:23]
	v_mfma_f32_16x16x32_bf16 v[16:19], v[214:217], v[156:159], v[16:19]
	v_mfma_f32_16x16x32_bf16 v[4:7], v[214:217], v[164:167], v[4:7]
	v_mfma_f32_16x16x32_bf16 v[72:75], v[206:209], v[194:197], v[48:51]
	v_mfma_f32_16x16x32_bf16 v[0:3], v[214:217], v[194:197], v[0:3]
	s_add_u32 s10, s10, 0x100
	s_addc_u32 s11, s11, 0
	s_add_u32 s37, s37, 0x100
	s_addc_u32 s39, s39, 0
	s_cmp_gt_u32 s67, 13
	s_barrier
	s_cbranch_scc0 .LBB0_880

.Lup_half_peel:
	s_add_u32 s2, s10, 0xfffc0080
	s_addc_u32 s3, s11, -1
	ds_read_b128 v[48:51], v237
	ds_read_b128 v[52:55], v237 offset:1024
	ds_read_b128 v[104:107], v237 offset:2048
	ds_read_b128 v[108:111], v237 offset:3072
	s_cmp_eq_u32 s67, 12
	s_cselect_b32 s13, s1, s3
	s_cselect_b32 s12, s9, s2
	s_cselect_b32 s3, s14, s39
	s_cselect_b32 s2, s15, s37
	s_add_i32 m0, s54, 0xc000
	ds_read_b128 v[112:115], v238
	ds_read_b128 v[116:119], v238 offset:1024
	ds_read_b128 v[120:123], v238 offset:2048
	ds_read_b128 v[156:159], v238 offset:3072
	ds_read_b128 v[160:163], v238 offset:4096
	ds_read_b128 v[164:167], v238 offset:5120
	ds_read_b128 v[190:193], v238 offset:6144
	global_load_lds_dwordx4 v186, s[10:11]
	s_add_i32 m0, s54, 0xe000
	ds_read_b128 v[194:197], v238 offset:7168
	global_load_lds_dwordx4 v188, s[10:11]
	s_waitcnt lgkmcnt(8)
	s_barrier
	s_waitcnt lgkmcnt(0)
	v_mfma_f32_16x16x32_bf16 v[152:155], v[48:51], v[112:115], 0
	v_mfma_f32_16x16x32_bf16 v[68:71], v[104:107], v[112:115], 0
	v_mfma_f32_16x16x32_bf16 v[148:151], v[48:51], v[120:123], 0
	v_mfma_f32_16x16x32_bf16 v[64:67], v[104:107], v[120:123], 0
	v_mfma_f32_16x16x32_bf16 v[136:139], v[48:51], v[160:163], 0
	v_mfma_f32_16x16x32_bf16 v[44:47], v[104:107], v[160:163], 0
	v_mfma_f32_16x16x32_bf16 v[128:131], v[48:51], v[190:193], 0
	v_mfma_f32_16x16x32_bf16 v[40:43], v[104:107], v[190:193], 0
	v_mfma_f32_16x16x32_bf16 v[152:155], v[52:55], v[116:119], v[152:155]
	v_mfma_f32_16x16x32_bf16 v[68:71], v[108:111], v[116:119], v[68:71]
	v_mfma_f32_16x16x32_bf16 v[148:151], v[52:55], v[156:159], v[148:151]
	v_mfma_f32_16x16x32_bf16 v[64:67], v[108:111], v[156:159], v[64:67]
	v_mfma_f32_16x16x32_bf16 v[136:139], v[52:55], v[164:167], v[136:139]
	v_mfma_f32_16x16x32_bf16 v[44:47], v[108:111], v[164:167], v[44:47]
	v_mfma_f32_16x16x32_bf16 v[128:131], v[52:55], v[194:197], v[128:131]
	v_mfma_f32_16x16x32_bf16 v[40:43], v[108:111], v[194:197], v[40:43]
	s_barrier
	s_add_u32 s98, s2, 0x80
	s_addc_u32 s99, s3, 0
	s_add_i32 m0, s53, 0x10000
	ds_read_b128 v[198:201], v237 offset:16384
	ds_read_b128 v[202:205], v237 offset:17408
	ds_read_b128 v[206:209], v237 offset:18432
	global_load_lds_dwordx4 v168, s[2:3]
	s_add_i32 m0, s53, 0x12000
	ds_read_b128 v[210:213], v237 offset:19456
	global_load_lds_dwordx4 v184, s[2:3]
	s_barrier
	s_waitcnt lgkmcnt(0)
	v_mfma_f32_16x16x32_bf16 v[144:147], v[198:201], v[112:115], 0
	v_mfma_f32_16x16x32_bf16 v[60:63], v[206:209], v[112:115], 0
	v_mfma_f32_16x16x32_bf16 v[56:59], v[206:209], v[120:123], 0
	v_mfma_f32_16x16x32_bf16 v[36:39], v[206:209], v[160:163], 0
	v_mfma_f32_16x16x32_bf16 v[32:35], v[206:209], v[190:193], 0
	v_mfma_f32_16x16x32_bf16 v[144:147], v[202:205], v[116:119], v[144:147]
	v_mfma_f32_16x16x32_bf16 v[60:63], v[210:213], v[116:119], v[60:63]
	v_mfma_f32_16x16x32_bf16 v[112:115], v[198:201], v[120:123], 0
	v_mfma_f32_16x16x32_bf16 v[56:59], v[210:213], v[156:159], v[56:59]
	v_mfma_f32_16x16x32_bf16 v[116:119], v[198:201], v[160:163], 0
	v_mfma_f32_16x16x32_bf16 v[36:39], v[210:213], v[164:167], v[36:39]
	v_mfma_f32_16x16x32_bf16 v[120:123], v[198:201], v[190:193], 0
	v_mfma_f32_16x16x32_bf16 v[32:35], v[210:213], v[194:197], v[32:35]
	v_mfma_f32_16x16x32_bf16 v[112:115], v[202:205], v[156:159], v[112:115]
	v_mfma_f32_16x16x32_bf16 v[116:119], v[202:205], v[164:167], v[116:119]
	v_mfma_f32_16x16x32_bf16 v[120:123], v[202:205], v[194:197], v[120:123]
	s_mov_b32 m0, s54
	s_add_u32 s100, s12, 0x80
	s_addc_u32 s101, s13, 0
	s_barrier
	ds_read_b128 v[124:127], v238 offset:16384
	ds_read_b128 v[132:135], v238 offset:17408
	ds_read_b128 v[140:143], v238 offset:18432
	ds_read_b128 v[156:159], v238 offset:19456
	ds_read_b128 v[160:163], v238 offset:20480
	ds_read_b128 v[164:167], v238 offset:21504
	ds_read_b128 v[190:193], v238 offset:22528
	global_load_lds_dwordx4 v180, s[12:13]
	s_mov_b32 m0, s55
	ds_read_b128 v[194:197], v238 offset:23552
	global_load_lds_dwordx4 v182, s[12:13]
	s_barrier
	s_waitcnt lgkmcnt(0)
	s_barrier
	s_add_i32 m0, s53, 0x14000
	s_add_u32 s68, s2, 0x40000
	s_addc_u32 s69, s3, 0
	global_load_lds_dwordx4 v168, s[68:69]
	s_add_i32 m0, s53, 0x16000
	s_add_u32 s12, s12, 0x40000
	s_addc_u32 s13, s13, 0
	global_load_lds_dwordx4 v184, s[68:69]
	s_waitcnt vmcnt(6)
	s_barrier
	s_barrier
	ds_read_b128 v[76:79], v237 offset:32768
	ds_read_b128 v[92:95], v237 offset:33792
	ds_read_b128 v[104:107], v237 offset:34816
	ds_read_b128 v[108:111], v237 offset:35840
	s_mov_b32 m0, s56
	ds_read_b128 v[124:127], v238 offset:32768
	ds_read_b128 v[132:135], v238 offset:33792
	ds_read_b128 v[156:159], v238 offset:34816
	ds_read_b128 v[160:163], v238 offset:35840
	ds_read_b128 v[164:167], v238 offset:36864
	ds_read_b128 v[190:193], v238 offset:37888
	ds_read_b128 v[194:197], v238 offset:38912
	global_load_lds_dwordx4 v180, s[12:13]
	s_mov_b32 m0, s57
	ds_read_b128 v[198:201], v238 offset:39936
	global_load_lds_dwordx4 v182, s[12:13]
	s_waitcnt lgkmcnt(8)
	s_barrier
	s_waitcnt lgkmcnt(0)
	v_mfma_f32_16x16x32_bf16 v[140:143], v[76:79], v[124:127], v[152:155]
	v_mfma_f32_16x16x32_bf16 v[152:155], v[92:95], v[132:135], v[140:143]
	v_mfma_f32_16x16x32_bf16 v[68:71], v[104:107], v[124:127], v[68:71]
	v_mfma_f32_16x16x32_bf16 v[140:143], v[76:79], v[156:159], v[148:151]
	v_mfma_f32_16x16x32_bf16 v[64:67], v[104:107], v[156:159], v[64:67]
	v_mfma_f32_16x16x32_bf16 v[136:139], v[76:79], v[164:167], v[136:139]
	v_mfma_f32_16x16x32_bf16 v[44:47], v[104:107], v[164:167], v[44:47]
	v_mfma_f32_16x16x32_bf16 v[128:131], v[76:79], v[194:197], v[128:131]
	v_mfma_f32_16x16x32_bf16 v[40:43], v[104:107], v[194:197], v[40:43]
	v_mfma_f32_16x16x32_bf16 v[68:71], v[108:111], v[132:135], v[68:71]
	v_mfma_f32_16x16x32_bf16 v[148:151], v[92:95], v[160:163], v[140:143]
	v_mfma_f32_16x16x32_bf16 v[64:67], v[108:111], v[160:163], v[64:67]
	v_mfma_f32_16x16x32_bf16 v[136:139], v[92:95], v[190:193], v[136:139]
	v_mfma_f32_16x16x32_bf16 v[44:47], v[108:111], v[190:193], v[44:47]
	v_mfma_f32_16x16x32_bf16 v[128:131], v[92:95], v[198:201], v[128:131]
	v_mfma_f32_16x16x32_bf16 v[40:43], v[108:111], v[198:201], v[40:43]
	s_barrier
	ds_read_b128 v[202:205], v237 offset:49152
	ds_read_b128 v[206:209], v237 offset:50176
	s_add_i32 m0, s53, 0x18000
	ds_read_b128 v[210:213], v237 offset:51200
	global_load_lds_dwordx4 v168, s[98:99]
	s_add_i32 m0, s53, 0x1a000
	ds_read_b128 v[214:217], v237 offset:52224
	global_load_lds_dwordx4 v184, s[98:99]
	s_barrier
	s_waitcnt lgkmcnt(0)
	v_mfma_f32_16x16x32_bf16 v[140:143], v[202:205], v[124:127], v[144:147]
	v_mfma_f32_16x16x32_bf16 v[112:115], v[202:205], v[156:159], v[112:115]
	v_mfma_f32_16x16x32_bf16 v[144:147], v[206:209], v[132:135], v[140:143]
	v_mfma_f32_16x16x32_bf16 v[60:63], v[210:213], v[124:127], v[60:63]
	v_mfma_f32_16x16x32_bf16 v[140:143], v[206:209], v[160:163], v[112:115]
	v_mfma_f32_16x16x32_bf16 v[112:115], v[202:205], v[164:167], v[116:119]
	v_mfma_f32_16x16x32_bf16 v[60:63], v[214:217], v[132:135], v[60:63]
	v_mfma_f32_16x16x32_bf16 v[56:59], v[210:213], v[156:159], v[56:59]
	v_mfma_f32_16x16x32_bf16 v[132:135], v[206:209], v[190:193], v[112:115]
	v_mfma_f32_16x16x32_bf16 v[36:39], v[210:213], v[164:167], v[36:39]
	v_mfma_f32_16x16x32_bf16 v[112:115], v[202:205], v[194:197], v[120:123]
	v_mfma_f32_16x16x32_bf16 v[32:35], v[210:213], v[194:197], v[32:35]
	v_mfma_f32_16x16x32_bf16 v[56:59], v[214:217], v[160:163], v[56:59]
	v_mfma_f32_16x16x32_bf16 v[36:39], v[214:217], v[190:193], v[36:39]
	v_mfma_f32_16x16x32_bf16 v[124:127], v[206:209], v[198:201], v[112:115]
	v_mfma_f32_16x16x32_bf16 v[32:35], v[214:217], v[198:201], v[32:35]
	s_mov_b32 m0, s62
	s_barrier
	ds_read_b128 v[112:115], v238 offset:49152
	ds_read_b128 v[116:119], v238 offset:50176
	ds_read_b128 v[120:123], v238 offset:51200
	ds_read_b128 v[156:159], v238 offset:52224
	ds_read_b128 v[160:163], v238 offset:53248
	ds_read_b128 v[164:167], v238 offset:54272
	ds_read_b128 v[190:193], v238 offset:55296
	global_load_lds_dwordx4 v180, s[100:101]
	s_mov_b32 m0, s63
	ds_read_b128 v[194:197], v238 offset:56320
	global_load_lds_dwordx4 v182, s[100:101]
	s_barrier
	s_waitcnt lgkmcnt(0)
	s_barrier
	s_add_i32 m0, s53, 0x1c000
	s_add_u32 s2, s2, 0x40080
	s_addc_u32 s3, s3, 0
	global_load_lds_dwordx4 v168, s[2:3]
	s_add_i32 m0, s53, 0x1e000
	s_add_i32 s67, s67, 2
	global_load_lds_dwordx4 v184, s[2:3]
	s_waitcnt vmcnt(6)
	s_barrier
	s_add_u32 s10, s10, 0x100
	s_addc_u32 s11, s11, 0
	s_add_u32 s37, s37, 0x100
	s_addc_u32 s39, s39, 0
	s_cmp_gt_u32 s67, 13
	s_barrier
.Lup_half_loop:
	s_add_u32 s2, s10, 0xfffc0080
	s_addc_u32 s3, s11, -1
	ds_read_b128 v[48:51], v237
	ds_read_b128 v[52:55], v237 offset:1024
	ds_read_b128 v[104:107], v237 offset:2048
	ds_read_b128 v[108:111], v237 offset:3072
	s_cmp_eq_u32 s67, 12
	s_cselect_b32 s13, s1, s3
	s_cselect_b32 s12, s9, s2
	s_cselect_b32 s3, s14, s39
	s_cselect_b32 s2, s15, s37
	s_add_i32 m0, s54, 0xc000
	ds_read_b128 v[112:115], v238
	ds_read_b128 v[116:119], v238 offset:1024
	ds_read_b128 v[120:123], v238 offset:2048
	ds_read_b128 v[156:159], v238 offset:3072
	ds_read_b128 v[160:163], v238 offset:4096
	ds_read_b128 v[164:167], v238 offset:5120
	ds_read_b128 v[190:193], v238 offset:6144
	global_load_lds_dwordx4 v186, s[10:11]
	s_add_i32 m0, s54, 0xe000
	ds_read_b128 v[194:197], v238 offset:7168
	global_load_lds_dwordx4 v188, s[10:11]
	s_waitcnt lgkmcnt(8)
	s_barrier
	s_waitcnt lgkmcnt(0)
	v_mfma_f32_16x16x32_bf16 v[152:155], v[48:51], v[112:115], v[152:155]
	v_mfma_f32_16x16x32_bf16 v[68:71], v[104:107], v[112:115], v[68:71]
	v_mfma_f32_16x16x32_bf16 v[148:151], v[48:51], v[120:123], v[148:151]
	v_mfma_f32_16x16x32_bf16 v[64:67], v[104:107], v[120:123], v[64:67]
	v_mfma_f32_16x16x32_bf16 v[136:139], v[48:51], v[160:163], v[136:139]
	v_mfma_f32_16x16x32_bf16 v[44:47], v[104:107], v[160:163], v[44:47]
	v_mfma_f32_16x16x32_bf16 v[128:131], v[48:51], v[190:193], v[128:131]
	v_mfma_f32_16x16x32_bf16 v[40:43], v[104:107], v[190:193], v[40:43]
	v_mfma_f32_16x16x32_bf16 v[152:155], v[52:55], v[116:119], v[152:155]
	v_mfma_f32_16x16x32_bf16 v[68:71], v[108:111], v[116:119], v[68:71]
	v_mfma_f32_16x16x32_bf16 v[148:151], v[52:55], v[156:159], v[148:151]
	v_mfma_f32_16x16x32_bf16 v[64:67], v[108:111], v[156:159], v[64:67]
	v_mfma_f32_16x16x32_bf16 v[136:139], v[52:55], v[164:167], v[136:139]
	v_mfma_f32_16x16x32_bf16 v[44:47], v[108:111], v[164:167], v[44:47]
	v_mfma_f32_16x16x32_bf16 v[128:131], v[52:55], v[194:197], v[128:131]
	v_mfma_f32_16x16x32_bf16 v[40:43], v[108:111], v[194:197], v[40:43]
	s_barrier
	s_add_u32 s98, s2, 0x80
	s_addc_u32 s99, s3, 0
	s_add_i32 m0, s53, 0x10000
	ds_read_b128 v[198:201], v237 offset:16384
	ds_read_b128 v[202:205], v237 offset:17408
	ds_read_b128 v[206:209], v237 offset:18432
	global_load_lds_dwordx4 v168, s[2:3]
	s_add_i32 m0, s53, 0x12000
	ds_read_b128 v[210:213], v237 offset:19456
	global_load_lds_dwordx4 v184, s[2:3]
	s_barrier
	s_waitcnt lgkmcnt(0)
	v_mfma_f32_16x16x32_bf16 v[144:147], v[198:201], v[112:115], v[144:147]
	v_mfma_f32_16x16x32_bf16 v[60:63], v[206:209], v[112:115], v[60:63]
	v_mfma_f32_16x16x32_bf16 v[56:59], v[206:209], v[120:123], v[56:59]
	v_mfma_f32_16x16x32_bf16 v[36:39], v[206:209], v[160:163], v[36:39]
	v_mfma_f32_16x16x32_bf16 v[32:35], v[206:209], v[190:193], v[32:35]
	v_mfma_f32_16x16x32_bf16 v[144:147], v[202:205], v[116:119], v[144:147]
	v_mfma_f32_16x16x32_bf16 v[60:63], v[210:213], v[116:119], v[60:63]
	v_mfma_f32_16x16x32_bf16 v[112:115], v[198:201], v[120:123], v[140:143]
	v_mfma_f32_16x16x32_bf16 v[56:59], v[210:213], v[156:159], v[56:59]
	v_mfma_f32_16x16x32_bf16 v[116:119], v[198:201], v[160:163], v[132:135]
	v_mfma_f32_16x16x32_bf16 v[36:39], v[210:213], v[164:167], v[36:39]
	v_mfma_f32_16x16x32_bf16 v[120:123], v[198:201], v[190:193], v[124:127]
	v_mfma_f32_16x16x32_bf16 v[32:35], v[210:213], v[194:197], v[32:35]
	v_mfma_f32_16x16x32_bf16 v[112:115], v[202:205], v[156:159], v[112:115]
	v_mfma_f32_16x16x32_bf16 v[116:119], v[202:205], v[164:167], v[116:119]
	v_mfma_f32_16x16x32_bf16 v[120:123], v[202:205], v[194:197], v[120:123]
	s_mov_b32 m0, s54
	s_add_u32 s100, s12, 0x80
	s_addc_u32 s101, s13, 0
	s_barrier
	ds_read_b128 v[124:127], v238 offset:16384
	ds_read_b128 v[132:135], v238 offset:17408
	ds_read_b128 v[140:143], v238 offset:18432
	ds_read_b128 v[156:159], v238 offset:19456
	ds_read_b128 v[160:163], v238 offset:20480
	ds_read_b128 v[164:167], v238 offset:21504
	ds_read_b128 v[190:193], v238 offset:22528
	global_load_lds_dwordx4 v180, s[12:13]
	s_mov_b32 m0, s55
	ds_read_b128 v[194:197], v238 offset:23552
	global_load_lds_dwordx4 v182, s[12:13]
	s_barrier
	s_waitcnt lgkmcnt(0)
	s_barrier
	s_add_i32 m0, s53, 0x14000
	s_add_u32 s68, s2, 0x40000
	s_addc_u32 s69, s3, 0
	global_load_lds_dwordx4 v168, s[68:69]
	s_add_i32 m0, s53, 0x16000
	s_add_u32 s12, s12, 0x40000
	s_addc_u32 s13, s13, 0
	global_load_lds_dwordx4 v184, s[68:69]
	s_waitcnt vmcnt(6)
	s_barrier
	s_barrier
	ds_read_b128 v[76:79], v237 offset:32768
	ds_read_b128 v[92:95], v237 offset:33792
	ds_read_b128 v[104:107], v237 offset:34816
	ds_read_b128 v[108:111], v237 offset:35840
	s_mov_b32 m0, s56
	ds_read_b128 v[124:127], v238 offset:32768
	ds_read_b128 v[132:135], v238 offset:33792
	ds_read_b128 v[156:159], v238 offset:34816
	ds_read_b128 v[160:163], v238 offset:35840
	ds_read_b128 v[164:167], v238 offset:36864
	ds_read_b128 v[190:193], v238 offset:37888
	ds_read_b128 v[194:197], v238 offset:38912
	global_load_lds_dwordx4 v180, s[12:13]
	s_mov_b32 m0, s57
	ds_read_b128 v[198:201], v238 offset:39936
	global_load_lds_dwordx4 v182, s[12:13]
	s_waitcnt lgkmcnt(8)
	s_barrier
	s_waitcnt lgkmcnt(0)
	v_mfma_f32_16x16x32_bf16 v[140:143], v[76:79], v[124:127], v[152:155]
	v_mfma_f32_16x16x32_bf16 v[152:155], v[92:95], v[132:135], v[140:143]
	v_mfma_f32_16x16x32_bf16 v[68:71], v[104:107], v[124:127], v[68:71]
	v_mfma_f32_16x16x32_bf16 v[140:143], v[76:79], v[156:159], v[148:151]
	v_mfma_f32_16x16x32_bf16 v[64:67], v[104:107], v[156:159], v[64:67]
	v_mfma_f32_16x16x32_bf16 v[136:139], v[76:79], v[164:167], v[136:139]
	v_mfma_f32_16x16x32_bf16 v[44:47], v[104:107], v[164:167], v[44:47]
	v_mfma_f32_16x16x32_bf16 v[128:131], v[76:79], v[194:197], v[128:131]
	v_mfma_f32_16x16x32_bf16 v[40:43], v[104:107], v[194:197], v[40:43]
	v_mfma_f32_16x16x32_bf16 v[68:71], v[108:111], v[132:135], v[68:71]
	v_mfma_f32_16x16x32_bf16 v[148:151], v[92:95], v[160:163], v[140:143]
	v_mfma_f32_16x16x32_bf16 v[64:67], v[108:111], v[160:163], v[64:67]
	v_mfma_f32_16x16x32_bf16 v[136:139], v[92:95], v[190:193], v[136:139]
	v_mfma_f32_16x16x32_bf16 v[44:47], v[108:111], v[190:193], v[44:47]
	v_mfma_f32_16x16x32_bf16 v[128:131], v[92:95], v[198:201], v[128:131]
	v_mfma_f32_16x16x32_bf16 v[40:43], v[108:111], v[198:201], v[40:43]
	s_barrier
	ds_read_b128 v[202:205], v237 offset:49152
	ds_read_b128 v[206:209], v237 offset:50176
	s_add_i32 m0, s53, 0x18000
	ds_read_b128 v[210:213], v237 offset:51200
	global_load_lds_dwordx4 v168, s[98:99]
	s_add_i32 m0, s53, 0x1a000
	ds_read_b128 v[214:217], v237 offset:52224
	global_load_lds_dwordx4 v184, s[98:99]
	s_barrier
	s_waitcnt lgkmcnt(0)
	v_mfma_f32_16x16x32_bf16 v[140:143], v[202:205], v[124:127], v[144:147]
	v_mfma_f32_16x16x32_bf16 v[112:115], v[202:205], v[156:159], v[112:115]
	v_mfma_f32_16x16x32_bf16 v[144:147], v[206:209], v[132:135], v[140:143]
	v_mfma_f32_16x16x32_bf16 v[60:63], v[210:213], v[124:127], v[60:63]
	v_mfma_f32_16x16x32_bf16 v[140:143], v[206:209], v[160:163], v[112:115]
	v_mfma_f32_16x16x32_bf16 v[112:115], v[202:205], v[164:167], v[116:119]
	v_mfma_f32_16x16x32_bf16 v[60:63], v[214:217], v[132:135], v[60:63]
	v_mfma_f32_16x16x32_bf16 v[56:59], v[210:213], v[156:159], v[56:59]
	v_mfma_f32_16x16x32_bf16 v[132:135], v[206:209], v[190:193], v[112:115]
	v_mfma_f32_16x16x32_bf16 v[36:39], v[210:213], v[164:167], v[36:39]
	v_mfma_f32_16x16x32_bf16 v[112:115], v[202:205], v[194:197], v[120:123]
	v_mfma_f32_16x16x32_bf16 v[32:35], v[210:213], v[194:197], v[32:35]
	v_mfma_f32_16x16x32_bf16 v[56:59], v[214:217], v[160:163], v[56:59]
	v_mfma_f32_16x16x32_bf16 v[36:39], v[214:217], v[190:193], v[36:39]
	v_mfma_f32_16x16x32_bf16 v[124:127], v[206:209], v[198:201], v[112:115]
	v_mfma_f32_16x16x32_bf16 v[32:35], v[214:217], v[198:201], v[32:35]
	s_mov_b32 m0, s62
	s_barrier
	ds_read_b128 v[112:115], v238 offset:49152
	ds_read_b128 v[116:119], v238 offset:50176
	ds_read_b128 v[120:123], v238 offset:51200
	ds_read_b128 v[156:159], v238 offset:52224
	ds_read_b128 v[160:163], v238 offset:53248
	ds_read_b128 v[164:167], v238 offset:54272
	ds_read_b128 v[190:193], v238 offset:55296
	global_load_lds_dwordx4 v180, s[100:101]
	s_mov_b32 m0, s63
	ds_read_b128 v[194:197], v238 offset:56320
	global_load_lds_dwordx4 v182, s[100:101]
	s_barrier
	s_waitcnt lgkmcnt(0)
	s_barrier
	s_add_i32 m0, s53, 0x1c000
	s_add_u32 s2, s2, 0x40080
	s_addc_u32 s3, s3, 0
	global_load_lds_dwordx4 v168, s[2:3]
	s_add_i32 m0, s53, 0x1e000
	s_add_i32 s67, s67, 2
	global_load_lds_dwordx4 v184, s[2:3]
	s_waitcnt vmcnt(6)
	s_barrier
	s_add_u32 s10, s10, 0x100
	s_addc_u32 s11, s11, 0
	s_add_u32 s37, s37, 0x100
	s_addc_u32 s39, s39, 0
	s_cmp_gt_u32 s67, 13
	s_barrier
	s_cbranch_scc0 .Lup_half_loop
	s_branch .Lup_epi

.LBB0_1048:
	s_add_u32 s56, s2, 0x100
	s_addc_u32 s57, s3, 0
	s_mov_b32 s58, -2
	s_add_u32 s2, s24, 0x100
	s_addc_u32 s3, s25, 0
	ds_read_b128 v[40:43], v194
	ds_read_b128 v[44:47], v194 offset:1024
	ds_read_b128 v[48:51], v194 offset:2048
	ds_read_b128 v[52:55], v194 offset:3072
	s_cmp_eq_u32 s58, 40
	s_cselect_b32 s27, s1, s3
	s_cselect_b32 s26, s0, s2
	s_cselect_b32 s9, s23, s57
	s_cselect_b32 s8, s22, s56
	s_add_i32 m0, s37, 0xc000
	ds_read_b128 v[56:59], v195
	ds_read_b128 v[60:63], v195 offset:1024
	ds_read_b128 v[72:75], v195 offset:2048
	ds_read_b128 v[84:87], v195 offset:3072
	ds_read_b128 v[182:185], v195 offset:4096
	ds_read_b128 v[186:189], v195 offset:5120
	ds_read_b128 v[196:199], v195 offset:6144
	global_load_lds_dwordx4 v166, s[24:25]
	s_add_i32 m0, s37, 0xe000
	ds_read_b128 v[200:203], v195 offset:7168
	global_load_lds_dwordx4 v180, s[24:25]
	s_waitcnt lgkmcnt(8)
	s_barrier
	s_waitcnt lgkmcnt(0)
	v_mfma_f32_16x16x32_bf16 v[156:159], v[40:43], v[56:59], 0
	v_mfma_f32_16x16x32_bf16 v[152:155], v[48:51], v[56:59], 0
	v_mfma_f32_16x16x32_bf16 v[140:143], v[40:43], v[72:75], 0
	v_mfma_f32_16x16x32_bf16 v[136:139], v[48:51], v[72:75], 0
	v_mfma_f32_16x16x32_bf16 v[124:127], v[40:43], v[182:185], 0
	v_mfma_f32_16x16x32_bf16 v[120:123], v[48:51], v[182:185], 0
	v_mfma_f32_16x16x32_bf16 v[108:111], v[40:43], v[196:199], 0
	v_mfma_f32_16x16x32_bf16 v[104:107], v[48:51], v[196:199], 0
	v_mfma_f32_16x16x32_bf16 v[156:159], v[44:47], v[60:63], v[156:159]
	v_mfma_f32_16x16x32_bf16 v[152:155], v[52:55], v[60:63], v[152:155]
	v_mfma_f32_16x16x32_bf16 v[140:143], v[44:47], v[84:87], v[140:143]
	v_mfma_f32_16x16x32_bf16 v[136:139], v[52:55], v[84:87], v[136:139]
	v_mfma_f32_16x16x32_bf16 v[124:127], v[44:47], v[186:189], v[124:127]
	v_mfma_f32_16x16x32_bf16 v[120:123], v[52:55], v[186:189], v[120:123]
	v_mfma_f32_16x16x32_bf16 v[108:111], v[44:47], v[200:203], v[108:111]
	v_mfma_f32_16x16x32_bf16 v[104:107], v[52:55], v[200:203], v[104:107]
	s_barrier
	ds_read_b128 v[204:207], v194 offset:16384
	ds_read_b128 v[208:211], v194 offset:17408
	ds_read_b128 v[212:215], v194 offset:18432
	s_add_i32 m0, s36, 0x10000
	ds_read_b128 v[216:219], v194 offset:19456
	global_load_lds_dwordx4 v168, s[8:9]
	s_add_i32 m0, s36, 0x12000
	s_add_u32 s98, s8, 0x80
	s_addc_u32 s99, s9, 0
	global_load_lds_dwordx4 v164, s[8:9]
	s_barrier
	s_waitcnt lgkmcnt(0)
	v_mfma_f32_16x16x32_bf16 v[148:151], v[204:207], v[56:59], 0
	v_mfma_f32_16x16x32_bf16 v[56:59], v[212:215], v[56:59], 0
	v_mfma_f32_16x16x32_bf16 v[148:151], v[208:211], v[60:63], v[148:151]
	v_mfma_f32_16x16x32_bf16 v[56:59], v[216:219], v[60:63], v[56:59]
	v_mfma_f32_16x16x32_bf16 v[60:63], v[204:207], v[72:75], 0
	v_mfma_f32_16x16x32_bf16 v[72:75], v[212:215], v[72:75], 0
	v_mfma_f32_16x16x32_bf16 v[112:115], v[212:215], v[182:185], 0
	v_mfma_f32_16x16x32_bf16 v[100:103], v[204:207], v[196:199], 0
	v_mfma_f32_16x16x32_bf16 v[96:99], v[212:215], v[196:199], 0
	v_mfma_f32_16x16x32_bf16 v[60:63], v[208:211], v[84:87], v[60:63]
	v_mfma_f32_16x16x32_bf16 v[72:75], v[216:219], v[84:87], v[72:75]
	v_mfma_f32_16x16x32_bf16 v[84:87], v[204:207], v[182:185], 0
	v_mfma_f32_16x16x32_bf16 v[112:115], v[216:219], v[186:189], v[112:115]
	v_mfma_f32_16x16x32_bf16 v[100:103], v[208:211], v[200:203], v[100:103]
	v_mfma_f32_16x16x32_bf16 v[96:99], v[216:219], v[200:203], v[96:99]
	v_mfma_f32_16x16x32_bf16 v[84:87], v[208:211], v[186:189], v[84:87]
	s_mov_b32 m0, s37
	s_add_u32 s100, s26, 0x80
	s_addc_u32 s101, s27, 0
	s_barrier
	ds_read_b128 v[116:119], v195 offset:16384
	ds_read_b128 v[128:131], v195 offset:17408
	ds_read_b128 v[132:135], v195 offset:18432
	ds_read_b128 v[144:147], v195 offset:19456
	ds_read_b128 v[182:185], v195 offset:20480
	ds_read_b128 v[186:189], v195 offset:21504
	ds_read_b128 v[196:199], v195 offset:22528
	global_load_lds_dwordx4 v160, s[26:27]
	s_mov_b32 m0, s38
	ds_read_b128 v[200:203], v195 offset:23552
	global_load_lds_dwordx4 v162, s[26:27]
	s_barrier
	s_waitcnt lgkmcnt(0)
	v_mfma_f32_16x16x32_bf16 v[92:95], v[40:43], v[116:119], 0
	v_mfma_f32_16x16x32_bf16 v[88:91], v[48:51], v[116:119], 0
	v_mfma_f32_16x16x32_bf16 v[68:71], v[40:43], v[132:135], 0
	v_mfma_f32_16x16x32_bf16 v[64:67], v[48:51], v[132:135], 0
	v_mfma_f32_16x16x32_bf16 v[28:31], v[40:43], v[182:185], 0
	v_mfma_f32_16x16x32_bf16 v[24:27], v[48:51], v[182:185], 0
	v_mfma_f32_16x16x32_bf16 v[12:15], v[40:43], v[196:199], 0
	v_mfma_f32_16x16x32_bf16 v[8:11], v[48:51], v[196:199], 0
	v_mfma_f32_16x16x32_bf16 v[92:95], v[44:47], v[128:131], v[92:95]
	v_mfma_f32_16x16x32_bf16 v[88:91], v[52:55], v[128:131], v[88:91]
	v_mfma_f32_16x16x32_bf16 v[68:71], v[44:47], v[144:147], v[68:71]
	v_mfma_f32_16x16x32_bf16 v[64:67], v[52:55], v[144:147], v[64:67]
	v_mfma_f32_16x16x32_bf16 v[28:31], v[44:47], v[186:189], v[28:31]
	v_mfma_f32_16x16x32_bf16 v[24:27], v[52:55], v[186:189], v[24:27]
	v_mfma_f32_16x16x32_bf16 v[12:15], v[44:47], v[200:203], v[12:15]
	v_mfma_f32_16x16x32_bf16 v[8:11], v[52:55], v[200:203], v[8:11]
	s_barrier
	s_add_i32 m0, s36, 0x14000
	s_add_u32 s24, s8, 0xb0000
	s_addc_u32 s25, s9, 0
	global_load_lds_dwordx4 v168, s[24:25]
	s_add_i32 m0, s36, 0x16000
	s_nop 0
	global_load_lds_dwordx4 v164, s[24:25]
	s_waitcnt vmcnt(6)
	s_barrier
	v_mfma_f32_16x16x32_bf16 v[36:39], v[204:207], v[132:135], 0
	v_mfma_f32_16x16x32_bf16 v[32:35], v[212:215], v[132:135], 0
	v_mfma_f32_16x16x32_bf16 v[20:23], v[204:207], v[182:185], 0
	v_mfma_f32_16x16x32_bf16 v[16:19], v[212:215], v[182:185], 0
	v_mfma_f32_16x16x32_bf16 v[4:7], v[204:207], v[196:199], 0
	v_mfma_f32_16x16x32_bf16 v[0:3], v[212:215], v[196:199], 0
	v_mfma_f32_16x16x32_bf16 v[40:43], v[204:207], v[116:119], 0
	v_mfma_f32_16x16x32_bf16 v[44:47], v[212:215], v[116:119], 0
	v_mfma_f32_16x16x32_bf16 v[36:39], v[208:211], v[144:147], v[36:39]
	v_mfma_f32_16x16x32_bf16 v[32:35], v[216:219], v[144:147], v[32:35]
	v_mfma_f32_16x16x32_bf16 v[20:23], v[208:211], v[186:189], v[20:23]
	v_mfma_f32_16x16x32_bf16 v[16:19], v[216:219], v[186:189], v[16:19]
	v_mfma_f32_16x16x32_bf16 v[4:7], v[208:211], v[200:203], v[4:7]
	v_mfma_f32_16x16x32_bf16 v[0:3], v[216:219], v[200:203], v[0:3]
	v_mfma_f32_16x16x32_bf16 v[40:43], v[208:211], v[128:131], v[40:43]
	v_mfma_f32_16x16x32_bf16 v[44:47], v[216:219], v[128:131], v[44:47]
	s_barrier
	ds_read_b128 v[48:51], v194 offset:32768
	ds_read_b128 v[52:55], v194 offset:33792
	ds_read_b128 v[76:79], v194 offset:34816
	ds_read_b128 v[80:83], v194 offset:35840
	s_add_u32 s24, s26, 0xb0000
	s_addc_u32 s25, s27, 0
	s_mov_b32 m0, s39
	ds_read_b128 v[116:119], v195 offset:32768
	ds_read_b128 v[128:131], v195 offset:33792
	ds_read_b128 v[182:185], v195 offset:34816
	ds_read_b128 v[186:189], v195 offset:35840
	ds_read_b128 v[196:199], v195 offset:36864
	ds_read_b128 v[200:203], v195 offset:37888
	ds_read_b128 v[204:207], v195 offset:38912
	global_load_lds_dwordx4 v160, s[24:25]
	s_mov_b32 m0, s40
	ds_read_b128 v[208:211], v195 offset:39936
	global_load_lds_dwordx4 v162, s[24:25]
	s_waitcnt lgkmcnt(8)
	s_barrier
	s_waitcnt lgkmcnt(0)
	v_mfma_f32_16x16x32_bf16 v[132:135], v[48:51], v[116:119], v[156:159]
	v_mfma_f32_16x16x32_bf16 v[156:159], v[52:55], v[128:131], v[132:135]
	v_mfma_f32_16x16x32_bf16 v[132:135], v[76:79], v[116:119], v[152:155]
	v_mfma_f32_16x16x32_bf16 v[152:155], v[80:83], v[128:131], v[132:135]
	v_mfma_f32_16x16x32_bf16 v[132:135], v[48:51], v[182:185], v[140:143]
	v_mfma_f32_16x16x32_bf16 v[140:143], v[52:55], v[186:189], v[132:135]
	v_mfma_f32_16x16x32_bf16 v[132:135], v[76:79], v[182:185], v[136:139]
	v_mfma_f32_16x16x32_bf16 v[124:127], v[48:51], v[196:199], v[124:127]
	v_mfma_f32_16x16x32_bf16 v[120:123], v[76:79], v[196:199], v[120:123]
	v_mfma_f32_16x16x32_bf16 v[108:111], v[48:51], v[204:207], v[108:111]
	v_mfma_f32_16x16x32_bf16 v[104:107], v[76:79], v[204:207], v[104:107]
	v_mfma_f32_16x16x32_bf16 v[136:139], v[80:83], v[186:189], v[132:135]
	v_mfma_f32_16x16x32_bf16 v[124:127], v[52:55], v[200:203], v[124:127]
	v_mfma_f32_16x16x32_bf16 v[120:123], v[80:83], v[200:203], v[120:123]
	v_mfma_f32_16x16x32_bf16 v[108:111], v[52:55], v[208:211], v[108:111]
	v_mfma_f32_16x16x32_bf16 v[104:107], v[80:83], v[208:211], v[104:107]
	s_barrier
	ds_read_b128 v[212:215], v194 offset:49152
	ds_read_b128 v[216:219], v194 offset:50176
	s_add_i32 m0, s36, 0x18000
	ds_read_b128 v[220:223], v194 offset:51200
	global_load_lds_dwordx4 v168, s[98:99]
	s_add_i32 m0, s36, 0x1a000
	ds_read_b128 v[236:239], v194 offset:52224
	global_load_lds_dwordx4 v164, s[98:99]
	s_barrier
	s_waitcnt lgkmcnt(0)
	v_mfma_f32_16x16x32_bf16 v[56:59], v[220:223], v[116:119], v[56:59]
	v_mfma_f32_16x16x32_bf16 v[132:135], v[212:215], v[116:119], v[148:151]
	v_mfma_f32_16x16x32_bf16 v[144:147], v[236:239], v[128:131], v[56:59]
	v_mfma_f32_16x16x32_bf16 v[56:59], v[212:215], v[182:185], v[60:63]
	v_mfma_f32_16x16x32_bf16 v[148:151], v[216:219], v[128:131], v[132:135]
	v_mfma_f32_16x16x32_bf16 v[132:135], v[216:219], v[186:189], v[56:59]
	v_mfma_f32_16x16x32_bf16 v[56:59], v[220:223], v[182:185], v[72:75]
	v_mfma_f32_16x16x32_bf16 v[128:131], v[236:239], v[186:189], v[56:59]
	v_mfma_f32_16x16x32_bf16 v[56:59], v[212:215], v[196:199], v[84:87]
	v_mfma_f32_16x16x32_bf16 v[116:119], v[216:219], v[200:203], v[56:59]
	v_mfma_f32_16x16x32_bf16 v[56:59], v[220:223], v[196:199], v[112:115]
	v_mfma_f32_16x16x32_bf16 v[112:115], v[236:239], v[200:203], v[56:59]
	v_mfma_f32_16x16x32_bf16 v[56:59], v[212:215], v[204:207], v[100:103]
	v_mfma_f32_16x16x32_bf16 v[100:103], v[216:219], v[208:211], v[56:59]
	v_mfma_f32_16x16x32_bf16 v[56:59], v[220:223], v[204:207], v[96:99]
	v_mfma_f32_16x16x32_bf16 v[96:99], v[236:239], v[208:211], v[56:59]
	s_mov_b32 m0, s47
	s_barrier
	s_nop 2
	ds_read_b128 v[56:59], v195 offset:49152
	ds_read_b128 v[60:63], v195 offset:50176
	ds_read_b128 v[72:75], v195 offset:51200
	ds_read_b128 v[84:87], v195 offset:52224
	ds_read_b128 v[182:185], v195 offset:53248
	ds_read_b128 v[186:189], v195 offset:54272
	ds_read_b128 v[196:199], v195 offset:55296
	global_load_lds_dwordx4 v160, s[100:101]
	s_mov_b32 m0, s49
	ds_read_b128 v[200:203], v195 offset:56320
	global_load_lds_dwordx4 v162, s[100:101]
	s_barrier
	s_waitcnt lgkmcnt(0)
	v_mfma_f32_16x16x32_bf16 v[92:95], v[48:51], v[56:59], v[92:95]
	v_mfma_f32_16x16x32_bf16 v[88:91], v[76:79], v[56:59], v[88:91]
	v_mfma_f32_16x16x32_bf16 v[68:71], v[48:51], v[72:75], v[68:71]
	v_mfma_f32_16x16x32_bf16 v[64:67], v[76:79], v[72:75], v[64:67]
	v_mfma_f32_16x16x32_bf16 v[28:31], v[48:51], v[182:185], v[28:31]
	v_mfma_f32_16x16x32_bf16 v[24:27], v[76:79], v[182:185], v[24:27]
	v_mfma_f32_16x16x32_bf16 v[12:15], v[48:51], v[196:199], v[12:15]
	v_mfma_f32_16x16x32_bf16 v[8:11], v[76:79], v[196:199], v[8:11]
	v_mfma_f32_16x16x32_bf16 v[92:95], v[52:55], v[60:63], v[92:95]
	v_mfma_f32_16x16x32_bf16 v[88:91], v[80:83], v[60:63], v[88:91]
	v_mfma_f32_16x16x32_bf16 v[68:71], v[52:55], v[84:87], v[68:71]
	v_mfma_f32_16x16x32_bf16 v[64:67], v[80:83], v[84:87], v[64:67]
	v_mfma_f32_16x16x32_bf16 v[28:31], v[52:55], v[186:189], v[28:31]
	v_mfma_f32_16x16x32_bf16 v[24:27], v[80:83], v[186:189], v[24:27]
	v_mfma_f32_16x16x32_bf16 v[12:15], v[52:55], v[200:203], v[12:15]
	v_mfma_f32_16x16x32_bf16 v[8:11], v[80:83], v[200:203], v[8:11]
	s_barrier
	s_add_i32 m0, s36, 0x1c000
	s_add_u32 s8, s8, 0xb0080
	s_addc_u32 s9, s9, 0
	global_load_lds_dwordx4 v168, s[8:9]
	s_add_i32 m0, s36, 0x1e000
	s_add_i32 s58, s58, 2
	global_load_lds_dwordx4 v164, s[8:9]
	s_waitcnt vmcnt(6)
	s_barrier
	v_mfma_f32_16x16x32_bf16 v[40:43], v[212:215], v[56:59], v[40:43]
	v_mfma_f32_16x16x32_bf16 v[80:83], v[216:219], v[60:63], v[40:43]
	v_mfma_f32_16x16x32_bf16 v[40:43], v[220:223], v[56:59], v[44:47]
	v_mfma_f32_16x16x32_bf16 v[36:39], v[212:215], v[72:75], v[36:39]
	v_mfma_f32_16x16x32_bf16 v[32:35], v[220:223], v[72:75], v[32:35]
	v_mfma_f32_16x16x32_bf16 v[20:23], v[212:215], v[182:185], v[20:23]
	v_mfma_f32_16x16x32_bf16 v[16:19], v[220:223], v[182:185], v[16:19]
	v_mfma_f32_16x16x32_bf16 v[4:7], v[212:215], v[196:199], v[4:7]
	v_mfma_f32_16x16x32_bf16 v[0:3], v[220:223], v[196:199], v[0:3]
	v_mfma_f32_16x16x32_bf16 v[76:79], v[236:239], v[60:63], v[40:43]
	v_mfma_f32_16x16x32_bf16 v[36:39], v[216:219], v[84:87], v[36:39]
	v_mfma_f32_16x16x32_bf16 v[32:35], v[236:239], v[84:87], v[32:35]
	v_mfma_f32_16x16x32_bf16 v[20:23], v[216:219], v[186:189], v[20:23]
	v_mfma_f32_16x16x32_bf16 v[16:19], v[236:239], v[186:189], v[16:19]
	v_mfma_f32_16x16x32_bf16 v[4:7], v[216:219], v[200:203], v[4:7]
	v_mfma_f32_16x16x32_bf16 v[0:3], v[236:239], v[200:203], v[0:3]
	s_add_u32 s56, s56, 0x100
	s_addc_u32 s57, s57, 0
	s_cmp_gt_u32 s58, 41
	s_mov_b64 s[24:25], s[2:3]
	s_barrier
.LBB0_1049:
	s_add_u32 s2, s24, 0x100
	s_addc_u32 s3, s25, 0
	ds_read_b128 v[40:43], v194
	ds_read_b128 v[44:47], v194 offset:1024
	ds_read_b128 v[48:51], v194 offset:2048
	ds_read_b128 v[52:55], v194 offset:3072
	s_cmp_eq_u32 s58, 40
	s_cselect_b32 s27, s1, s3
	s_cselect_b32 s26, s0, s2
	s_cselect_b32 s9, s23, s57
	s_cselect_b32 s8, s22, s56
	s_add_i32 m0, s37, 0xc000
	ds_read_b128 v[56:59], v195
	ds_read_b128 v[60:63], v195 offset:1024
	ds_read_b128 v[72:75], v195 offset:2048
	ds_read_b128 v[84:87], v195 offset:3072
	ds_read_b128 v[182:185], v195 offset:4096
	ds_read_b128 v[186:189], v195 offset:5120
	ds_read_b128 v[196:199], v195 offset:6144
	global_load_lds_dwordx4 v166, s[24:25]
	s_add_i32 m0, s37, 0xe000
	ds_read_b128 v[200:203], v195 offset:7168
	global_load_lds_dwordx4 v180, s[24:25]
	s_waitcnt lgkmcnt(8)
	s_barrier
	s_waitcnt lgkmcnt(0)
	v_mfma_f32_16x16x32_bf16 v[156:159], v[40:43], v[56:59], v[156:159]
	v_mfma_f32_16x16x32_bf16 v[152:155], v[48:51], v[56:59], v[152:155]
	v_mfma_f32_16x16x32_bf16 v[140:143], v[40:43], v[72:75], v[140:143]
	v_mfma_f32_16x16x32_bf16 v[136:139], v[48:51], v[72:75], v[136:139]
	v_mfma_f32_16x16x32_bf16 v[124:127], v[40:43], v[182:185], v[124:127]
	v_mfma_f32_16x16x32_bf16 v[120:123], v[48:51], v[182:185], v[120:123]
	v_mfma_f32_16x16x32_bf16 v[108:111], v[40:43], v[196:199], v[108:111]
	v_mfma_f32_16x16x32_bf16 v[104:107], v[48:51], v[196:199], v[104:107]
	v_mfma_f32_16x16x32_bf16 v[156:159], v[44:47], v[60:63], v[156:159]
	v_mfma_f32_16x16x32_bf16 v[152:155], v[52:55], v[60:63], v[152:155]
	v_mfma_f32_16x16x32_bf16 v[140:143], v[44:47], v[84:87], v[140:143]
	v_mfma_f32_16x16x32_bf16 v[136:139], v[52:55], v[84:87], v[136:139]
	v_mfma_f32_16x16x32_bf16 v[124:127], v[44:47], v[186:189], v[124:127]
	v_mfma_f32_16x16x32_bf16 v[120:123], v[52:55], v[186:189], v[120:123]
	v_mfma_f32_16x16x32_bf16 v[108:111], v[44:47], v[200:203], v[108:111]
	v_mfma_f32_16x16x32_bf16 v[104:107], v[52:55], v[200:203], v[104:107]
	s_barrier
	ds_read_b128 v[204:207], v194 offset:16384
	ds_read_b128 v[208:211], v194 offset:17408
	ds_read_b128 v[212:215], v194 offset:18432
	s_add_i32 m0, s36, 0x10000
	ds_read_b128 v[216:219], v194 offset:19456
	global_load_lds_dwordx4 v168, s[8:9]
	s_add_i32 m0, s36, 0x12000
	s_add_u32 s98, s8, 0x80
	s_addc_u32 s99, s9, 0
	global_load_lds_dwordx4 v164, s[8:9]
	s_barrier
	s_waitcnt lgkmcnt(0)
	v_mfma_f32_16x16x32_bf16 v[148:151], v[204:207], v[56:59], v[148:151]
	v_mfma_f32_16x16x32_bf16 v[56:59], v[212:215], v[56:59], v[144:147]
	v_mfma_f32_16x16x32_bf16 v[148:151], v[208:211], v[60:63], v[148:151]
	v_mfma_f32_16x16x32_bf16 v[56:59], v[216:219], v[60:63], v[56:59]
	v_mfma_f32_16x16x32_bf16 v[60:63], v[204:207], v[72:75], v[132:135]
	v_mfma_f32_16x16x32_bf16 v[72:75], v[212:215], v[72:75], v[128:131]
	v_mfma_f32_16x16x32_bf16 v[112:115], v[212:215], v[182:185], v[112:115]
	v_mfma_f32_16x16x32_bf16 v[100:103], v[204:207], v[196:199], v[100:103]
	v_mfma_f32_16x16x32_bf16 v[96:99], v[212:215], v[196:199], v[96:99]
	v_mfma_f32_16x16x32_bf16 v[60:63], v[208:211], v[84:87], v[60:63]
	v_mfma_f32_16x16x32_bf16 v[72:75], v[216:219], v[84:87], v[72:75]
	v_mfma_f32_16x16x32_bf16 v[84:87], v[204:207], v[182:185], v[116:119]
	v_mfma_f32_16x16x32_bf16 v[112:115], v[216:219], v[186:189], v[112:115]
	v_mfma_f32_16x16x32_bf16 v[100:103], v[208:211], v[200:203], v[100:103]
	v_mfma_f32_16x16x32_bf16 v[96:99], v[216:219], v[200:203], v[96:99]
	v_mfma_f32_16x16x32_bf16 v[84:87], v[208:211], v[186:189], v[84:87]
	s_mov_b32 m0, s37
	s_add_u32 s100, s26, 0x80
	s_addc_u32 s101, s27, 0
	s_barrier
	ds_read_b128 v[116:119], v195 offset:16384
	ds_read_b128 v[128:131], v195 offset:17408
	ds_read_b128 v[132:135], v195 offset:18432
	ds_read_b128 v[144:147], v195 offset:19456
	ds_read_b128 v[182:185], v195 offset:20480
	ds_read_b128 v[186:189], v195 offset:21504
	ds_read_b128 v[196:199], v195 offset:22528
	global_load_lds_dwordx4 v160, s[26:27]
	s_mov_b32 m0, s38
	ds_read_b128 v[200:203], v195 offset:23552
	global_load_lds_dwordx4 v162, s[26:27]
	s_barrier
	s_waitcnt lgkmcnt(0)
	v_mfma_f32_16x16x32_bf16 v[92:95], v[40:43], v[116:119], v[92:95]
	v_mfma_f32_16x16x32_bf16 v[88:91], v[48:51], v[116:119], v[88:91]
	v_mfma_f32_16x16x32_bf16 v[68:71], v[40:43], v[132:135], v[68:71]
	v_mfma_f32_16x16x32_bf16 v[64:67], v[48:51], v[132:135], v[64:67]
	v_mfma_f32_16x16x32_bf16 v[28:31], v[40:43], v[182:185], v[28:31]
	v_mfma_f32_16x16x32_bf16 v[24:27], v[48:51], v[182:185], v[24:27]
	v_mfma_f32_16x16x32_bf16 v[12:15], v[40:43], v[196:199], v[12:15]
	v_mfma_f32_16x16x32_bf16 v[8:11], v[48:51], v[196:199], v[8:11]
	v_mfma_f32_16x16x32_bf16 v[92:95], v[44:47], v[128:131], v[92:95]
	v_mfma_f32_16x16x32_bf16 v[88:91], v[52:55], v[128:131], v[88:91]
	v_mfma_f32_16x16x32_bf16 v[68:71], v[44:47], v[144:147], v[68:71]
	v_mfma_f32_16x16x32_bf16 v[64:67], v[52:55], v[144:147], v[64:67]
	v_mfma_f32_16x16x32_bf16 v[28:31], v[44:47], v[186:189], v[28:31]
	v_mfma_f32_16x16x32_bf16 v[24:27], v[52:55], v[186:189], v[24:27]
	v_mfma_f32_16x16x32_bf16 v[12:15], v[44:47], v[200:203], v[12:15]
	v_mfma_f32_16x16x32_bf16 v[8:11], v[52:55], v[200:203], v[8:11]
	s_barrier
	s_add_i32 m0, s36, 0x14000
	s_add_u32 s24, s8, 0xb0000
	s_addc_u32 s25, s9, 0
	global_load_lds_dwordx4 v168, s[24:25]
	s_add_i32 m0, s36, 0x16000
	s_nop 0
	global_load_lds_dwordx4 v164, s[24:25]
	s_waitcnt vmcnt(6)
	s_barrier
	v_mfma_f32_16x16x32_bf16 v[36:39], v[204:207], v[132:135], v[36:39]
	v_mfma_f32_16x16x32_bf16 v[32:35], v[212:215], v[132:135], v[32:35]
	v_mfma_f32_16x16x32_bf16 v[20:23], v[204:207], v[182:185], v[20:23]
	v_mfma_f32_16x16x32_bf16 v[16:19], v[212:215], v[182:185], v[16:19]
	v_mfma_f32_16x16x32_bf16 v[4:7], v[204:207], v[196:199], v[4:7]
	v_mfma_f32_16x16x32_bf16 v[0:3], v[212:215], v[196:199], v[0:3]
	v_mfma_f32_16x16x32_bf16 v[40:43], v[204:207], v[116:119], v[80:83]
	v_mfma_f32_16x16x32_bf16 v[44:47], v[212:215], v[116:119], v[76:79]
	v_mfma_f32_16x16x32_bf16 v[36:39], v[208:211], v[144:147], v[36:39]
	v_mfma_f32_16x16x32_bf16 v[32:35], v[216:219], v[144:147], v[32:35]
	v_mfma_f32_16x16x32_bf16 v[20:23], v[208:211], v[186:189], v[20:23]
	v_mfma_f32_16x16x32_bf16 v[16:19], v[216:219], v[186:189], v[16:19]
	v_mfma_f32_16x16x32_bf16 v[4:7], v[208:211], v[200:203], v[4:7]
	v_mfma_f32_16x16x32_bf16 v[0:3], v[216:219], v[200:203], v[0:3]
	v_mfma_f32_16x16x32_bf16 v[40:43], v[208:211], v[128:131], v[40:43]
	v_mfma_f32_16x16x32_bf16 v[44:47], v[216:219], v[128:131], v[44:47]
	s_barrier
	ds_read_b128 v[48:51], v194 offset:32768
	ds_read_b128 v[52:55], v194 offset:33792
	ds_read_b128 v[76:79], v194 offset:34816
	ds_read_b128 v[80:83], v194 offset:35840
	s_add_u32 s24, s26, 0xb0000
	s_addc_u32 s25, s27, 0
	s_mov_b32 m0, s39
	ds_read_b128 v[116:119], v195 offset:32768
	ds_read_b128 v[128:131], v195 offset:33792
	ds_read_b128 v[182:185], v195 offset:34816
	ds_read_b128 v[186:189], v195 offset:35840
	ds_read_b128 v[196:199], v195 offset:36864
	ds_read_b128 v[200:203], v195 offset:37888
	ds_read_b128 v[204:207], v195 offset:38912
	global_load_lds_dwordx4 v160, s[24:25]
	s_mov_b32 m0, s40
	ds_read_b128 v[208:211], v195 offset:39936
	global_load_lds_dwordx4 v162, s[24:25]
	s_waitcnt lgkmcnt(8)
	s_barrier
	s_waitcnt lgkmcnt(0)
	v_mfma_f32_16x16x32_bf16 v[132:135], v[48:51], v[116:119], v[156:159]
	v_mfma_f32_16x16x32_bf16 v[156:159], v[52:55], v[128:131], v[132:135]
	v_mfma_f32_16x16x32_bf16 v[132:135], v[76:79], v[116:119], v[152:155]
	v_mfma_f32_16x16x32_bf16 v[152:155], v[80:83], v[128:131], v[132:135]
	v_mfma_f32_16x16x32_bf16 v[132:135], v[48:51], v[182:185], v[140:143]
	v_mfma_f32_16x16x32_bf16 v[140:143], v[52:55], v[186:189], v[132:135]
	v_mfma_f32_16x16x32_bf16 v[132:135], v[76:79], v[182:185], v[136:139]
	v_mfma_f32_16x16x32_bf16 v[124:127], v[48:51], v[196:199], v[124:127]
	v_mfma_f32_16x16x32_bf16 v[120:123], v[76:79], v[196:199], v[120:123]
	v_mfma_f32_16x16x32_bf16 v[108:111], v[48:51], v[204:207], v[108:111]
	v_mfma_f32_16x16x32_bf16 v[104:107], v[76:79], v[204:207], v[104:107]
	v_mfma_f32_16x16x32_bf16 v[136:139], v[80:83], v[186:189], v[132:135]
	v_mfma_f32_16x16x32_bf16 v[124:127], v[52:55], v[200:203], v[124:127]
	v_mfma_f32_16x16x32_bf16 v[120:123], v[80:83], v[200:203], v[120:123]
	v_mfma_f32_16x16x32_bf16 v[108:111], v[52:55], v[208:211], v[108:111]
	v_mfma_f32_16x16x32_bf16 v[104:107], v[80:83], v[208:211], v[104:107]
	s_barrier
	ds_read_b128 v[212:215], v194 offset:49152
	ds_read_b128 v[216:219], v194 offset:50176
	s_add_i32 m0, s36, 0x18000
	ds_read_b128 v[220:223], v194 offset:51200
	global_load_lds_dwordx4 v168, s[98:99]
	s_add_i32 m0, s36, 0x1a000
	ds_read_b128 v[236:239], v194 offset:52224
	global_load_lds_dwordx4 v164, s[98:99]
	s_barrier
	s_waitcnt lgkmcnt(0)
	v_mfma_f32_16x16x32_bf16 v[56:59], v[220:223], v[116:119], v[56:59]
	v_mfma_f32_16x16x32_bf16 v[132:135], v[212:215], v[116:119], v[148:151]
	v_mfma_f32_16x16x32_bf16 v[144:147], v[236:239], v[128:131], v[56:59]
	v_mfma_f32_16x16x32_bf16 v[56:59], v[212:215], v[182:185], v[60:63]
	v_mfma_f32_16x16x32_bf16 v[148:151], v[216:219], v[128:131], v[132:135]
	v_mfma_f32_16x16x32_bf16 v[132:135], v[216:219], v[186:189], v[56:59]
	v_mfma_f32_16x16x32_bf16 v[56:59], v[220:223], v[182:185], v[72:75]
	v_mfma_f32_16x16x32_bf16 v[128:131], v[236:239], v[186:189], v[56:59]
	v_mfma_f32_16x16x32_bf16 v[56:59], v[212:215], v[196:199], v[84:87]
	v_mfma_f32_16x16x32_bf16 v[116:119], v[216:219], v[200:203], v[56:59]
	v_mfma_f32_16x16x32_bf16 v[56:59], v[220:223], v[196:199], v[112:115]
	v_mfma_f32_16x16x32_bf16 v[112:115], v[236:239], v[200:203], v[56:59]
	v_mfma_f32_16x16x32_bf16 v[56:59], v[212:215], v[204:207], v[100:103]
	v_mfma_f32_16x16x32_bf16 v[100:103], v[216:219], v[208:211], v[56:59]
	v_mfma_f32_16x16x32_bf16 v[56:59], v[220:223], v[204:207], v[96:99]
	v_mfma_f32_16x16x32_bf16 v[96:99], v[236:239], v[208:211], v[56:59]
	s_mov_b32 m0, s47
	s_barrier
	s_nop 2
	ds_read_b128 v[56:59], v195 offset:49152
	ds_read_b128 v[60:63], v195 offset:50176
	ds_read_b128 v[72:75], v195 offset:51200
	ds_read_b128 v[84:87], v195 offset:52224
	ds_read_b128 v[182:185], v195 offset:53248
	ds_read_b128 v[186:189], v195 offset:54272
	ds_read_b128 v[196:199], v195 offset:55296
	global_load_lds_dwordx4 v160, s[100:101]
	s_mov_b32 m0, s49
	ds_read_b128 v[200:203], v195 offset:56320
	global_load_lds_dwordx4 v162, s[100:101]
	s_barrier
	s_waitcnt lgkmcnt(0)
	v_mfma_f32_16x16x32_bf16 v[92:95], v[48:51], v[56:59], v[92:95]
	v_mfma_f32_16x16x32_bf16 v[88:91], v[76:79], v[56:59], v[88:91]
	v_mfma_f32_16x16x32_bf16 v[68:71], v[48:51], v[72:75], v[68:71]
	v_mfma_f32_16x16x32_bf16 v[64:67], v[76:79], v[72:75], v[64:67]
	v_mfma_f32_16x16x32_bf16 v[28:31], v[48:51], v[182:185], v[28:31]
	v_mfma_f32_16x16x32_bf16 v[24:27], v[76:79], v[182:185], v[24:27]
	v_mfma_f32_16x16x32_bf16 v[12:15], v[48:51], v[196:199], v[12:15]
	v_mfma_f32_16x16x32_bf16 v[8:11], v[76:79], v[196:199], v[8:11]
	v_mfma_f32_16x16x32_bf16 v[92:95], v[52:55], v[60:63], v[92:95]
	v_mfma_f32_16x16x32_bf16 v[88:91], v[80:83], v[60:63], v[88:91]
	v_mfma_f32_16x16x32_bf16 v[68:71], v[52:55], v[84:87], v[68:71]
	v_mfma_f32_16x16x32_bf16 v[64:67], v[80:83], v[84:87], v[64:67]
	v_mfma_f32_16x16x32_bf16 v[28:31], v[52:55], v[186:189], v[28:31]
	v_mfma_f32_16x16x32_bf16 v[24:27], v[80:83], v[186:189], v[24:27]
	v_mfma_f32_16x16x32_bf16 v[12:15], v[52:55], v[200:203], v[12:15]
	v_mfma_f32_16x16x32_bf16 v[8:11], v[80:83], v[200:203], v[8:11]
	s_barrier
	s_add_i32 m0, s36, 0x1c000
	s_add_u32 s8, s8, 0xb0080
	s_addc_u32 s9, s9, 0
	global_load_lds_dwordx4 v168, s[8:9]
	s_add_i32 m0, s36, 0x1e000
	s_add_i32 s58, s58, 2
	global_load_lds_dwordx4 v164, s[8:9]
	s_waitcnt vmcnt(6)
	s_barrier
	v_mfma_f32_16x16x32_bf16 v[40:43], v[212:215], v[56:59], v[40:43]
	v_mfma_f32_16x16x32_bf16 v[80:83], v[216:219], v[60:63], v[40:43]
	v_mfma_f32_16x16x32_bf16 v[40:43], v[220:223], v[56:59], v[44:47]
	v_mfma_f32_16x16x32_bf16 v[36:39], v[212:215], v[72:75], v[36:39]
	v_mfma_f32_16x16x32_bf16 v[32:35], v[220:223], v[72:75], v[32:35]
	v_mfma_f32_16x16x32_bf16 v[20:23], v[212:215], v[182:185], v[20:23]
	v_mfma_f32_16x16x32_bf16 v[16:19], v[220:223], v[182:185], v[16:19]
	v_mfma_f32_16x16x32_bf16 v[4:7], v[212:215], v[196:199], v[4:7]
	v_mfma_f32_16x16x32_bf16 v[0:3], v[220:223], v[196:199], v[0:3]
	v_mfma_f32_16x16x32_bf16 v[76:79], v[236:239], v[60:63], v[40:43]
	v_mfma_f32_16x16x32_bf16 v[36:39], v[216:219], v[84:87], v[36:39]
	v_mfma_f32_16x16x32_bf16 v[32:35], v[236:239], v[84:87], v[32:35]
	v_mfma_f32_16x16x32_bf16 v[20:23], v[216:219], v[186:189], v[20:23]
	v_mfma_f32_16x16x32_bf16 v[16:19], v[236:239], v[186:189], v[16:19]
	v_mfma_f32_16x16x32_bf16 v[4:7], v[216:219], v[200:203], v[4:7]
	v_mfma_f32_16x16x32_bf16 v[0:3], v[236:239], v[200:203], v[0:3]
	s_add_u32 s56, s56, 0x100
	s_addc_u32 s57, s57, 0
	s_cmp_gt_u32 s58, 41
	s_mov_b64 s[24:25], s[2:3]
	s_barrier
	s_cbranch_scc0 .LBB0_1049
	s_lshl_b32 s2, s55, 8
	v_mov_b32_e32 v186, v193
	v_mov_b32_e32 v196, v192
	s_or_b32 s2, s2, s46
	v_mov_b32_e32 v52, 0
	v_lshl_add_u32 v182, v196, 3, s2
	s_add_i32 s2, s54, -16
	s_lshr_b32 s2, s2, 3
	s_add_i32 s2, s2, 1
	s_cmp_gt_i32 s54, 15
	s_cselect_b32 s8, s2, 0
	s_mul_i32 s96, s8, 0x1800
	s_lshl_b64 s[2:3], s[96:97], 2
	s_add_u32 s2, s41, s2
	v_ashrrev_i32_e32 v183, 31, v182
	s_addc_u32 s3, s42, s3
	v_lshlrev_b64 v[40:41], 2, v[182:183]
	v_lshl_add_u64 v[42:43], s[2:3], 0, v[40:41]
	global_load_dwordx4 v[72:75], v[42:43], off
	s_lshl_b32 s96, s8, 10
	s_lshl_b64 s[2:3], s[96:97], 2
	s_add_u32 s2, s43, s2
	s_addc_u32 s3, s44, s3
	v_lshl_add_u64 v[184:185], s[2:3], 0, v[40:41]
	s_and_b64 vcc, exec, s[4:5]
	v_mov_b32_e32 v60, 0
	v_mov_b32_e32 v61, v52
	v_mov_b32_e32 v62, 0
	v_mov_b32_e32 v63, 0
	s_cbranch_vccnz .LBB0_1052
	global_load_dwordx4 v[60:63], v[184:185], off
